# v4 plus: GEMM main loops issue LDS-DMA with SGPR base + 32-bit VGPR offset where the 64-bit address pair was dead after the load (66 v_lshl_add_u64 removed)
# speedup vs baseline: 1.0021x; 1.0021x over previous
; #define PG8_STAGE(bufoff, gbase, voff) do { _Pragma("unroll") for (int _i = 0; _i < 2; ++_i) \
;         __builtin_amdgcn_global_load_lds((const unsigned*)((const char*)(gbase) + (voff)[_i]), (LAS unsigned*)(lds + (bufoff) + ldsw + _i * 8192), 16, 0, 0); } while (0)
; #define PG8_LDA(dst, b, h) do { _Pragma("unroll") for (int m = 0; m < 4; ++m) _Pragma("unroll") for (int k = 0; k < 2; ++k) dst[m][k] = *(const LAS bf16x8*)(lds + PG8_SA(b, h) + aoff + m * 2048 + k * 1024); } while (0)
; #define PG8_LDB(dst, b, h) do { _Pragma("unroll") for (int n = 0; n < 2; ++n) _Pragma("unroll") for (int k = 0; k < 2; ++k) dst[n][k] = *(const LAS bf16x8*)(lds + PG8_SB(b, h) + boff + n * 2048 + k * 1024); } while (0)
; #define PG8_MMA(ai, bj, At, Bt) do { __builtin_amdgcn_s_setprio(1); _Pragma("unroll") for (int m = 0; m < 4; ++m) _Pragma("unroll") for (int n = 0; n < 2; ++n) _Pragma("unroll") for (int k = 0; k < 2; ++k) \
;         acc[ai][bj][m][n] = __builtin_amdgcn_mfma_f32_16x16x32_bf16(Bt[n][k], At[m][k], acc[ai][bj][m][n], 0, 0, 0); __builtin_amdgcn_s_setprio(0); } while (0)
; #define PG8_WAIT_V(n) asm volatile("s_waitcnt vmcnt(" #n ")" ::: "memory")
; #define PG8_WAIT_L(n) asm volatile("s_waitcnt lgkmcnt(" #n ")" ::: "memory")
; #define PG8_BAR __builtin_amdgcn_s_barrier()
; #define PG8_SCHED __builtin_amdgcn_sched_barrier(0)
; template <class Epi, bool ALIGN_EPI = true>
; __device__ __forceinline__ void gemm_phase(LAS unsigned char* lds, const Gemm g, const StaticOrder& S, const Epi& E, int wave_k) {
;     ...
;         for (int t = 0; t < nt; t += 2) {
;             const bool last = (t == nt - 2);
;             const char* a1 = cA + (size_t)(t + 1) * kstep;
;             const char* a2 = last ? nA : cA + (size_t)(t + 2) * kstep; const char* b2 = last ? nB : cB + (size_t)(t + 2) * kstep;
;             const char* a3 = a2 + kstep; const char* b3 = b2 + kstep;
;             PG8_LDB(B0, 0, 0); PG8_LDB(B1, 0, 1); PG8_SCHED; PG8_LDA(At, 0, 0); PG8_STAGE(PG8_SA(1, 1), a1 + hstepA, voffA);
;             PG8_WAIT_V(8); PG8_WAIT_L(0); PG8_BAR; PG8_MMA(0, 0, At, B0); PG8_MMA(0, 1, At, B1); PG8_BAR; PG8_SCHED;
;             PG8_LDA(At, 0, 1); PG8_STAGE(PG8_SB(0, 0), b2, voffB); PG8_STAGE(PG8_SB(0, 1), b2 + hstepB, voffB); PG8_STAGE(PG8_SA(0, 0), a2, voffA);
;             PG8_WAIT_V(8); PG8_WAIT_L(0); PG8_BAR; PG8_MMA(1, 0, At, B0); PG8_MMA(1, 1, At, B1); PG8_BAR; PG8_SCHED;
.LBB0_81:
	s_add_u32 s16, s2, 0xfffc0080
	s_addc_u32 s17, s3, -1
	s_add_i32 s65, 0, 0x10000
	s_cmp_eq_u32 s64, 12
	s_cselect_b32 s19, s42, s17
	s_cselect_b32 s18, s43, s16
	s_cselect_b32 s17, s49, s63
	s_cselect_b32 s16, s51, s62
	s_add_i32 s68, 0, 0x14000
	v_add_u32_e32 v150, s65, v157
	v_add_u32_e32 v154, s68, v157
	ds_read_b128 v[138:141], v150
	ds_read_b128 v[142:145], v150 offset:1024
	ds_read_b128 v[146:149], v150 offset:2048
	ds_read_b128 v[150:153], v150 offset:3072
	ds_read_b128 v[162:165], v154
	ds_read_b128 v[166:169], v154 offset:1024
	ds_read_b128 v[170:173], v154 offset:2048
	ds_read_b128 v[174:177], v154 offset:3072
	s_add_i32 m0, s35, 0xc000
	ds_read_b128 v[178:181], v159
	ds_read_b128 v[182:185], v159 offset:1024
	ds_read_b128 v[186:189], v159 offset:2048
	ds_read_b128 v[190:193], v159 offset:3072
	ds_read_b128 v[194:197], v159 offset:4096
	ds_read_b128 v[198:201], v159 offset:5120
	ds_read_b128 v[202:205], v159 offset:6144
	ds_read_b128 v[206:209], v159 offset:7168
	global_load_lds_dwordx4 v134, s[2:3]
	s_add_i32 m0, s35, 0xe000
	s_nop 0
	global_load_lds_dwordx4 v136, s[2:3]
	s_waitcnt vmcnt(8)
	s_waitcnt lgkmcnt(0)
	s_barrier
	s_setprio 1
	s_waitcnt lgkmcnt(0)
	v_mfma_f32_16x16x32_bf16 v[124:127], v[138:141], v[178:181], v[124:127]
	v_mfma_f32_16x16x32_bf16 v[120:123], v[146:149], v[178:181], v[120:123]
	v_mfma_f32_16x16x32_bf16 v[108:111], v[138:141], v[186:189], v[108:111]
	v_mfma_f32_16x16x32_bf16 v[100:103], v[146:149], v[186:189], v[100:103]
	v_mfma_f32_16x16x32_bf16 v[92:95], v[138:141], v[194:197], v[92:95]
	v_mfma_f32_16x16x32_bf16 v[84:87], v[146:149], v[194:197], v[84:87]
	v_mfma_f32_16x16x32_bf16 v[76:79], v[138:141], v[202:205], v[76:79]
	v_mfma_f32_16x16x32_bf16 v[68:71], v[146:149], v[202:205], v[68:71]
	v_mfma_f32_16x16x32_bf16 v[124:127], v[142:145], v[182:185], v[124:127]
	v_mfma_f32_16x16x32_bf16 v[120:123], v[150:153], v[182:185], v[120:123]
	v_mfma_f32_16x16x32_bf16 v[108:111], v[142:145], v[190:193], v[108:111]
	v_mfma_f32_16x16x32_bf16 v[100:103], v[150:153], v[190:193], v[100:103]
	v_mfma_f32_16x16x32_bf16 v[92:95], v[142:145], v[198:201], v[92:95]
	v_mfma_f32_16x16x32_bf16 v[84:87], v[150:153], v[198:201], v[84:87]
	v_mfma_f32_16x16x32_bf16 v[76:79], v[142:145], v[206:209], v[76:79]
	v_mfma_f32_16x16x32_bf16 v[68:71], v[150:153], v[206:209], v[68:71]
	s_setprio 0
	s_setprio 1
	v_mfma_f32_16x16x32_bf16 v[116:119], v[162:165], v[178:181], v[116:119]
	v_mfma_f32_16x16x32_bf16 v[112:115], v[170:173], v[178:181], v[112:115]
	v_mfma_f32_16x16x32_bf16 v[104:107], v[162:165], v[186:189], v[104:107]
	v_mfma_f32_16x16x32_bf16 v[96:99], v[170:173], v[186:189], v[96:99]
	v_mfma_f32_16x16x32_bf16 v[88:91], v[162:165], v[194:197], v[88:91]
	v_mfma_f32_16x16x32_bf16 v[80:83], v[170:173], v[194:197], v[80:83]
	v_mfma_f32_16x16x32_bf16 v[72:75], v[162:165], v[202:205], v[72:75]
	v_mfma_f32_16x16x32_bf16 v[64:67], v[170:173], v[202:205], v[64:67]
	v_mfma_f32_16x16x32_bf16 v[116:119], v[166:169], v[182:185], v[116:119]
	v_mfma_f32_16x16x32_bf16 v[112:115], v[174:177], v[182:185], v[112:115]
	v_mfma_f32_16x16x32_bf16 v[104:107], v[166:169], v[190:193], v[104:107]
	v_mfma_f32_16x16x32_bf16 v[96:99], v[174:177], v[190:193], v[96:99]
	v_mfma_f32_16x16x32_bf16 v[88:91], v[166:169], v[198:201], v[88:91]
	v_mfma_f32_16x16x32_bf16 v[80:83], v[174:177], v[198:201], v[80:83]
	v_mfma_f32_16x16x32_bf16 v[72:75], v[166:169], v[206:209], v[72:75]
	v_mfma_f32_16x16x32_bf16 v[64:67], v[174:177], v[206:209], v[64:67]
	s_setprio 0
	s_barrier
	s_add_i32 s65, s65, s29
	v_lshl_add_u64 v[154:155], s[16:17], 0, v[160:161]
	s_mov_b32 m0, s65
	ds_read_b128 v[178:181], v159 offset:16384
	ds_read_b128 v[182:185], v159 offset:17408
	ds_read_b128 v[186:189], v159 offset:18432
	ds_read_b128 v[190:193], v159 offset:19456
	ds_read_b128 v[194:197], v159 offset:20480
	ds_read_b128 v[198:201], v159 offset:21504
	ds_read_b128 v[202:205], v159 offset:22528
	ds_read_b128 v[206:209], v159 offset:23552
	global_load_lds_dwordx4 v[154:155], off
	s_add_i32 m0, s65, 0x2000
	s_add_u32 s66, s16, 0x40000
	v_lshl_add_u64 v[210:211], s[16:17], 0, v[128:129]
	s_addc_u32 s67, s17, 0
	s_add_i32 s65, s68, s29
	global_load_lds_dwordx4 v[210:211], off
	s_mov_b32 m0, s65
	v_lshl_add_u64 v[218:219], s[18:19], 0, v[130:131]
	global_load_lds_dwordx4 v160, s[66:67]
	s_add_i32 m0, s65, 0x2000
	s_nop 0
	global_load_lds_dwordx4 v128, s[66:67]
	v_lshl_add_u64 v[212:213], s[18:19], 0, v[132:133]
	s_mov_b32 m0, s35
	s_nop 0
	global_load_lds_dwordx4 v[212:213], off
	s_mov_b32 m0, s56
	s_nop 0
	global_load_lds_dwordx4 v[218:219], off
	s_waitcnt vmcnt(8)
	s_waitcnt lgkmcnt(0)
	s_barrier
; #define PG8_STAGE(bufoff, gbase, voff) do { _Pragma("unroll") for (int _i = 0; _i < 2; ++_i) \
;         __builtin_amdgcn_global_load_lds((const unsigned*)((const char*)(gbase) + (voff)[_i]), (LAS unsigned*)(lds + (bufoff) + ldsw + _i * 8192), 16, 0, 0); } while (0)
; #define PG8_LDA(dst, b, h) do { _Pragma("unroll") for (int m = 0; m < 4; ++m) _Pragma("unroll") for (int k = 0; k < 2; ++k) dst[m][k] = *(const LAS bf16x8*)(lds + PG8_SA(b, h) + aoff + m * 2048 + k * 1024); } while (0)
; #define PG8_LDB(dst, b, h) do { _Pragma("unroll") for (int n = 0; n < 2; ++n) _Pragma("unroll") for (int k = 0; k < 2; ++k) dst[n][k] = *(const LAS bf16x8*)(lds + PG8_SB(b, h) + boff + n * 2048 + k * 1024); } while (0)
; #define PG8_MMA(ai, bj, At, Bt) do { __builtin_amdgcn_s_setprio(1); _Pragma("unroll") for (int m = 0; m < 4; ++m) _Pragma("unroll") for (int n = 0; n < 2; ++n) _Pragma("unroll") for (int k = 0; k < 2; ++k) \
;         acc[ai][bj][m][n] = __builtin_amdgcn_mfma_f32_16x16x32_bf16(Bt[n][k], At[m][k], acc[ai][bj][m][n], 0, 0, 0); __builtin_amdgcn_s_setprio(0); } while (0)
; #define PG8_WAIT_V(n) asm volatile("s_waitcnt vmcnt(" #n ")" ::: "memory")
; #define PG8_WAIT_L(n) asm volatile("s_waitcnt lgkmcnt(" #n ")" ::: "memory")
; #define PG8_BAR __builtin_amdgcn_s_barrier()
; #define PG8_SCHED __builtin_amdgcn_sched_barrier(0)
; template <class Epi, bool ALIGN_EPI = true>
; __device__ __forceinline__ void gemm_phase(LAS unsigned char* lds, const Gemm g, const StaticOrder& S, const Epi& E, int wave_k) {
;     ...
;             PG8_WAIT_V(8); PG8_WAIT_L(0); PG8_BAR; PG8_MMA(1, 0, At, B0); PG8_MMA(1, 1, At, B1); PG8_BAR; PG8_SCHED;
;             PG8_LDB(B0, 1, 0); PG8_LDB(B1, 1, 1); PG8_SCHED; PG8_LDA(At, 1, 0); PG8_STAGE(PG8_SA(0, 1), a2 + hstepA, voffA);
;             PG8_WAIT_V(8); PG8_WAIT_L(0); PG8_BAR; PG8_MMA(0, 0, At, B0); PG8_MMA(0, 1, At, B1); PG8_BAR; PG8_SCHED;
	s_setprio 1
	s_waitcnt lgkmcnt(0)
	v_mfma_f32_16x16x32_bf16 v[60:63], v[138:141], v[178:181], v[60:63]
	v_mfma_f32_16x16x32_bf16 v[52:55], v[146:149], v[178:181], v[52:55]
	v_mfma_f32_16x16x32_bf16 v[44:47], v[138:141], v[186:189], v[44:47]
	v_mfma_f32_16x16x32_bf16 v[36:39], v[146:149], v[186:189], v[36:39]
	v_mfma_f32_16x16x32_bf16 v[28:31], v[138:141], v[194:197], v[28:31]
	v_mfma_f32_16x16x32_bf16 v[20:23], v[146:149], v[194:197], v[20:23]
	v_mfma_f32_16x16x32_bf16 v[12:15], v[138:141], v[202:205], v[12:15]
	v_mfma_f32_16x16x32_bf16 v[4:7], v[146:149], v[202:205], v[4:7]
	v_mfma_f32_16x16x32_bf16 v[60:63], v[142:145], v[182:185], v[60:63]
	v_mfma_f32_16x16x32_bf16 v[52:55], v[150:153], v[182:185], v[52:55]
	v_mfma_f32_16x16x32_bf16 v[44:47], v[142:145], v[190:193], v[44:47]
	v_mfma_f32_16x16x32_bf16 v[36:39], v[150:153], v[190:193], v[36:39]
	v_mfma_f32_16x16x32_bf16 v[28:31], v[142:145], v[198:201], v[28:31]
	v_mfma_f32_16x16x32_bf16 v[20:23], v[150:153], v[198:201], v[20:23]
	v_mfma_f32_16x16x32_bf16 v[12:15], v[142:145], v[206:209], v[12:15]
	v_mfma_f32_16x16x32_bf16 v[4:7], v[150:153], v[206:209], v[4:7]
	s_setprio 0
	s_setprio 1
	v_mfma_f32_16x16x32_bf16 v[56:59], v[162:165], v[178:181], v[56:59]
	v_mfma_f32_16x16x32_bf16 v[48:51], v[170:173], v[178:181], v[48:51]
	v_mfma_f32_16x16x32_bf16 v[40:43], v[162:165], v[186:189], v[40:43]
	v_mfma_f32_16x16x32_bf16 v[32:35], v[170:173], v[186:189], v[32:35]
	v_mfma_f32_16x16x32_bf16 v[24:27], v[162:165], v[194:197], v[24:27]
	v_mfma_f32_16x16x32_bf16 v[16:19], v[170:173], v[194:197], v[16:19]
	v_mfma_f32_16x16x32_bf16 v[8:11], v[162:165], v[202:205], v[8:11]
	v_mfma_f32_16x16x32_bf16 v[0:3], v[170:173], v[202:205], v[0:3]
	v_mfma_f32_16x16x32_bf16 v[56:59], v[166:169], v[182:185], v[56:59]
	v_mfma_f32_16x16x32_bf16 v[48:51], v[174:177], v[182:185], v[48:51]
	v_mfma_f32_16x16x32_bf16 v[40:43], v[166:169], v[190:193], v[40:43]
	v_mfma_f32_16x16x32_bf16 v[32:35], v[174:177], v[190:193], v[32:35]
	v_mfma_f32_16x16x32_bf16 v[24:27], v[166:169], v[198:201], v[24:27]
	v_mfma_f32_16x16x32_bf16 v[16:19], v[174:177], v[198:201], v[16:19]
	v_mfma_f32_16x16x32_bf16 v[8:11], v[166:169], v[206:209], v[8:11]
	v_mfma_f32_16x16x32_bf16 v[0:3], v[174:177], v[206:209], v[0:3]
	s_setprio 0
	s_barrier
	s_add_i32 s65, 0, 0x18000
	s_add_i32 s66, 0, 0x1c000
	v_add_u32_e32 v150, s65, v157
	v_add_u32_e32 v174, s66, v157
	ds_read_b128 v[138:141], v150
	ds_read_b128 v[142:145], v150 offset:1024
	ds_read_b128 v[146:149], v150 offset:2048
	ds_read_b128 v[150:153], v150 offset:3072
	ds_read_b128 v[162:165], v174
	ds_read_b128 v[166:169], v174 offset:1024
	ds_read_b128 v[170:173], v174 offset:2048
	ds_read_b128 v[174:177], v174 offset:3072
	s_add_u32 s18, s18, 0x40000
	s_addc_u32 s19, s19, 0
	s_mov_b32 m0, s57
	ds_read_b128 v[178:181], v159 offset:32768
	ds_read_b128 v[182:185], v159 offset:33792
	ds_read_b128 v[186:189], v159 offset:34816
	ds_read_b128 v[190:193], v159 offset:35840
	ds_read_b128 v[194:197], v159 offset:36864
	ds_read_b128 v[198:201], v159 offset:37888
	ds_read_b128 v[202:205], v159 offset:38912
	ds_read_b128 v[206:209], v159 offset:39936
	global_load_lds_dwordx4 v132, s[18:19]
	s_mov_b32 m0, s58
	s_nop 0
	global_load_lds_dwordx4 v130, s[18:19]
	s_waitcnt vmcnt(8)
	s_waitcnt lgkmcnt(0)
	s_barrier
	s_setprio 1
	s_waitcnt lgkmcnt(0)
	v_mfma_f32_16x16x32_bf16 v[124:127], v[138:141], v[178:181], v[124:127]
	v_mfma_f32_16x16x32_bf16 v[120:123], v[146:149], v[178:181], v[120:123]
	v_mfma_f32_16x16x32_bf16 v[108:111], v[138:141], v[186:189], v[108:111]
	v_mfma_f32_16x16x32_bf16 v[100:103], v[146:149], v[186:189], v[100:103]
	v_mfma_f32_16x16x32_bf16 v[92:95], v[138:141], v[194:197], v[92:95]
	v_mfma_f32_16x16x32_bf16 v[84:87], v[146:149], v[194:197], v[84:87]
	v_mfma_f32_16x16x32_bf16 v[76:79], v[138:141], v[202:205], v[76:79]
	v_mfma_f32_16x16x32_bf16 v[68:71], v[146:149], v[202:205], v[68:71]
	v_mfma_f32_16x16x32_bf16 v[124:127], v[142:145], v[182:185], v[124:127]
	v_mfma_f32_16x16x32_bf16 v[120:123], v[150:153], v[182:185], v[120:123]
	v_mfma_f32_16x16x32_bf16 v[108:111], v[142:145], v[190:193], v[108:111]
	v_mfma_f32_16x16x32_bf16 v[100:103], v[150:153], v[190:193], v[100:103]
	v_mfma_f32_16x16x32_bf16 v[92:95], v[142:145], v[198:201], v[92:95]
	v_mfma_f32_16x16x32_bf16 v[84:87], v[150:153], v[198:201], v[84:87]
	v_mfma_f32_16x16x32_bf16 v[76:79], v[142:145], v[206:209], v[76:79]
	v_mfma_f32_16x16x32_bf16 v[68:71], v[150:153], v[206:209], v[68:71]
	s_setprio 0
	s_setprio 1
	v_mfma_f32_16x16x32_bf16 v[116:119], v[162:165], v[178:181], v[116:119]
	v_mfma_f32_16x16x32_bf16 v[112:115], v[170:173], v[178:181], v[112:115]
	v_mfma_f32_16x16x32_bf16 v[104:107], v[162:165], v[186:189], v[104:107]
	v_mfma_f32_16x16x32_bf16 v[96:99], v[170:173], v[186:189], v[96:99]
	v_mfma_f32_16x16x32_bf16 v[88:91], v[162:165], v[194:197], v[88:91]
	v_mfma_f32_16x16x32_bf16 v[80:83], v[170:173], v[194:197], v[80:83]
	v_mfma_f32_16x16x32_bf16 v[72:75], v[162:165], v[202:205], v[72:75]
	v_mfma_f32_16x16x32_bf16 v[64:67], v[170:173], v[202:205], v[64:67]
	v_mfma_f32_16x16x32_bf16 v[116:119], v[166:169], v[182:185], v[116:119]
	v_mfma_f32_16x16x32_bf16 v[112:115], v[174:177], v[182:185], v[112:115]
	v_mfma_f32_16x16x32_bf16 v[104:107], v[166:169], v[190:193], v[104:107]
	v_mfma_f32_16x16x32_bf16 v[96:99], v[174:177], v[190:193], v[96:99]
	v_mfma_f32_16x16x32_bf16 v[88:91], v[166:169], v[198:201], v[88:91]
	v_mfma_f32_16x16x32_bf16 v[80:83], v[174:177], v[198:201], v[80:83]
	v_mfma_f32_16x16x32_bf16 v[72:75], v[166:169], v[206:209], v[72:75]
	v_mfma_f32_16x16x32_bf16 v[64:67], v[174:177], v[206:209], v[64:67]
	s_setprio 0
	s_barrier
; #define PG8_STAGE(bufoff, gbase, voff) do { _Pragma("unroll") for (int _i = 0; _i < 2; ++_i) \
;         __builtin_amdgcn_global_load_lds((const unsigned*)((const char*)(gbase) + (voff)[_i]), (LAS unsigned*)(lds + (bufoff) + ldsw + _i * 8192), 16, 0, 0); } while (0)
; #define PG8_LDA(dst, b, h) do { _Pragma("unroll") for (int m = 0; m < 4; ++m) _Pragma("unroll") for (int k = 0; k < 2; ++k) dst[m][k] = *(const LAS bf16x8*)(lds + PG8_SA(b, h) + aoff + m * 2048 + k * 1024); } while (0)
; #define PG8_MMA(ai, bj, At, Bt) do { __builtin_amdgcn_s_setprio(1); _Pragma("unroll") for (int m = 0; m < 4; ++m) _Pragma("unroll") for (int n = 0; n < 2; ++n) _Pragma("unroll") for (int k = 0; k < 2; ++k) \
;         acc[ai][bj][m][n] = __builtin_amdgcn_mfma_f32_16x16x32_bf16(Bt[n][k], At[m][k], acc[ai][bj][m][n], 0, 0, 0); __builtin_amdgcn_s_setprio(0); } while (0)
; #define PG8_WAIT_V(n) asm volatile("s_waitcnt vmcnt(" #n ")" ::: "memory")
; #define PG8_WAIT_L(n) asm volatile("s_waitcnt lgkmcnt(" #n ")" ::: "memory")
; #define PG8_BAR __builtin_amdgcn_s_barrier()
; #define PG8_SCHED __builtin_amdgcn_sched_barrier(0)
; template <class Epi, bool ALIGN_EPI = true>
; __device__ __forceinline__ void gemm_phase(LAS unsigned char* lds, const Gemm g, const StaticOrder& S, const Epi& E, int wave_k) {
;     ...
;             PG8_LDA(At, 1, 1); PG8_STAGE(PG8_SB(1, 0), b3, voffB); PG8_STAGE(PG8_SB(1, 1), b3 + hstepB, voffB); PG8_STAGE(PG8_SA(1, 0), a3, voffA);
;             PG8_WAIT_V(8); PG8_WAIT_L(0); PG8_BAR; PG8_MMA(1, 0, At, B0); PG8_MMA(1, 1, At, B1); PG8_BAR; PG8_SCHED;
;         }
;         if constexpr (ALIGN_EPI) { if (wr == 0) PG8_BAR; }
	s_add_i32 s18, s65, s29
	v_lshl_add_u64 v[154:155], v[154:155], 0, s[22:23]
	s_mov_b32 m0, s18
	ds_read_b128 v[178:181], v159 offset:49152
	ds_read_b128 v[182:185], v159 offset:50176
	ds_read_b128 v[186:189], v159 offset:51200
	ds_read_b128 v[190:193], v159 offset:52224
	ds_read_b128 v[194:197], v159 offset:53248
	ds_read_b128 v[198:201], v159 offset:54272
	ds_read_b128 v[202:205], v159 offset:55296
	ds_read_b128 v[206:209], v159 offset:56320
	global_load_lds_dwordx4 v[154:155], off
	s_add_i32 m0, s18, 0x2000
	s_add_u32 s16, s16, 0x40080
	v_lshl_add_u64 v[154:155], v[210:211], 0, s[22:23]
	s_addc_u32 s17, s17, 0
	s_add_i32 s18, s66, s29
	global_load_lds_dwordx4 v[154:155], off
	s_mov_b32 m0, s18
	s_nop 0
	global_load_lds_dwordx4 v160, s[16:17]
	s_add_i32 m0, s18, 0x2000
	s_nop 0
	global_load_lds_dwordx4 v128, s[16:17]
	v_lshl_add_u64 v[154:155], v[212:213], 0, s[22:23]
	s_mov_b32 m0, s59
	s_nop 0
	global_load_lds_dwordx4 v[154:155], off
	v_lshl_add_u64 v[154:155], v[218:219], 0, s[22:23]
	s_mov_b32 m0, s60
	s_nop 0
	global_load_lds_dwordx4 v[154:155], off
	s_waitcnt vmcnt(8)
	s_waitcnt lgkmcnt(0)
	s_barrier
	s_setprio 1
	s_waitcnt lgkmcnt(0)
	v_mfma_f32_16x16x32_bf16 v[60:63], v[138:141], v[178:181], v[60:63]
	v_mfma_f32_16x16x32_bf16 v[52:55], v[146:149], v[178:181], v[52:55]
	v_mfma_f32_16x16x32_bf16 v[44:47], v[138:141], v[186:189], v[44:47]
	v_mfma_f32_16x16x32_bf16 v[36:39], v[146:149], v[186:189], v[36:39]
	v_mfma_f32_16x16x32_bf16 v[28:31], v[138:141], v[194:197], v[28:31]
	v_mfma_f32_16x16x32_bf16 v[20:23], v[146:149], v[194:197], v[20:23]
	v_mfma_f32_16x16x32_bf16 v[12:15], v[138:141], v[202:205], v[12:15]
	v_mfma_f32_16x16x32_bf16 v[4:7], v[146:149], v[202:205], v[4:7]
	v_mfma_f32_16x16x32_bf16 v[60:63], v[142:145], v[182:185], v[60:63]
	v_mfma_f32_16x16x32_bf16 v[52:55], v[150:153], v[182:185], v[52:55]
	v_mfma_f32_16x16x32_bf16 v[44:47], v[142:145], v[190:193], v[44:47]
	v_mfma_f32_16x16x32_bf16 v[36:39], v[150:153], v[190:193], v[36:39]
	v_mfma_f32_16x16x32_bf16 v[28:31], v[142:145], v[198:201], v[28:31]
	v_mfma_f32_16x16x32_bf16 v[20:23], v[150:153], v[198:201], v[20:23]
	v_mfma_f32_16x16x32_bf16 v[12:15], v[142:145], v[206:209], v[12:15]
	v_mfma_f32_16x16x32_bf16 v[4:7], v[150:153], v[206:209], v[4:7]
	s_setprio 0
	s_setprio 1
	v_mfma_f32_16x16x32_bf16 v[56:59], v[162:165], v[178:181], v[56:59]
	v_mfma_f32_16x16x32_bf16 v[48:51], v[170:173], v[178:181], v[48:51]
	v_mfma_f32_16x16x32_bf16 v[40:43], v[162:165], v[186:189], v[40:43]
	v_mfma_f32_16x16x32_bf16 v[32:35], v[170:173], v[186:189], v[32:35]
	v_mfma_f32_16x16x32_bf16 v[24:27], v[162:165], v[194:197], v[24:27]
	v_mfma_f32_16x16x32_bf16 v[16:19], v[170:173], v[194:197], v[16:19]
	v_mfma_f32_16x16x32_bf16 v[8:11], v[162:165], v[202:205], v[8:11]
	v_mfma_f32_16x16x32_bf16 v[0:3], v[170:173], v[202:205], v[0:3]
	v_mfma_f32_16x16x32_bf16 v[56:59], v[166:169], v[182:185], v[56:59]
	v_mfma_f32_16x16x32_bf16 v[48:51], v[174:177], v[182:185], v[48:51]
	v_mfma_f32_16x16x32_bf16 v[40:43], v[166:169], v[190:193], v[40:43]
	v_mfma_f32_16x16x32_bf16 v[32:35], v[174:177], v[190:193], v[32:35]
	v_mfma_f32_16x16x32_bf16 v[24:27], v[166:169], v[198:201], v[24:27]
	v_mfma_f32_16x16x32_bf16 v[16:19], v[174:177], v[198:201], v[16:19]
	v_mfma_f32_16x16x32_bf16 v[8:11], v[166:169], v[206:209], v[8:11]
	v_mfma_f32_16x16x32_bf16 v[0:3], v[174:177], v[206:209], v[0:3]
	s_setprio 0
	s_barrier
	s_add_i32 s64, s64, 2
	s_add_u32 s2, s2, 0x100
	s_addc_u32 s3, s3, 0
	s_add_u32 s62, s62, 0x100
	s_addc_u32 s63, s63, 0
	s_cmp_gt_u32 s64, 13
	s_cbranch_scc0 .LBB0_81
	s_and_b64 vcc, exec, s[46:47]
	s_cbranch_vccz .LBB0_84
	s_barrier

; #define PG8_STAGE(bufoff, gbase, voff) do { _Pragma("unroll") for (int _i = 0; _i < 2; ++_i) \
;         __builtin_amdgcn_global_load_lds((const unsigned*)((const char*)(gbase) + (voff)[_i]), (LAS unsigned*)(lds + (bufoff) + ldsw + _i * 8192), 16, 0, 0); } while (0)
; #define PG8_LDA(dst, b, h) do { _Pragma("unroll") for (int m = 0; m < 4; ++m) _Pragma("unroll") for (int k = 0; k < 2; ++k) dst[m][k] = *(const LAS bf16x8*)(lds + PG8_SA(b, h) + aoff + m * 2048 + k * 1024); } while (0)
; #define PG8_LDB(dst, b, h) do { _Pragma("unroll") for (int n = 0; n < 2; ++n) _Pragma("unroll") for (int k = 0; k < 2; ++k) dst[n][k] = *(const LAS bf16x8*)(lds + PG8_SB(b, h) + boff + n * 2048 + k * 1024); } while (0)
; #define PG8_MMA(ai, bj, At, Bt) do { __builtin_amdgcn_s_setprio(1); _Pragma("unroll") for (int m = 0; m < 4; ++m) _Pragma("unroll") for (int n = 0; n < 2; ++n) _Pragma("unroll") for (int k = 0; k < 2; ++k) \
;         acc[ai][bj][m][n] = __builtin_amdgcn_mfma_f32_16x16x32_bf16(Bt[n][k], At[m][k], acc[ai][bj][m][n], 0, 0, 0); __builtin_amdgcn_s_setprio(0); } while (0)
; #define PG8_WAIT_V(n) asm volatile("s_waitcnt vmcnt(" #n ")" ::: "memory")
; #define PG8_WAIT_L(n) asm volatile("s_waitcnt lgkmcnt(" #n ")" ::: "memory")
; #define PG8_BAR __builtin_amdgcn_s_barrier()
; #define PG8_SCHED __builtin_amdgcn_sched_barrier(0)
; template <class Epi, bool ALIGN_EPI = true>
; __device__ __forceinline__ void gemm_phase(LAS unsigned char* lds, const Gemm g, const StaticOrder& S, const Epi& E, int wave_k) {
;     ...
;         for (int t = 0; t < nt; t += 2) {
;             const bool last = (t == nt - 2);
;             const char* a1 = cA + (size_t)(t + 1) * kstep;
;             const char* a2 = last ? nA : cA + (size_t)(t + 2) * kstep; const char* b2 = last ? nB : cB + (size_t)(t + 2) * kstep;
;             const char* a3 = a2 + kstep; const char* b3 = b2 + kstep;
;             PG8_LDB(B0, 0, 0); PG8_LDB(B1, 0, 1); PG8_SCHED; PG8_LDA(At, 0, 0); PG8_STAGE(PG8_SA(1, 1), a1 + hstepA, voffA);
;             PG8_WAIT_V(8); PG8_WAIT_L(0); PG8_BAR; PG8_MMA(0, 0, At, B0); PG8_MMA(0, 1, At, B1); PG8_BAR; PG8_SCHED;
;             PG8_LDA(At, 0, 1); PG8_STAGE(PG8_SB(0, 0), b2, voffB); PG8_STAGE(PG8_SB(0, 1), b2 + hstepB, voffB); PG8_STAGE(PG8_SA(0, 0), a2, voffA);
;             PG8_WAIT_V(8); PG8_WAIT_L(0); PG8_BAR; PG8_MMA(1, 0, At, B0); PG8_MMA(1, 1, At, B1); PG8_BAR; PG8_SCHED;
.LBB0_170:
	s_add_u32 s16, s24, 0x100
	s_addc_u32 s17, s25, 0
	s_add_i32 s71, 0, 0x10000
	s_cmp_eq_u32 s70, 40
	s_cselect_b32 s29, s1, s17
	s_cselect_b32 s28, s0, s16
	v_add_u32_e32 v142, s71, v145
	s_cselect_b32 s27, s37, s47
	s_cselect_b32 s26, s36, s46
	s_add_i32 s72, 0, 0x14000
	ds_read_b128 v[138:141], v142
	ds_read_b128 v[148:151], v142 offset:1024
	ds_read_b128 v[152:155], v142 offset:2048
	ds_read_b128 v[156:159], v142 offset:3072
	v_add_u32_e32 v142, s72, v145
	ds_read_b128 v[162:165], v142
	ds_read_b128 v[166:169], v142 offset:1024
	ds_read_b128 v[170:173], v142 offset:2048
	ds_read_b128 v[174:177], v142 offset:3072
	v_lshl_add_u64 v[142:143], s[24:25], 0, v[134:135]
	s_add_i32 m0, s57, 0xc000
	ds_read_b128 v[178:181], v147
	ds_read_b128 v[182:185], v147 offset:1024
	ds_read_b128 v[186:189], v147 offset:2048
	ds_read_b128 v[190:193], v147 offset:3072
	ds_read_b128 v[194:197], v147 offset:4096
	ds_read_b128 v[198:201], v147 offset:5120
	ds_read_b128 v[202:205], v147 offset:6144
	ds_read_b128 v[206:209], v147 offset:7168
	global_load_lds_dwordx4 v[142:143], off
	v_lshl_add_u64 v[142:143], s[24:25], 0, v[136:137]
	s_add_i32 m0, s57, 0xe000
	s_nop 0
	global_load_lds_dwordx4 v[142:143], off
	s_waitcnt vmcnt(8)
	s_waitcnt lgkmcnt(0)
	s_barrier
	s_setprio 1
	s_waitcnt lgkmcnt(0)
	v_mfma_f32_16x16x32_bf16 v[124:127], v[138:141], v[178:181], v[124:127]
	v_mfma_f32_16x16x32_bf16 v[120:123], v[152:155], v[178:181], v[120:123]
	v_mfma_f32_16x16x32_bf16 v[108:111], v[138:141], v[186:189], v[108:111]
	v_mfma_f32_16x16x32_bf16 v[104:107], v[152:155], v[186:189], v[104:107]
	v_mfma_f32_16x16x32_bf16 v[92:95], v[138:141], v[194:197], v[92:95]
	v_mfma_f32_16x16x32_bf16 v[88:91], v[152:155], v[194:197], v[88:91]
	v_mfma_f32_16x16x32_bf16 v[76:79], v[138:141], v[202:205], v[76:79]
	v_mfma_f32_16x16x32_bf16 v[72:75], v[152:155], v[202:205], v[72:75]
	v_mfma_f32_16x16x32_bf16 v[124:127], v[148:151], v[182:185], v[124:127]
	v_mfma_f32_16x16x32_bf16 v[120:123], v[156:159], v[182:185], v[120:123]
	v_mfma_f32_16x16x32_bf16 v[108:111], v[148:151], v[190:193], v[108:111]
	v_mfma_f32_16x16x32_bf16 v[104:107], v[156:159], v[190:193], v[104:107]
	v_mfma_f32_16x16x32_bf16 v[92:95], v[148:151], v[198:201], v[92:95]
	v_mfma_f32_16x16x32_bf16 v[88:91], v[156:159], v[198:201], v[88:91]
	v_mfma_f32_16x16x32_bf16 v[76:79], v[148:151], v[206:209], v[76:79]
	v_mfma_f32_16x16x32_bf16 v[72:75], v[156:159], v[206:209], v[72:75]
	s_setprio 0
	s_setprio 1
	v_mfma_f32_16x16x32_bf16 v[116:119], v[162:165], v[178:181], v[116:119]
	v_mfma_f32_16x16x32_bf16 v[112:115], v[170:173], v[178:181], v[112:115]
	v_mfma_f32_16x16x32_bf16 v[100:103], v[162:165], v[186:189], v[100:103]
	v_mfma_f32_16x16x32_bf16 v[96:99], v[170:173], v[186:189], v[96:99]
	v_mfma_f32_16x16x32_bf16 v[84:87], v[162:165], v[194:197], v[84:87]
	v_mfma_f32_16x16x32_bf16 v[80:83], v[170:173], v[194:197], v[80:83]
	v_mfma_f32_16x16x32_bf16 v[68:71], v[162:165], v[202:205], v[68:71]
	v_mfma_f32_16x16x32_bf16 v[64:67], v[170:173], v[202:205], v[64:67]
	v_mfma_f32_16x16x32_bf16 v[116:119], v[166:169], v[182:185], v[116:119]
	v_mfma_f32_16x16x32_bf16 v[112:115], v[174:177], v[182:185], v[112:115]
	v_mfma_f32_16x16x32_bf16 v[100:103], v[166:169], v[190:193], v[100:103]
	v_mfma_f32_16x16x32_bf16 v[96:99], v[174:177], v[190:193], v[96:99]
	v_mfma_f32_16x16x32_bf16 v[84:87], v[166:169], v[198:201], v[84:87]
	v_mfma_f32_16x16x32_bf16 v[80:83], v[174:177], v[198:201], v[80:83]
	v_mfma_f32_16x16x32_bf16 v[68:71], v[166:169], v[206:209], v[68:71]
	v_mfma_f32_16x16x32_bf16 v[64:67], v[174:177], v[206:209], v[64:67]
	s_setprio 0
	s_barrier
	s_add_i32 s24, s71, s52
	v_lshl_add_u64 v[142:143], s[26:27], 0, v[160:161]
	s_mov_b32 m0, s24
	ds_read_b128 v[178:181], v147 offset:16384
	ds_read_b128 v[182:185], v147 offset:17408
	ds_read_b128 v[186:189], v147 offset:18432
	ds_read_b128 v[190:193], v147 offset:19456
	ds_read_b128 v[194:197], v147 offset:20480
	ds_read_b128 v[198:201], v147 offset:21504
	ds_read_b128 v[202:205], v147 offset:22528
	ds_read_b128 v[206:209], v147 offset:23552
	global_load_lds_dwordx4 v[142:143], off
	s_add_i32 m0, s24, 0x2000
	s_add_u32 s24, s26, 0xb0000
	v_lshl_add_u64 v[210:211], s[26:27], 0, v[132:133]
	s_addc_u32 s25, s27, 0
	s_add_i32 s71, s72, s52
	global_load_lds_dwordx4 v[210:211], off
	s_mov_b32 m0, s71
	v_lshl_add_u64 v[218:219], s[28:29], 0, v[130:131]
	global_load_lds_dwordx4 v160, s[24:25]
	s_add_i32 m0, s71, 0x2000
	s_nop 0
	global_load_lds_dwordx4 v132, s[24:25]
	v_lshl_add_u64 v[212:213], s[28:29], 0, v[128:129]
	s_mov_b32 m0, s57
	s_nop 0
	global_load_lds_dwordx4 v[212:213], off
	s_mov_b32 m0, s58
	s_nop 0
	global_load_lds_dwordx4 v[218:219], off
	s_waitcnt vmcnt(8)
	s_waitcnt lgkmcnt(0)
	s_barrier
; #define PG8_STAGE(bufoff, gbase, voff) do { _Pragma("unroll") for (int _i = 0; _i < 2; ++_i) \
;         __builtin_amdgcn_global_load_lds((const unsigned*)((const char*)(gbase) + (voff)[_i]), (LAS unsigned*)(lds + (bufoff) + ldsw + _i * 8192), 16, 0, 0); } while (0)
; #define PG8_LDA(dst, b, h) do { _Pragma("unroll") for (int m = 0; m < 4; ++m) _Pragma("unroll") for (int k = 0; k < 2; ++k) dst[m][k] = *(const LAS bf16x8*)(lds + PG8_SA(b, h) + aoff + m * 2048 + k * 1024); } while (0)
; #define PG8_LDB(dst, b, h) do { _Pragma("unroll") for (int n = 0; n < 2; ++n) _Pragma("unroll") for (int k = 0; k < 2; ++k) dst[n][k] = *(const LAS bf16x8*)(lds + PG8_SB(b, h) + boff + n * 2048 + k * 1024); } while (0)
; #define PG8_MMA(ai, bj, At, Bt) do { __builtin_amdgcn_s_setprio(1); _Pragma("unroll") for (int m = 0; m < 4; ++m) _Pragma("unroll") for (int n = 0; n < 2; ++n) _Pragma("unroll") for (int k = 0; k < 2; ++k) \
;         acc[ai][bj][m][n] = __builtin_amdgcn_mfma_f32_16x16x32_bf16(Bt[n][k], At[m][k], acc[ai][bj][m][n], 0, 0, 0); __builtin_amdgcn_s_setprio(0); } while (0)
; #define PG8_WAIT_V(n) asm volatile("s_waitcnt vmcnt(" #n ")" ::: "memory")
; #define PG8_WAIT_L(n) asm volatile("s_waitcnt lgkmcnt(" #n ")" ::: "memory")
; #define PG8_BAR __builtin_amdgcn_s_barrier()
; #define PG8_SCHED __builtin_amdgcn_sched_barrier(0)
; template <class Epi, bool ALIGN_EPI = true>
; __device__ __forceinline__ void gemm_phase(LAS unsigned char* lds, const Gemm g, const StaticOrder& S, const Epi& E, int wave_k) {
;     ...
;             PG8_WAIT_V(8); PG8_WAIT_L(0); PG8_BAR; PG8_MMA(1, 0, At, B0); PG8_MMA(1, 1, At, B1); PG8_BAR; PG8_SCHED;
;             PG8_LDB(B0, 1, 0); PG8_LDB(B1, 1, 1); PG8_SCHED; PG8_LDA(At, 1, 0); PG8_STAGE(PG8_SA(0, 1), a2 + hstepA, voffA);
;             PG8_WAIT_V(8); PG8_WAIT_L(0); PG8_BAR; PG8_MMA(0, 0, At, B0); PG8_MMA(0, 1, At, B1); PG8_BAR; PG8_SCHED;
	s_setprio 1
	s_waitcnt lgkmcnt(0)
	v_mfma_f32_16x16x32_bf16 v[60:63], v[138:141], v[178:181], v[60:63]
	v_mfma_f32_16x16x32_bf16 v[56:59], v[152:155], v[178:181], v[56:59]
	v_mfma_f32_16x16x32_bf16 v[44:47], v[138:141], v[186:189], v[44:47]
	v_mfma_f32_16x16x32_bf16 v[40:43], v[152:155], v[186:189], v[40:43]
	v_mfma_f32_16x16x32_bf16 v[28:31], v[138:141], v[194:197], v[28:31]
	v_mfma_f32_16x16x32_bf16 v[24:27], v[152:155], v[194:197], v[24:27]
	v_mfma_f32_16x16x32_bf16 v[12:15], v[138:141], v[202:205], v[12:15]
	v_mfma_f32_16x16x32_bf16 v[8:11], v[152:155], v[202:205], v[8:11]
	v_mfma_f32_16x16x32_bf16 v[60:63], v[148:151], v[182:185], v[60:63]
	v_mfma_f32_16x16x32_bf16 v[56:59], v[156:159], v[182:185], v[56:59]
	v_mfma_f32_16x16x32_bf16 v[44:47], v[148:151], v[190:193], v[44:47]
	v_mfma_f32_16x16x32_bf16 v[40:43], v[156:159], v[190:193], v[40:43]
	v_mfma_f32_16x16x32_bf16 v[28:31], v[148:151], v[198:201], v[28:31]
	v_mfma_f32_16x16x32_bf16 v[24:27], v[156:159], v[198:201], v[24:27]
	v_mfma_f32_16x16x32_bf16 v[12:15], v[148:151], v[206:209], v[12:15]
	v_mfma_f32_16x16x32_bf16 v[8:11], v[156:159], v[206:209], v[8:11]
	s_setprio 0
	s_setprio 1
	v_mfma_f32_16x16x32_bf16 v[52:55], v[162:165], v[178:181], v[52:55]
	v_mfma_f32_16x16x32_bf16 v[48:51], v[170:173], v[178:181], v[48:51]
	v_mfma_f32_16x16x32_bf16 v[36:39], v[162:165], v[186:189], v[36:39]
	v_mfma_f32_16x16x32_bf16 v[32:35], v[170:173], v[186:189], v[32:35]
	v_mfma_f32_16x16x32_bf16 v[20:23], v[162:165], v[194:197], v[20:23]
	v_mfma_f32_16x16x32_bf16 v[16:19], v[170:173], v[194:197], v[16:19]
	v_mfma_f32_16x16x32_bf16 v[4:7], v[162:165], v[202:205], v[4:7]
	v_mfma_f32_16x16x32_bf16 v[0:3], v[170:173], v[202:205], v[0:3]
	v_mfma_f32_16x16x32_bf16 v[52:55], v[166:169], v[182:185], v[52:55]
	v_mfma_f32_16x16x32_bf16 v[48:51], v[174:177], v[182:185], v[48:51]
	v_mfma_f32_16x16x32_bf16 v[36:39], v[166:169], v[190:193], v[36:39]
	v_mfma_f32_16x16x32_bf16 v[32:35], v[174:177], v[190:193], v[32:35]
	v_mfma_f32_16x16x32_bf16 v[20:23], v[166:169], v[198:201], v[20:23]
	v_mfma_f32_16x16x32_bf16 v[16:19], v[174:177], v[198:201], v[16:19]
	v_mfma_f32_16x16x32_bf16 v[4:7], v[166:169], v[206:209], v[4:7]
	v_mfma_f32_16x16x32_bf16 v[0:3], v[174:177], v[206:209], v[0:3]
	s_setprio 0
	s_barrier
	s_add_i32 s71, 0, 0x18000
	s_add_i32 s72, 0, 0x1c000
	v_add_u32_e32 v156, s71, v145
	v_add_u32_e32 v174, s72, v145
	ds_read_b128 v[138:141], v156
	ds_read_b128 v[148:151], v156 offset:1024
	ds_read_b128 v[152:155], v156 offset:2048
	ds_read_b128 v[156:159], v156 offset:3072
	ds_read_b128 v[162:165], v174
	ds_read_b128 v[166:169], v174 offset:1024
	ds_read_b128 v[170:173], v174 offset:2048
	ds_read_b128 v[174:177], v174 offset:3072
	s_add_u32 s24, s28, 0xb0000
	s_addc_u32 s25, s29, 0
	s_mov_b32 m0, s59
	ds_read_b128 v[178:181], v147 offset:32768
	ds_read_b128 v[182:185], v147 offset:33792
	ds_read_b128 v[186:189], v147 offset:34816
	ds_read_b128 v[190:193], v147 offset:35840
	ds_read_b128 v[194:197], v147 offset:36864
	ds_read_b128 v[198:201], v147 offset:37888
	ds_read_b128 v[202:205], v147 offset:38912
	ds_read_b128 v[206:209], v147 offset:39936
	global_load_lds_dwordx4 v128, s[24:25]
	s_mov_b32 m0, s60
	s_nop 0
	global_load_lds_dwordx4 v130, s[24:25]
	s_waitcnt vmcnt(8)
	s_waitcnt lgkmcnt(0)
	s_barrier
	s_setprio 1
	s_waitcnt lgkmcnt(0)
	v_mfma_f32_16x16x32_bf16 v[124:127], v[138:141], v[178:181], v[124:127]
	v_mfma_f32_16x16x32_bf16 v[120:123], v[152:155], v[178:181], v[120:123]
	v_mfma_f32_16x16x32_bf16 v[108:111], v[138:141], v[186:189], v[108:111]
	v_mfma_f32_16x16x32_bf16 v[104:107], v[152:155], v[186:189], v[104:107]
	v_mfma_f32_16x16x32_bf16 v[92:95], v[138:141], v[194:197], v[92:95]
	v_mfma_f32_16x16x32_bf16 v[88:91], v[152:155], v[194:197], v[88:91]
	v_mfma_f32_16x16x32_bf16 v[76:79], v[138:141], v[202:205], v[76:79]
	v_mfma_f32_16x16x32_bf16 v[72:75], v[152:155], v[202:205], v[72:75]
	v_mfma_f32_16x16x32_bf16 v[124:127], v[148:151], v[182:185], v[124:127]
	v_mfma_f32_16x16x32_bf16 v[120:123], v[156:159], v[182:185], v[120:123]
	v_mfma_f32_16x16x32_bf16 v[108:111], v[148:151], v[190:193], v[108:111]
	v_mfma_f32_16x16x32_bf16 v[104:107], v[156:159], v[190:193], v[104:107]
	v_mfma_f32_16x16x32_bf16 v[92:95], v[148:151], v[198:201], v[92:95]
	v_mfma_f32_16x16x32_bf16 v[88:91], v[156:159], v[198:201], v[88:91]
	v_mfma_f32_16x16x32_bf16 v[76:79], v[148:151], v[206:209], v[76:79]
	v_mfma_f32_16x16x32_bf16 v[72:75], v[156:159], v[206:209], v[72:75]
	s_setprio 0
	s_setprio 1
	v_mfma_f32_16x16x32_bf16 v[116:119], v[162:165], v[178:181], v[116:119]
	v_mfma_f32_16x16x32_bf16 v[112:115], v[170:173], v[178:181], v[112:115]
	v_mfma_f32_16x16x32_bf16 v[100:103], v[162:165], v[186:189], v[100:103]
	v_mfma_f32_16x16x32_bf16 v[96:99], v[170:173], v[186:189], v[96:99]
	v_mfma_f32_16x16x32_bf16 v[84:87], v[162:165], v[194:197], v[84:87]
	v_mfma_f32_16x16x32_bf16 v[80:83], v[170:173], v[194:197], v[80:83]
	v_mfma_f32_16x16x32_bf16 v[68:71], v[162:165], v[202:205], v[68:71]
	v_mfma_f32_16x16x32_bf16 v[64:67], v[170:173], v[202:205], v[64:67]
	v_mfma_f32_16x16x32_bf16 v[116:119], v[166:169], v[182:185], v[116:119]
	v_mfma_f32_16x16x32_bf16 v[112:115], v[174:177], v[182:185], v[112:115]
	v_mfma_f32_16x16x32_bf16 v[100:103], v[166:169], v[190:193], v[100:103]
	v_mfma_f32_16x16x32_bf16 v[96:99], v[174:177], v[190:193], v[96:99]
	v_mfma_f32_16x16x32_bf16 v[84:87], v[166:169], v[198:201], v[84:87]
	v_mfma_f32_16x16x32_bf16 v[80:83], v[174:177], v[198:201], v[80:83]
	v_mfma_f32_16x16x32_bf16 v[68:71], v[166:169], v[206:209], v[68:71]
	v_mfma_f32_16x16x32_bf16 v[64:67], v[174:177], v[206:209], v[64:67]
	s_setprio 0
	s_barrier
; #define PG8_STAGE(bufoff, gbase, voff) do { _Pragma("unroll") for (int _i = 0; _i < 2; ++_i) \
;         __builtin_amdgcn_global_load_lds((const unsigned*)((const char*)(gbase) + (voff)[_i]), (LAS unsigned*)(lds + (bufoff) + ldsw + _i * 8192), 16, 0, 0); } while (0)
; #define PG8_LDA(dst, b, h) do { _Pragma("unroll") for (int m = 0; m < 4; ++m) _Pragma("unroll") for (int k = 0; k < 2; ++k) dst[m][k] = *(const LAS bf16x8*)(lds + PG8_SA(b, h) + aoff + m * 2048 + k * 1024); } while (0)
; #define PG8_MMA(ai, bj, At, Bt) do { __builtin_amdgcn_s_setprio(1); _Pragma("unroll") for (int m = 0; m < 4; ++m) _Pragma("unroll") for (int n = 0; n < 2; ++n) _Pragma("unroll") for (int k = 0; k < 2; ++k) \
;         acc[ai][bj][m][n] = __builtin_amdgcn_mfma_f32_16x16x32_bf16(Bt[n][k], At[m][k], acc[ai][bj][m][n], 0, 0, 0); __builtin_amdgcn_s_setprio(0); } while (0)
; #define PG8_WAIT_V(n) asm volatile("s_waitcnt vmcnt(" #n ")" ::: "memory")
; #define PG8_WAIT_L(n) asm volatile("s_waitcnt lgkmcnt(" #n ")" ::: "memory")
; #define PG8_BAR __builtin_amdgcn_s_barrier()
; #define PG8_SCHED __builtin_amdgcn_sched_barrier(0)
; template <class Epi, bool ALIGN_EPI = true>
; __device__ __forceinline__ void gemm_phase(LAS unsigned char* lds, const Gemm g, const StaticOrder& S, const Epi& E, int wave_k) {
;     ...
;             PG8_LDA(At, 1, 1); PG8_STAGE(PG8_SB(1, 0), b3, voffB); PG8_STAGE(PG8_SB(1, 1), b3 + hstepB, voffB); PG8_STAGE(PG8_SA(1, 0), a3, voffA);
;             PG8_WAIT_V(8); PG8_WAIT_L(0); PG8_BAR; PG8_MMA(1, 0, At, B0); PG8_MMA(1, 1, At, B1); PG8_BAR; PG8_SCHED;
;         }
;         if constexpr (ALIGN_EPI) { if (wr == 0) PG8_BAR; }
	s_add_i32 s24, s71, s52
	v_lshl_add_u64 v[142:143], v[142:143], 0, s[22:23]
	s_mov_b32 m0, s24
	ds_read_b128 v[178:181], v147 offset:49152
	ds_read_b128 v[182:185], v147 offset:50176
	ds_read_b128 v[186:189], v147 offset:51200
	ds_read_b128 v[190:193], v147 offset:52224
	ds_read_b128 v[194:197], v147 offset:53248
	ds_read_b128 v[198:201], v147 offset:54272
	ds_read_b128 v[202:205], v147 offset:55296
	ds_read_b128 v[206:209], v147 offset:56320
	global_load_lds_dwordx4 v[142:143], off
	s_add_i32 m0, s24, 0x2000
	s_add_u32 s24, s26, 0xb0080
	v_lshl_add_u64 v[142:143], v[210:211], 0, s[22:23]
	s_addc_u32 s25, s27, 0
	s_add_i32 s26, s72, s52
	global_load_lds_dwordx4 v[142:143], off
	s_mov_b32 m0, s26
	s_nop 0
	global_load_lds_dwordx4 v160, s[24:25]
	s_add_i32 m0, s26, 0x2000
	s_nop 0
	global_load_lds_dwordx4 v132, s[24:25]
	v_lshl_add_u64 v[142:143], v[212:213], 0, s[22:23]
	s_mov_b32 m0, s50
	s_nop 0
	global_load_lds_dwordx4 v[142:143], off
	v_lshl_add_u64 v[142:143], v[218:219], 0, s[22:23]
	s_mov_b32 m0, s51
	s_nop 0
	global_load_lds_dwordx4 v[142:143], off
	s_waitcnt vmcnt(8)
	s_waitcnt lgkmcnt(0)
	s_barrier
	s_setprio 1
	s_waitcnt lgkmcnt(0)
	v_mfma_f32_16x16x32_bf16 v[60:63], v[138:141], v[178:181], v[60:63]
	v_mfma_f32_16x16x32_bf16 v[56:59], v[152:155], v[178:181], v[56:59]
	v_mfma_f32_16x16x32_bf16 v[44:47], v[138:141], v[186:189], v[44:47]
	v_mfma_f32_16x16x32_bf16 v[40:43], v[152:155], v[186:189], v[40:43]
	v_mfma_f32_16x16x32_bf16 v[28:31], v[138:141], v[194:197], v[28:31]
	v_mfma_f32_16x16x32_bf16 v[24:27], v[152:155], v[194:197], v[24:27]
	v_mfma_f32_16x16x32_bf16 v[12:15], v[138:141], v[202:205], v[12:15]
	v_mfma_f32_16x16x32_bf16 v[8:11], v[152:155], v[202:205], v[8:11]
	v_mfma_f32_16x16x32_bf16 v[60:63], v[148:151], v[182:185], v[60:63]
	v_mfma_f32_16x16x32_bf16 v[56:59], v[156:159], v[182:185], v[56:59]
	v_mfma_f32_16x16x32_bf16 v[44:47], v[148:151], v[190:193], v[44:47]
	v_mfma_f32_16x16x32_bf16 v[40:43], v[156:159], v[190:193], v[40:43]
	v_mfma_f32_16x16x32_bf16 v[28:31], v[148:151], v[198:201], v[28:31]
	v_mfma_f32_16x16x32_bf16 v[24:27], v[156:159], v[198:201], v[24:27]
	v_mfma_f32_16x16x32_bf16 v[12:15], v[148:151], v[206:209], v[12:15]
	v_mfma_f32_16x16x32_bf16 v[8:11], v[156:159], v[206:209], v[8:11]
	s_setprio 0
	s_setprio 1
	v_mfma_f32_16x16x32_bf16 v[52:55], v[162:165], v[178:181], v[52:55]
	v_mfma_f32_16x16x32_bf16 v[48:51], v[170:173], v[178:181], v[48:51]
	v_mfma_f32_16x16x32_bf16 v[36:39], v[162:165], v[186:189], v[36:39]
	v_mfma_f32_16x16x32_bf16 v[32:35], v[170:173], v[186:189], v[32:35]
	v_mfma_f32_16x16x32_bf16 v[20:23], v[162:165], v[194:197], v[20:23]
	v_mfma_f32_16x16x32_bf16 v[16:19], v[170:173], v[194:197], v[16:19]
	v_mfma_f32_16x16x32_bf16 v[4:7], v[162:165], v[202:205], v[4:7]
	v_mfma_f32_16x16x32_bf16 v[0:3], v[170:173], v[202:205], v[0:3]
	v_mfma_f32_16x16x32_bf16 v[52:55], v[166:169], v[182:185], v[52:55]
	v_mfma_f32_16x16x32_bf16 v[48:51], v[174:177], v[182:185], v[48:51]
	v_mfma_f32_16x16x32_bf16 v[36:39], v[166:169], v[190:193], v[36:39]
	v_mfma_f32_16x16x32_bf16 v[32:35], v[174:177], v[190:193], v[32:35]
	v_mfma_f32_16x16x32_bf16 v[20:23], v[166:169], v[198:201], v[20:23]
	v_mfma_f32_16x16x32_bf16 v[16:19], v[174:177], v[198:201], v[16:19]
	v_mfma_f32_16x16x32_bf16 v[4:7], v[166:169], v[206:209], v[4:7]
	v_mfma_f32_16x16x32_bf16 v[0:3], v[174:177], v[206:209], v[0:3]
	s_setprio 0
	s_barrier
	s_add_i32 s70, s70, 2
	s_add_u32 s46, s46, 0x100
	s_addc_u32 s47, s47, 0
	s_cmp_gt_u32 s70, 41
	s_mov_b64 s[24:25], s[16:17]
	s_cbranch_scc0 .LBB0_170
	s_and_b64 vcc, exec, s[34:35]
	s_cbranch_vccz .LBB0_173
	s_barrier

; #define PG8_STAGE(bufoff, gbase, voff) do { _Pragma("unroll") for (int _i = 0; _i < 2; ++_i) \
;         __builtin_amdgcn_global_load_lds((const unsigned*)((const char*)(gbase) + (voff)[_i]), (LAS unsigned*)(lds + (bufoff) + ldsw + _i * 8192), 16, 0, 0); } while (0)
; #define PG8_LDA(dst, b, h) do { _Pragma("unroll") for (int m = 0; m < 4; ++m) _Pragma("unroll") for (int k = 0; k < 2; ++k) dst[m][k] = *(const LAS bf16x8*)(lds + PG8_SA(b, h) + aoff + m * 2048 + k * 1024); } while (0)
; #define PG8_LDB(dst, b, h) do { _Pragma("unroll") for (int n = 0; n < 2; ++n) _Pragma("unroll") for (int k = 0; k < 2; ++k) dst[n][k] = *(const LAS bf16x8*)(lds + PG8_SB(b, h) + boff + n * 2048 + k * 1024); } while (0)
; #define PG8_MMA(ai, bj, At, Bt) do { __builtin_amdgcn_s_setprio(1); _Pragma("unroll") for (int m = 0; m < 4; ++m) _Pragma("unroll") for (int n = 0; n < 2; ++n) _Pragma("unroll") for (int k = 0; k < 2; ++k) \
;         acc[ai][bj][m][n] = __builtin_amdgcn_mfma_f32_16x16x32_bf16(Bt[n][k], At[m][k], acc[ai][bj][m][n], 0, 0, 0); __builtin_amdgcn_s_setprio(0); } while (0)
; #define PG8_WAIT_V(n) asm volatile("s_waitcnt vmcnt(" #n ")" ::: "memory")
; #define PG8_WAIT_L(n) asm volatile("s_waitcnt lgkmcnt(" #n ")" ::: "memory")
; #define PG8_BAR __builtin_amdgcn_s_barrier()
; #define PG8_SCHED __builtin_amdgcn_sched_barrier(0)
; template <class Epi, bool ALIGN_EPI = true>
; __device__ __forceinline__ void gemm_phase(LAS unsigned char* lds, const Gemm g, const StaticOrder& S, const Epi& E, int wave_k) {
;     ...
;         for (int t = 0; t < nt; t += 2) {
;             const bool last = (t == nt - 2);
;             const char* a1 = cA + (size_t)(t + 1) * kstep;
;             const char* a2 = last ? nA : cA + (size_t)(t + 2) * kstep; const char* b2 = last ? nB : cB + (size_t)(t + 2) * kstep;
;             const char* a3 = a2 + kstep; const char* b3 = b2 + kstep;
;             PG8_LDB(B0, 0, 0); PG8_LDB(B1, 0, 1); PG8_SCHED; PG8_LDA(At, 0, 0); PG8_STAGE(PG8_SA(1, 1), a1 + hstepA, voffA);
;             PG8_WAIT_V(8); PG8_WAIT_L(0); PG8_BAR; PG8_MMA(0, 0, At, B0); PG8_MMA(0, 1, At, B1); PG8_BAR; PG8_SCHED;
;             PG8_LDA(At, 0, 1); PG8_STAGE(PG8_SB(0, 0), b2, voffB); PG8_STAGE(PG8_SB(0, 1), b2 + hstepB, voffB); PG8_STAGE(PG8_SA(0, 0), a2, voffA);
;             PG8_WAIT_V(8); PG8_WAIT_L(0); PG8_BAR; PG8_MMA(1, 0, At, B0); PG8_MMA(1, 1, At, B1); PG8_BAR; PG8_SCHED;
.LBB0_256:
	s_add_u32 s16, s46, 0xfffc0080
	s_addc_u32 s17, s47, -1
	s_add_i32 s49, 0, 0x10000
	s_cmp_eq_u32 s48, 12
	s_cselect_b32 s25, s1, s17
	s_cselect_b32 s24, s26, s16
	s_cselect_b32 s17, s27, s45
	s_cselect_b32 s16, s37, s41
	s_add_i32 s72, 0, 0x14000
	v_add_u32_e32 v152, s49, v168
	v_add_u32_e32 v160, s72, v168
	ds_read_b128 v[140:143], v152
	ds_read_b128 v[144:147], v152 offset:1024
	ds_read_b128 v[148:151], v152 offset:2048
	ds_read_b128 v[152:155], v152 offset:3072
	ds_read_b128 v[156:159], v160
	ds_read_b128 v[162:165], v160 offset:1024
	ds_read_b128 v[170:173], v160 offset:2048
	ds_read_b128 v[174:177], v160 offset:3072
	s_add_i32 m0, s59, 0xc000
	ds_read_b128 v[178:181], v169
	ds_read_b128 v[182:185], v169 offset:1024
	ds_read_b128 v[186:189], v169 offset:2048
	ds_read_b128 v[190:193], v169 offset:3072
	ds_read_b128 v[194:197], v169 offset:4096
	ds_read_b128 v[198:201], v169 offset:5120
	ds_read_b128 v[202:205], v169 offset:6144
	ds_read_b128 v[206:209], v169 offset:7168
	global_load_lds_dwordx4 v136, s[46:47]
	s_add_i32 m0, s59, 0xe000
	s_nop 0
	global_load_lds_dwordx4 v138, s[46:47]
	s_waitcnt vmcnt(8)
	s_waitcnt lgkmcnt(0)
	s_barrier
	s_setprio 1
	s_waitcnt lgkmcnt(0)
	v_mfma_f32_16x16x32_bf16 v[124:127], v[140:143], v[178:181], v[124:127]
	v_mfma_f32_16x16x32_bf16 v[120:123], v[148:151], v[178:181], v[120:123]
	v_mfma_f32_16x16x32_bf16 v[108:111], v[140:143], v[186:189], v[108:111]
	v_mfma_f32_16x16x32_bf16 v[104:107], v[148:151], v[186:189], v[104:107]
	v_mfma_f32_16x16x32_bf16 v[92:95], v[140:143], v[194:197], v[92:95]
	v_mfma_f32_16x16x32_bf16 v[88:91], v[148:151], v[194:197], v[88:91]
	v_mfma_f32_16x16x32_bf16 v[76:79], v[140:143], v[202:205], v[76:79]
	v_mfma_f32_16x16x32_bf16 v[72:75], v[148:151], v[202:205], v[72:75]
	v_mfma_f32_16x16x32_bf16 v[124:127], v[144:147], v[182:185], v[124:127]
	v_mfma_f32_16x16x32_bf16 v[120:123], v[152:155], v[182:185], v[120:123]
	v_mfma_f32_16x16x32_bf16 v[108:111], v[144:147], v[190:193], v[108:111]
	v_mfma_f32_16x16x32_bf16 v[104:107], v[152:155], v[190:193], v[104:107]
	v_mfma_f32_16x16x32_bf16 v[92:95], v[144:147], v[198:201], v[92:95]
	v_mfma_f32_16x16x32_bf16 v[88:91], v[152:155], v[198:201], v[88:91]
	v_mfma_f32_16x16x32_bf16 v[76:79], v[144:147], v[206:209], v[76:79]
	v_mfma_f32_16x16x32_bf16 v[72:75], v[152:155], v[206:209], v[72:75]
	s_setprio 0
	s_setprio 1
	v_mfma_f32_16x16x32_bf16 v[116:119], v[156:159], v[178:181], v[116:119]
	v_mfma_f32_16x16x32_bf16 v[112:115], v[170:173], v[178:181], v[112:115]
	v_mfma_f32_16x16x32_bf16 v[100:103], v[156:159], v[186:189], v[100:103]
	v_mfma_f32_16x16x32_bf16 v[96:99], v[170:173], v[186:189], v[96:99]
	v_mfma_f32_16x16x32_bf16 v[84:87], v[156:159], v[194:197], v[84:87]
	v_mfma_f32_16x16x32_bf16 v[80:83], v[170:173], v[194:197], v[80:83]
	v_mfma_f32_16x16x32_bf16 v[68:71], v[156:159], v[202:205], v[68:71]
	v_mfma_f32_16x16x32_bf16 v[64:67], v[170:173], v[202:205], v[64:67]
	v_mfma_f32_16x16x32_bf16 v[116:119], v[162:165], v[182:185], v[116:119]
	v_mfma_f32_16x16x32_bf16 v[112:115], v[174:177], v[182:185], v[112:115]
	v_mfma_f32_16x16x32_bf16 v[100:103], v[162:165], v[190:193], v[100:103]
	v_mfma_f32_16x16x32_bf16 v[96:99], v[174:177], v[190:193], v[96:99]
	v_mfma_f32_16x16x32_bf16 v[84:87], v[162:165], v[198:201], v[84:87]
	v_mfma_f32_16x16x32_bf16 v[80:83], v[174:177], v[198:201], v[80:83]
	v_mfma_f32_16x16x32_bf16 v[68:71], v[162:165], v[206:209], v[68:71]
	v_mfma_f32_16x16x32_bf16 v[64:67], v[174:177], v[206:209], v[64:67]
	s_setprio 0
	s_barrier
	s_add_i32 s49, s49, s58
	v_lshl_add_u64 v[210:211], s[16:17], 0, v[130:131]
	s_mov_b32 m0, s49
	ds_read_b128 v[178:181], v169 offset:16384
	ds_read_b128 v[182:185], v169 offset:17408
	ds_read_b128 v[186:189], v169 offset:18432
	ds_read_b128 v[190:193], v169 offset:19456
	ds_read_b128 v[194:197], v169 offset:20480
	ds_read_b128 v[198:201], v169 offset:21504
	ds_read_b128 v[202:205], v169 offset:22528
	ds_read_b128 v[206:209], v169 offset:23552
	global_load_lds_dwordx4 v[210:211], off
	s_add_i32 m0, s49, 0x2000
	s_add_u32 s66, s16, 0x40000
	v_lshl_add_u64 v[212:213], s[16:17], 0, v[134:135]
	s_addc_u32 s67, s17, 0
	s_add_i32 s49, s72, s58
	global_load_lds_dwordx4 v[212:213], off
	s_mov_b32 m0, s49
	v_lshl_add_u64 v[220:221], s[24:25], 0, v[132:133]
	global_load_lds_dwordx4 v130, s[66:67]
	s_add_i32 m0, s49, 0x2000
	s_nop 0
	global_load_lds_dwordx4 v134, s[66:67]
	v_lshl_add_u64 v[218:219], s[24:25], 0, v[128:129]
	s_mov_b32 m0, s59
	s_nop 0
	global_load_lds_dwordx4 v[218:219], off
	s_mov_b32 m0, s60
	s_nop 0
	global_load_lds_dwordx4 v[220:221], off
	s_waitcnt vmcnt(8)
	s_waitcnt lgkmcnt(0)
	s_barrier
; #define PG8_STAGE(bufoff, gbase, voff) do { _Pragma("unroll") for (int _i = 0; _i < 2; ++_i) \
;         __builtin_amdgcn_global_load_lds((const unsigned*)((const char*)(gbase) + (voff)[_i]), (LAS unsigned*)(lds + (bufoff) + ldsw + _i * 8192), 16, 0, 0); } while (0)
; #define PG8_LDA(dst, b, h) do { _Pragma("unroll") for (int m = 0; m < 4; ++m) _Pragma("unroll") for (int k = 0; k < 2; ++k) dst[m][k] = *(const LAS bf16x8*)(lds + PG8_SA(b, h) + aoff + m * 2048 + k * 1024); } while (0)
; #define PG8_LDB(dst, b, h) do { _Pragma("unroll") for (int n = 0; n < 2; ++n) _Pragma("unroll") for (int k = 0; k < 2; ++k) dst[n][k] = *(const LAS bf16x8*)(lds + PG8_SB(b, h) + boff + n * 2048 + k * 1024); } while (0)
; #define PG8_MMA(ai, bj, At, Bt) do { __builtin_amdgcn_s_setprio(1); _Pragma("unroll") for (int m = 0; m < 4; ++m) _Pragma("unroll") for (int n = 0; n < 2; ++n) _Pragma("unroll") for (int k = 0; k < 2; ++k) \
;         acc[ai][bj][m][n] = __builtin_amdgcn_mfma_f32_16x16x32_bf16(Bt[n][k], At[m][k], acc[ai][bj][m][n], 0, 0, 0); __builtin_amdgcn_s_setprio(0); } while (0)
; #define PG8_WAIT_V(n) asm volatile("s_waitcnt vmcnt(" #n ")" ::: "memory")
; #define PG8_WAIT_L(n) asm volatile("s_waitcnt lgkmcnt(" #n ")" ::: "memory")
; #define PG8_BAR __builtin_amdgcn_s_barrier()
; #define PG8_SCHED __builtin_amdgcn_sched_barrier(0)
; template <class Epi, bool ALIGN_EPI = true>
; __device__ __forceinline__ void gemm_phase(LAS unsigned char* lds, const Gemm g, const StaticOrder& S, const Epi& E, int wave_k) {
;     ...
;             PG8_WAIT_V(8); PG8_WAIT_L(0); PG8_BAR; PG8_MMA(1, 0, At, B0); PG8_MMA(1, 1, At, B1); PG8_BAR; PG8_SCHED;
;             PG8_LDB(B0, 1, 0); PG8_LDB(B1, 1, 1); PG8_SCHED; PG8_LDA(At, 1, 0); PG8_STAGE(PG8_SA(0, 1), a2 + hstepA, voffA);
;             PG8_WAIT_V(8); PG8_WAIT_L(0); PG8_BAR; PG8_MMA(0, 0, At, B0); PG8_MMA(0, 1, At, B1); PG8_BAR; PG8_SCHED;
	s_setprio 1
	s_waitcnt lgkmcnt(0)
	v_mfma_f32_16x16x32_bf16 v[60:63], v[140:143], v[178:181], v[60:63]
	v_mfma_f32_16x16x32_bf16 v[56:59], v[148:151], v[178:181], v[56:59]
	v_mfma_f32_16x16x32_bf16 v[44:47], v[140:143], v[186:189], v[44:47]
	v_mfma_f32_16x16x32_bf16 v[40:43], v[148:151], v[186:189], v[40:43]
	v_mfma_f32_16x16x32_bf16 v[28:31], v[140:143], v[194:197], v[28:31]
	v_mfma_f32_16x16x32_bf16 v[24:27], v[148:151], v[194:197], v[24:27]
	v_mfma_f32_16x16x32_bf16 v[12:15], v[140:143], v[202:205], v[12:15]
	v_mfma_f32_16x16x32_bf16 v[8:11], v[148:151], v[202:205], v[8:11]
	v_mfma_f32_16x16x32_bf16 v[60:63], v[144:147], v[182:185], v[60:63]
	v_mfma_f32_16x16x32_bf16 v[56:59], v[152:155], v[182:185], v[56:59]
	v_mfma_f32_16x16x32_bf16 v[44:47], v[144:147], v[190:193], v[44:47]
	v_mfma_f32_16x16x32_bf16 v[40:43], v[152:155], v[190:193], v[40:43]
	v_mfma_f32_16x16x32_bf16 v[28:31], v[144:147], v[198:201], v[28:31]
	v_mfma_f32_16x16x32_bf16 v[24:27], v[152:155], v[198:201], v[24:27]
	v_mfma_f32_16x16x32_bf16 v[12:15], v[144:147], v[206:209], v[12:15]
	v_mfma_f32_16x16x32_bf16 v[8:11], v[152:155], v[206:209], v[8:11]
	s_setprio 0
	s_setprio 1
	v_mfma_f32_16x16x32_bf16 v[52:55], v[156:159], v[178:181], v[52:55]
	v_mfma_f32_16x16x32_bf16 v[48:51], v[170:173], v[178:181], v[48:51]
	v_mfma_f32_16x16x32_bf16 v[36:39], v[156:159], v[186:189], v[36:39]
	v_mfma_f32_16x16x32_bf16 v[32:35], v[170:173], v[186:189], v[32:35]
	v_mfma_f32_16x16x32_bf16 v[20:23], v[156:159], v[194:197], v[20:23]
	v_mfma_f32_16x16x32_bf16 v[16:19], v[170:173], v[194:197], v[16:19]
	v_mfma_f32_16x16x32_bf16 v[4:7], v[156:159], v[202:205], v[4:7]
	v_mfma_f32_16x16x32_bf16 v[0:3], v[170:173], v[202:205], v[0:3]
	v_mfma_f32_16x16x32_bf16 v[52:55], v[162:165], v[182:185], v[52:55]
	v_mfma_f32_16x16x32_bf16 v[48:51], v[174:177], v[182:185], v[48:51]
	v_mfma_f32_16x16x32_bf16 v[36:39], v[162:165], v[190:193], v[36:39]
	v_mfma_f32_16x16x32_bf16 v[32:35], v[174:177], v[190:193], v[32:35]
	v_mfma_f32_16x16x32_bf16 v[20:23], v[162:165], v[198:201], v[20:23]
	v_mfma_f32_16x16x32_bf16 v[16:19], v[174:177], v[198:201], v[16:19]
	v_mfma_f32_16x16x32_bf16 v[4:7], v[162:165], v[206:209], v[4:7]
	v_mfma_f32_16x16x32_bf16 v[0:3], v[174:177], v[206:209], v[0:3]
	s_setprio 0
	s_barrier
	s_add_i32 s49, 0, 0x18000
	s_add_i32 s66, 0, 0x1c000
	v_add_u32_e32 v152, s49, v168
	v_add_u32_e32 v160, s66, v168
	ds_read_b128 v[140:143], v152
	ds_read_b128 v[144:147], v152 offset:1024
	ds_read_b128 v[148:151], v152 offset:2048
	ds_read_b128 v[152:155], v152 offset:3072
	ds_read_b128 v[156:159], v160
	ds_read_b128 v[162:165], v160 offset:1024
	ds_read_b128 v[170:173], v160 offset:2048
	ds_read_b128 v[174:177], v160 offset:3072
	s_add_u32 s24, s24, 0x40000
	s_addc_u32 s25, s25, 0
	s_mov_b32 m0, s61
	ds_read_b128 v[178:181], v169 offset:32768
	ds_read_b128 v[182:185], v169 offset:33792
	ds_read_b128 v[186:189], v169 offset:34816
	ds_read_b128 v[190:193], v169 offset:35840
	ds_read_b128 v[194:197], v169 offset:36864
	ds_read_b128 v[198:201], v169 offset:37888
	ds_read_b128 v[202:205], v169 offset:38912
	ds_read_b128 v[206:209], v169 offset:39936
	global_load_lds_dwordx4 v128, s[24:25]
	s_mov_b32 m0, s62
	s_nop 0
	global_load_lds_dwordx4 v132, s[24:25]
	s_waitcnt vmcnt(8)
	s_waitcnt lgkmcnt(0)
	s_barrier
	s_setprio 1
	s_waitcnt lgkmcnt(0)
	v_mfma_f32_16x16x32_bf16 v[124:127], v[140:143], v[178:181], v[124:127]
	v_mfma_f32_16x16x32_bf16 v[120:123], v[148:151], v[178:181], v[120:123]
	v_mfma_f32_16x16x32_bf16 v[108:111], v[140:143], v[186:189], v[108:111]
	v_mfma_f32_16x16x32_bf16 v[104:107], v[148:151], v[186:189], v[104:107]
	v_mfma_f32_16x16x32_bf16 v[92:95], v[140:143], v[194:197], v[92:95]
	v_mfma_f32_16x16x32_bf16 v[88:91], v[148:151], v[194:197], v[88:91]
	v_mfma_f32_16x16x32_bf16 v[76:79], v[140:143], v[202:205], v[76:79]
	v_mfma_f32_16x16x32_bf16 v[72:75], v[148:151], v[202:205], v[72:75]
	v_mfma_f32_16x16x32_bf16 v[124:127], v[144:147], v[182:185], v[124:127]
	v_mfma_f32_16x16x32_bf16 v[120:123], v[152:155], v[182:185], v[120:123]
	v_mfma_f32_16x16x32_bf16 v[108:111], v[144:147], v[190:193], v[108:111]
	v_mfma_f32_16x16x32_bf16 v[104:107], v[152:155], v[190:193], v[104:107]
	v_mfma_f32_16x16x32_bf16 v[92:95], v[144:147], v[198:201], v[92:95]
	v_mfma_f32_16x16x32_bf16 v[88:91], v[152:155], v[198:201], v[88:91]
	v_mfma_f32_16x16x32_bf16 v[76:79], v[144:147], v[206:209], v[76:79]
	v_mfma_f32_16x16x32_bf16 v[72:75], v[152:155], v[206:209], v[72:75]
	s_setprio 0
	s_setprio 1
	v_mfma_f32_16x16x32_bf16 v[116:119], v[156:159], v[178:181], v[116:119]
	v_mfma_f32_16x16x32_bf16 v[112:115], v[170:173], v[178:181], v[112:115]
	v_mfma_f32_16x16x32_bf16 v[100:103], v[156:159], v[186:189], v[100:103]
	v_mfma_f32_16x16x32_bf16 v[96:99], v[170:173], v[186:189], v[96:99]
	v_mfma_f32_16x16x32_bf16 v[84:87], v[156:159], v[194:197], v[84:87]
	v_mfma_f32_16x16x32_bf16 v[80:83], v[170:173], v[194:197], v[80:83]
	v_mfma_f32_16x16x32_bf16 v[68:71], v[156:159], v[202:205], v[68:71]
	v_mfma_f32_16x16x32_bf16 v[64:67], v[170:173], v[202:205], v[64:67]
	v_mfma_f32_16x16x32_bf16 v[116:119], v[162:165], v[182:185], v[116:119]
	v_mfma_f32_16x16x32_bf16 v[112:115], v[174:177], v[182:185], v[112:115]
	v_mfma_f32_16x16x32_bf16 v[100:103], v[162:165], v[190:193], v[100:103]
	v_mfma_f32_16x16x32_bf16 v[96:99], v[174:177], v[190:193], v[96:99]
	v_mfma_f32_16x16x32_bf16 v[84:87], v[162:165], v[198:201], v[84:87]
	v_mfma_f32_16x16x32_bf16 v[80:83], v[174:177], v[198:201], v[80:83]
	v_mfma_f32_16x16x32_bf16 v[68:71], v[162:165], v[206:209], v[68:71]
	v_mfma_f32_16x16x32_bf16 v[64:67], v[174:177], v[206:209], v[64:67]
	s_setprio 0
	s_barrier
; #define PG8_STAGE(bufoff, gbase, voff) do { _Pragma("unroll") for (int _i = 0; _i < 2; ++_i) \
;         __builtin_amdgcn_global_load_lds((const unsigned*)((const char*)(gbase) + (voff)[_i]), (LAS unsigned*)(lds + (bufoff) + ldsw + _i * 8192), 16, 0, 0); } while (0)
; #define PG8_LDA(dst, b, h) do { _Pragma("unroll") for (int m = 0; m < 4; ++m) _Pragma("unroll") for (int k = 0; k < 2; ++k) dst[m][k] = *(const LAS bf16x8*)(lds + PG8_SA(b, h) + aoff + m * 2048 + k * 1024); } while (0)
; #define PG8_MMA(ai, bj, At, Bt) do { __builtin_amdgcn_s_setprio(1); _Pragma("unroll") for (int m = 0; m < 4; ++m) _Pragma("unroll") for (int n = 0; n < 2; ++n) _Pragma("unroll") for (int k = 0; k < 2; ++k) \
;         acc[ai][bj][m][n] = __builtin_amdgcn_mfma_f32_16x16x32_bf16(Bt[n][k], At[m][k], acc[ai][bj][m][n], 0, 0, 0); __builtin_amdgcn_s_setprio(0); } while (0)
; #define PG8_WAIT_V(n) asm volatile("s_waitcnt vmcnt(" #n ")" ::: "memory")
; #define PG8_WAIT_L(n) asm volatile("s_waitcnt lgkmcnt(" #n ")" ::: "memory")
; #define PG8_BAR __builtin_amdgcn_s_barrier()
; #define PG8_SCHED __builtin_amdgcn_sched_barrier(0)
; template <class Epi, bool ALIGN_EPI = true>
; __device__ __forceinline__ void gemm_phase(LAS unsigned char* lds, const Gemm g, const StaticOrder& S, const Epi& E, int wave_k) {
;     ...
;             PG8_LDA(At, 1, 1); PG8_STAGE(PG8_SB(1, 0), b3, voffB); PG8_STAGE(PG8_SB(1, 1), b3 + hstepB, voffB); PG8_STAGE(PG8_SA(1, 0), a3, voffA);
;             PG8_WAIT_V(8); PG8_WAIT_L(0); PG8_BAR; PG8_MMA(1, 0, At, B0); PG8_MMA(1, 1, At, B1); PG8_BAR; PG8_SCHED;
;         }
;         if constexpr (ALIGN_EPI) { if (wr == 0) PG8_BAR; }
	s_add_i32 s24, s49, s58
	v_lshl_add_u64 v[210:211], v[210:211], 0, s[22:23]
	s_mov_b32 m0, s24
	ds_read_b128 v[178:181], v169 offset:49152
	ds_read_b128 v[182:185], v169 offset:50176
	ds_read_b128 v[186:189], v169 offset:51200
	ds_read_b128 v[190:193], v169 offset:52224
	ds_read_b128 v[194:197], v169 offset:53248
	ds_read_b128 v[198:201], v169 offset:54272
	ds_read_b128 v[202:205], v169 offset:55296
	ds_read_b128 v[206:209], v169 offset:56320
	global_load_lds_dwordx4 v[210:211], off
	s_add_i32 m0, s24, 0x2000
	s_add_u32 s16, s16, 0x40080
	v_lshl_add_u64 v[210:211], v[212:213], 0, s[22:23]
	s_addc_u32 s17, s17, 0
	s_add_i32 s24, s66, s58
	global_load_lds_dwordx4 v[210:211], off
	s_mov_b32 m0, s24
	s_nop 0
	global_load_lds_dwordx4 v130, s[16:17]
	s_add_i32 m0, s24, 0x2000
	s_nop 0
	global_load_lds_dwordx4 v134, s[16:17]
	v_lshl_add_u64 v[210:211], v[218:219], 0, s[22:23]
	s_mov_b32 m0, s64
	s_nop 0
	global_load_lds_dwordx4 v[210:211], off
	v_lshl_add_u64 v[210:211], v[220:221], 0, s[22:23]
	s_mov_b32 m0, s65
	s_nop 0
	global_load_lds_dwordx4 v[210:211], off
	s_waitcnt vmcnt(8)
	s_waitcnt lgkmcnt(0)
	s_barrier
	s_setprio 1
	s_waitcnt lgkmcnt(0)
	v_mfma_f32_16x16x32_bf16 v[60:63], v[140:143], v[178:181], v[60:63]
	v_mfma_f32_16x16x32_bf16 v[56:59], v[148:151], v[178:181], v[56:59]
	v_mfma_f32_16x16x32_bf16 v[44:47], v[140:143], v[186:189], v[44:47]
	v_mfma_f32_16x16x32_bf16 v[40:43], v[148:151], v[186:189], v[40:43]
	v_mfma_f32_16x16x32_bf16 v[28:31], v[140:143], v[194:197], v[28:31]
	v_mfma_f32_16x16x32_bf16 v[24:27], v[148:151], v[194:197], v[24:27]
	v_mfma_f32_16x16x32_bf16 v[12:15], v[140:143], v[202:205], v[12:15]
	v_mfma_f32_16x16x32_bf16 v[8:11], v[148:151], v[202:205], v[8:11]
	v_mfma_f32_16x16x32_bf16 v[60:63], v[144:147], v[182:185], v[60:63]
	v_mfma_f32_16x16x32_bf16 v[56:59], v[152:155], v[182:185], v[56:59]
	v_mfma_f32_16x16x32_bf16 v[44:47], v[144:147], v[190:193], v[44:47]
	v_mfma_f32_16x16x32_bf16 v[40:43], v[152:155], v[190:193], v[40:43]
	v_mfma_f32_16x16x32_bf16 v[28:31], v[144:147], v[198:201], v[28:31]
	v_mfma_f32_16x16x32_bf16 v[24:27], v[152:155], v[198:201], v[24:27]
	v_mfma_f32_16x16x32_bf16 v[12:15], v[144:147], v[206:209], v[12:15]
	v_mfma_f32_16x16x32_bf16 v[8:11], v[152:155], v[206:209], v[8:11]
	s_setprio 0
	s_setprio 1
	v_mfma_f32_16x16x32_bf16 v[52:55], v[156:159], v[178:181], v[52:55]
	v_mfma_f32_16x16x32_bf16 v[48:51], v[170:173], v[178:181], v[48:51]
	v_mfma_f32_16x16x32_bf16 v[36:39], v[156:159], v[186:189], v[36:39]
	v_mfma_f32_16x16x32_bf16 v[32:35], v[170:173], v[186:189], v[32:35]
	v_mfma_f32_16x16x32_bf16 v[20:23], v[156:159], v[194:197], v[20:23]
	v_mfma_f32_16x16x32_bf16 v[16:19], v[170:173], v[194:197], v[16:19]
	v_mfma_f32_16x16x32_bf16 v[4:7], v[156:159], v[202:205], v[4:7]
	v_mfma_f32_16x16x32_bf16 v[0:3], v[170:173], v[202:205], v[0:3]
	v_mfma_f32_16x16x32_bf16 v[52:55], v[162:165], v[182:185], v[52:55]
	v_mfma_f32_16x16x32_bf16 v[48:51], v[174:177], v[182:185], v[48:51]
	v_mfma_f32_16x16x32_bf16 v[36:39], v[162:165], v[190:193], v[36:39]
	v_mfma_f32_16x16x32_bf16 v[32:35], v[174:177], v[190:193], v[32:35]
	v_mfma_f32_16x16x32_bf16 v[20:23], v[162:165], v[198:201], v[20:23]
	v_mfma_f32_16x16x32_bf16 v[16:19], v[174:177], v[198:201], v[16:19]
	v_mfma_f32_16x16x32_bf16 v[4:7], v[162:165], v[206:209], v[4:7]
	v_mfma_f32_16x16x32_bf16 v[0:3], v[174:177], v[206:209], v[0:3]
	s_setprio 0
	s_barrier
	s_add_i32 s48, s48, 2
	s_add_u32 s46, s46, 0x100
	s_addc_u32 s47, s47, 0
	s_add_u32 s41, s41, 0x100
	s_addc_u32 s45, s45, 0
	s_cmp_gt_u32 s48, 13
	s_cbranch_scc0 .LBB0_256
	s_and_b64 vcc, exec, s[34:35]
	s_cbranch_vccz .LBB0_259
	s_barrier

; #define PG8_STAGE(bufoff, gbase, voff) do { _Pragma("unroll") for (int _i = 0; _i < 2; ++_i) \
;         __builtin_amdgcn_global_load_lds((const unsigned*)((const char*)(gbase) + (voff)[_i]), (LAS unsigned*)(lds + (bufoff) + ldsw + _i * 8192), 16, 0, 0); } while (0)
; #define PG8_LDA(dst, b, h) do { _Pragma("unroll") for (int m = 0; m < 4; ++m) _Pragma("unroll") for (int k = 0; k < 2; ++k) dst[m][k] = *(const LAS bf16x8*)(lds + PG8_SA(b, h) + aoff + m * 2048 + k * 1024); } while (0)
; #define PG8_LDB(dst, b, h) do { _Pragma("unroll") for (int n = 0; n < 2; ++n) _Pragma("unroll") for (int k = 0; k < 2; ++k) dst[n][k] = *(const LAS bf16x8*)(lds + PG8_SB(b, h) + boff + n * 2048 + k * 1024); } while (0)
; #define PG8_MMA(ai, bj, At, Bt) do { __builtin_amdgcn_s_setprio(1); _Pragma("unroll") for (int m = 0; m < 4; ++m) _Pragma("unroll") for (int n = 0; n < 2; ++n) _Pragma("unroll") for (int k = 0; k < 2; ++k) \
;         acc[ai][bj][m][n] = __builtin_amdgcn_mfma_f32_16x16x32_bf16(Bt[n][k], At[m][k], acc[ai][bj][m][n], 0, 0, 0); __builtin_amdgcn_s_setprio(0); } while (0)
; #define PG8_WAIT_V(n) asm volatile("s_waitcnt vmcnt(" #n ")" ::: "memory")
; #define PG8_WAIT_L(n) asm volatile("s_waitcnt lgkmcnt(" #n ")" ::: "memory")
; #define PG8_BAR __builtin_amdgcn_s_barrier()
; #define PG8_SCHED __builtin_amdgcn_sched_barrier(0)
; template <class Epi, bool ALIGN_EPI = true>
; __device__ __forceinline__ void gemm_phase(LAS unsigned char* lds, const Gemm g, const StaticOrder& S, const Epi& E, int wave_k) {
;     ...
;         for (int t = 0; t < nt; t += 2) {
;             const bool last = (t == nt - 2);
;             const char* a1 = cA + (size_t)(t + 1) * kstep;
;             const char* a2 = last ? nA : cA + (size_t)(t + 2) * kstep; const char* b2 = last ? nB : cB + (size_t)(t + 2) * kstep;
;             const char* a3 = a2 + kstep; const char* b3 = b2 + kstep;
;             PG8_LDB(B0, 0, 0); PG8_LDB(B1, 0, 1); PG8_SCHED; PG8_LDA(At, 0, 0); PG8_STAGE(PG8_SA(1, 1), a1 + hstepA, voffA);
;             PG8_WAIT_V(8); PG8_WAIT_L(0); PG8_BAR; PG8_MMA(0, 0, At, B0); PG8_MMA(0, 1, At, B1); PG8_BAR; PG8_SCHED;
;             PG8_LDA(At, 0, 1); PG8_STAGE(PG8_SB(0, 0), b2, voffB); PG8_STAGE(PG8_SB(0, 1), b2 + hstepB, voffB); PG8_STAGE(PG8_SA(0, 0), a2, voffA);
;             PG8_WAIT_V(8); PG8_WAIT_L(0); PG8_BAR; PG8_MMA(1, 0, At, B0); PG8_MMA(1, 1, At, B1); PG8_BAR; PG8_SCHED;
.LBB0_774:
	s_add_u32 s16, s24, 0x100
	s_addc_u32 s17, s25, 0
	s_add_i32 s61, 0, 0x10000
	s_cmp_eq_u32 s60, 2
	s_cselect_b32 s29, s19, s17
	s_cselect_b32 s28, s18, s16
	s_cselect_b32 s27, s21, s45
	s_cselect_b32 s26, s20, s44
	s_add_i32 s62, 0, 0x14000
	v_add_u32_e32 v154, s61, v139
	v_add_u32_e32 v158, s62, v139
	ds_read_b128 v[142:145], v154
	ds_read_b128 v[146:149], v154 offset:1024
	ds_read_b128 v[150:153], v154 offset:2048
	ds_read_b128 v[154:157], v154 offset:3072
	ds_read_b128 v[162:165], v158
	ds_read_b128 v[166:169], v158 offset:1024
	ds_read_b128 v[170:173], v158 offset:2048
	ds_read_b128 v[174:177], v158 offset:3072
	v_lshl_add_u64 v[158:159], s[24:25], 0, v[134:135]
	s_add_i32 m0, s48, 0xc000
	ds_read_b128 v[178:181], v141
	ds_read_b128 v[182:185], v141 offset:1024
	ds_read_b128 v[186:189], v141 offset:2048
	ds_read_b128 v[190:193], v141 offset:3072
	ds_read_b128 v[194:197], v141 offset:4096
	ds_read_b128 v[198:201], v141 offset:5120
	ds_read_b128 v[202:205], v141 offset:6144
	ds_read_b128 v[206:209], v141 offset:7168
	global_load_lds_dwordx4 v[158:159], off
	v_lshl_add_u64 v[158:159], s[24:25], 0, v[136:137]
	s_add_i32 m0, s48, 0xe000
	s_nop 0
	global_load_lds_dwordx4 v[158:159], off
	s_waitcnt vmcnt(8)
	s_waitcnt lgkmcnt(0)
	s_barrier
	s_setprio 1
	s_waitcnt lgkmcnt(0)
	v_mfma_f32_16x16x32_bf16 v[124:127], v[142:145], v[178:181], v[124:127]
	v_mfma_f32_16x16x32_bf16 v[120:123], v[150:153], v[178:181], v[120:123]
	v_mfma_f32_16x16x32_bf16 v[116:119], v[142:145], v[186:189], v[116:119]
	v_mfma_f32_16x16x32_bf16 v[112:115], v[150:153], v[186:189], v[112:115]
	v_mfma_f32_16x16x32_bf16 v[100:103], v[142:145], v[194:197], v[100:103]
	v_mfma_f32_16x16x32_bf16 v[96:99], v[150:153], v[194:197], v[96:99]
	v_mfma_f32_16x16x32_bf16 v[84:87], v[142:145], v[202:205], v[84:87]
	v_mfma_f32_16x16x32_bf16 v[80:83], v[150:153], v[202:205], v[80:83]
	v_mfma_f32_16x16x32_bf16 v[124:127], v[146:149], v[182:185], v[124:127]
	v_mfma_f32_16x16x32_bf16 v[120:123], v[154:157], v[182:185], v[120:123]
	v_mfma_f32_16x16x32_bf16 v[116:119], v[146:149], v[190:193], v[116:119]
	v_mfma_f32_16x16x32_bf16 v[112:115], v[154:157], v[190:193], v[112:115]
	v_mfma_f32_16x16x32_bf16 v[100:103], v[146:149], v[198:201], v[100:103]
	v_mfma_f32_16x16x32_bf16 v[96:99], v[154:157], v[198:201], v[96:99]
	v_mfma_f32_16x16x32_bf16 v[84:87], v[146:149], v[206:209], v[84:87]
	v_mfma_f32_16x16x32_bf16 v[80:83], v[154:157], v[206:209], v[80:83]
	s_setprio 0
	s_setprio 1
	v_mfma_f32_16x16x32_bf16 v[108:111], v[162:165], v[178:181], v[108:111]
	v_mfma_f32_16x16x32_bf16 v[104:107], v[170:173], v[178:181], v[104:107]
	v_mfma_f32_16x16x32_bf16 v[92:95], v[162:165], v[186:189], v[92:95]
	v_mfma_f32_16x16x32_bf16 v[88:91], v[170:173], v[186:189], v[88:91]
	v_mfma_f32_16x16x32_bf16 v[76:79], v[162:165], v[194:197], v[76:79]
	v_mfma_f32_16x16x32_bf16 v[72:75], v[170:173], v[194:197], v[72:75]
	v_mfma_f32_16x16x32_bf16 v[68:71], v[162:165], v[202:205], v[68:71]
	v_mfma_f32_16x16x32_bf16 v[64:67], v[170:173], v[202:205], v[64:67]
	v_mfma_f32_16x16x32_bf16 v[108:111], v[166:169], v[182:185], v[108:111]
	v_mfma_f32_16x16x32_bf16 v[104:107], v[174:177], v[182:185], v[104:107]
	v_mfma_f32_16x16x32_bf16 v[92:95], v[166:169], v[190:193], v[92:95]
	v_mfma_f32_16x16x32_bf16 v[88:91], v[174:177], v[190:193], v[88:91]
	v_mfma_f32_16x16x32_bf16 v[76:79], v[166:169], v[198:201], v[76:79]
	v_mfma_f32_16x16x32_bf16 v[72:75], v[174:177], v[198:201], v[72:75]
	v_mfma_f32_16x16x32_bf16 v[68:71], v[166:169], v[206:209], v[68:71]
	v_mfma_f32_16x16x32_bf16 v[64:67], v[174:177], v[206:209], v[64:67]
	s_setprio 0
	s_barrier
	s_add_i32 s24, s61, s46
	v_lshl_add_u64 v[158:159], s[26:27], 0, v[160:161]
	s_mov_b32 m0, s24
	ds_read_b128 v[178:181], v141 offset:16384
	ds_read_b128 v[182:185], v141 offset:17408
	ds_read_b128 v[186:189], v141 offset:18432
	ds_read_b128 v[190:193], v141 offset:19456
	ds_read_b128 v[194:197], v141 offset:20480
	ds_read_b128 v[198:201], v141 offset:21504
	ds_read_b128 v[202:205], v141 offset:22528
	ds_read_b128 v[206:209], v141 offset:23552
	global_load_lds_dwordx4 v[158:159], off
	s_add_i32 m0, s24, 0x2000
	s_add_u32 s24, s26, 0x18000
	v_lshl_add_u64 v[210:211], s[26:27], 0, v[128:129]
	s_addc_u32 s25, s27, 0
	s_add_i32 s61, s62, s46
	global_load_lds_dwordx4 v[210:211], off
	s_mov_b32 m0, s61
	v_lshl_add_u64 v[218:219], s[28:29], 0, v[130:131]
	global_load_lds_dwordx4 v160, s[24:25]
	s_add_i32 m0, s61, 0x2000
	s_nop 0
	global_load_lds_dwordx4 v128, s[24:25]
	v_lshl_add_u64 v[212:213], s[28:29], 0, v[132:133]
	s_mov_b32 m0, s48
	s_nop 0
	global_load_lds_dwordx4 v[212:213], off
	s_mov_b32 m0, s49
	s_nop 0
	global_load_lds_dwordx4 v[218:219], off
	s_waitcnt vmcnt(8)
	s_waitcnt lgkmcnt(0)
	s_barrier
; #define PG8_STAGE(bufoff, gbase, voff) do { _Pragma("unroll") for (int _i = 0; _i < 2; ++_i) \
;         __builtin_amdgcn_global_load_lds((const unsigned*)((const char*)(gbase) + (voff)[_i]), (LAS unsigned*)(lds + (bufoff) + ldsw + _i * 8192), 16, 0, 0); } while (0)
; #define PG8_LDA(dst, b, h) do { _Pragma("unroll") for (int m = 0; m < 4; ++m) _Pragma("unroll") for (int k = 0; k < 2; ++k) dst[m][k] = *(const LAS bf16x8*)(lds + PG8_SA(b, h) + aoff + m * 2048 + k * 1024); } while (0)
; #define PG8_LDB(dst, b, h) do { _Pragma("unroll") for (int n = 0; n < 2; ++n) _Pragma("unroll") for (int k = 0; k < 2; ++k) dst[n][k] = *(const LAS bf16x8*)(lds + PG8_SB(b, h) + boff + n * 2048 + k * 1024); } while (0)
; #define PG8_MMA(ai, bj, At, Bt) do { __builtin_amdgcn_s_setprio(1); _Pragma("unroll") for (int m = 0; m < 4; ++m) _Pragma("unroll") for (int n = 0; n < 2; ++n) _Pragma("unroll") for (int k = 0; k < 2; ++k) \
;         acc[ai][bj][m][n] = __builtin_amdgcn_mfma_f32_16x16x32_bf16(Bt[n][k], At[m][k], acc[ai][bj][m][n], 0, 0, 0); __builtin_amdgcn_s_setprio(0); } while (0)
; #define PG8_WAIT_V(n) asm volatile("s_waitcnt vmcnt(" #n ")" ::: "memory")
; #define PG8_WAIT_L(n) asm volatile("s_waitcnt lgkmcnt(" #n ")" ::: "memory")
; #define PG8_BAR __builtin_amdgcn_s_barrier()
; #define PG8_SCHED __builtin_amdgcn_sched_barrier(0)
; template <class Epi, bool ALIGN_EPI = true>
; __device__ __forceinline__ void gemm_phase(LAS unsigned char* lds, const Gemm g, const StaticOrder& S, const Epi& E, int wave_k) {
;     ...
;             PG8_WAIT_V(8); PG8_WAIT_L(0); PG8_BAR; PG8_MMA(1, 0, At, B0); PG8_MMA(1, 1, At, B1); PG8_BAR; PG8_SCHED;
;             PG8_LDB(B0, 1, 0); PG8_LDB(B1, 1, 1); PG8_SCHED; PG8_LDA(At, 1, 0); PG8_STAGE(PG8_SA(0, 1), a2 + hstepA, voffA);
;             PG8_WAIT_V(8); PG8_WAIT_L(0); PG8_BAR; PG8_MMA(0, 0, At, B0); PG8_MMA(0, 1, At, B1); PG8_BAR; PG8_SCHED;
	s_setprio 1
	s_waitcnt lgkmcnt(0)
	v_mfma_f32_16x16x32_bf16 v[60:63], v[142:145], v[178:181], v[60:63]
	v_mfma_f32_16x16x32_bf16 v[56:59], v[150:153], v[178:181], v[56:59]
	v_mfma_f32_16x16x32_bf16 v[52:55], v[142:145], v[186:189], v[52:55]
	v_mfma_f32_16x16x32_bf16 v[48:51], v[150:153], v[186:189], v[48:51]
	v_mfma_f32_16x16x32_bf16 v[36:39], v[142:145], v[194:197], v[36:39]
	v_mfma_f32_16x16x32_bf16 v[32:35], v[150:153], v[194:197], v[32:35]
	v_mfma_f32_16x16x32_bf16 v[20:23], v[142:145], v[202:205], v[20:23]
	v_mfma_f32_16x16x32_bf16 v[16:19], v[150:153], v[202:205], v[16:19]
	v_mfma_f32_16x16x32_bf16 v[60:63], v[146:149], v[182:185], v[60:63]
	v_mfma_f32_16x16x32_bf16 v[56:59], v[154:157], v[182:185], v[56:59]
	v_mfma_f32_16x16x32_bf16 v[52:55], v[146:149], v[190:193], v[52:55]
	v_mfma_f32_16x16x32_bf16 v[48:51], v[154:157], v[190:193], v[48:51]
	v_mfma_f32_16x16x32_bf16 v[36:39], v[146:149], v[198:201], v[36:39]
	v_mfma_f32_16x16x32_bf16 v[32:35], v[154:157], v[198:201], v[32:35]
	v_mfma_f32_16x16x32_bf16 v[20:23], v[146:149], v[206:209], v[20:23]
	v_mfma_f32_16x16x32_bf16 v[16:19], v[154:157], v[206:209], v[16:19]
	s_setprio 0
	s_setprio 1
	v_mfma_f32_16x16x32_bf16 v[44:47], v[162:165], v[178:181], v[44:47]
	v_mfma_f32_16x16x32_bf16 v[40:43], v[170:173], v[178:181], v[40:43]
	v_mfma_f32_16x16x32_bf16 v[28:31], v[162:165], v[186:189], v[28:31]
	v_mfma_f32_16x16x32_bf16 v[24:27], v[170:173], v[186:189], v[24:27]
	v_mfma_f32_16x16x32_bf16 v[12:15], v[162:165], v[194:197], v[12:15]
	v_mfma_f32_16x16x32_bf16 v[8:11], v[170:173], v[194:197], v[8:11]
	v_mfma_f32_16x16x32_bf16 v[4:7], v[162:165], v[202:205], v[4:7]
	v_mfma_f32_16x16x32_bf16 v[0:3], v[170:173], v[202:205], v[0:3]
	v_mfma_f32_16x16x32_bf16 v[44:47], v[166:169], v[182:185], v[44:47]
	v_mfma_f32_16x16x32_bf16 v[40:43], v[174:177], v[182:185], v[40:43]
	v_mfma_f32_16x16x32_bf16 v[28:31], v[166:169], v[190:193], v[28:31]
	v_mfma_f32_16x16x32_bf16 v[24:27], v[174:177], v[190:193], v[24:27]
	v_mfma_f32_16x16x32_bf16 v[12:15], v[166:169], v[198:201], v[12:15]
	v_mfma_f32_16x16x32_bf16 v[8:11], v[174:177], v[198:201], v[8:11]
	v_mfma_f32_16x16x32_bf16 v[4:7], v[166:169], v[206:209], v[4:7]
	v_mfma_f32_16x16x32_bf16 v[0:3], v[174:177], v[206:209], v[0:3]
	s_setprio 0
	s_barrier
	s_add_i32 s61, 0, 0x18000
	s_add_i32 s62, 0, 0x1c000
	v_add_u32_e32 v154, s61, v139
	v_add_u32_e32 v174, s62, v139
	ds_read_b128 v[142:145], v154
	ds_read_b128 v[146:149], v154 offset:1024
	ds_read_b128 v[150:153], v154 offset:2048
	ds_read_b128 v[154:157], v154 offset:3072
	ds_read_b128 v[162:165], v174
	ds_read_b128 v[166:169], v174 offset:1024
	ds_read_b128 v[170:173], v174 offset:2048
	ds_read_b128 v[174:177], v174 offset:3072
	s_add_u32 s24, s28, 0x28000
	s_addc_u32 s25, s29, 0
	s_mov_b32 m0, s50
	ds_read_b128 v[178:181], v141 offset:32768
	ds_read_b128 v[182:185], v141 offset:33792
	ds_read_b128 v[186:189], v141 offset:34816
	ds_read_b128 v[190:193], v141 offset:35840
	ds_read_b128 v[194:197], v141 offset:36864
	ds_read_b128 v[198:201], v141 offset:37888
	ds_read_b128 v[202:205], v141 offset:38912
	ds_read_b128 v[206:209], v141 offset:39936
	global_load_lds_dwordx4 v132, s[24:25]
	s_mov_b32 m0, s51
	s_nop 0
	global_load_lds_dwordx4 v130, s[24:25]
	s_waitcnt vmcnt(8)
	s_waitcnt lgkmcnt(0)
	s_barrier
	s_setprio 1
	s_waitcnt lgkmcnt(0)
	v_mfma_f32_16x16x32_bf16 v[124:127], v[142:145], v[178:181], v[124:127]
	v_mfma_f32_16x16x32_bf16 v[120:123], v[150:153], v[178:181], v[120:123]
	v_mfma_f32_16x16x32_bf16 v[116:119], v[142:145], v[186:189], v[116:119]
	v_mfma_f32_16x16x32_bf16 v[112:115], v[150:153], v[186:189], v[112:115]
	v_mfma_f32_16x16x32_bf16 v[100:103], v[142:145], v[194:197], v[100:103]
	v_mfma_f32_16x16x32_bf16 v[96:99], v[150:153], v[194:197], v[96:99]
	v_mfma_f32_16x16x32_bf16 v[84:87], v[142:145], v[202:205], v[84:87]
	v_mfma_f32_16x16x32_bf16 v[80:83], v[150:153], v[202:205], v[80:83]
	v_mfma_f32_16x16x32_bf16 v[124:127], v[146:149], v[182:185], v[124:127]
	v_mfma_f32_16x16x32_bf16 v[120:123], v[154:157], v[182:185], v[120:123]
	v_mfma_f32_16x16x32_bf16 v[116:119], v[146:149], v[190:193], v[116:119]
	v_mfma_f32_16x16x32_bf16 v[112:115], v[154:157], v[190:193], v[112:115]
	v_mfma_f32_16x16x32_bf16 v[100:103], v[146:149], v[198:201], v[100:103]
	v_mfma_f32_16x16x32_bf16 v[96:99], v[154:157], v[198:201], v[96:99]
	v_mfma_f32_16x16x32_bf16 v[84:87], v[146:149], v[206:209], v[84:87]
	v_mfma_f32_16x16x32_bf16 v[80:83], v[154:157], v[206:209], v[80:83]
	s_setprio 0
	s_setprio 1
	v_mfma_f32_16x16x32_bf16 v[108:111], v[162:165], v[178:181], v[108:111]
	v_mfma_f32_16x16x32_bf16 v[104:107], v[170:173], v[178:181], v[104:107]
	v_mfma_f32_16x16x32_bf16 v[92:95], v[162:165], v[186:189], v[92:95]
	v_mfma_f32_16x16x32_bf16 v[88:91], v[170:173], v[186:189], v[88:91]
	v_mfma_f32_16x16x32_bf16 v[76:79], v[162:165], v[194:197], v[76:79]
	v_mfma_f32_16x16x32_bf16 v[72:75], v[170:173], v[194:197], v[72:75]
	v_mfma_f32_16x16x32_bf16 v[68:71], v[162:165], v[202:205], v[68:71]
	v_mfma_f32_16x16x32_bf16 v[64:67], v[170:173], v[202:205], v[64:67]
	v_mfma_f32_16x16x32_bf16 v[108:111], v[166:169], v[182:185], v[108:111]
	v_mfma_f32_16x16x32_bf16 v[104:107], v[174:177], v[182:185], v[104:107]
	v_mfma_f32_16x16x32_bf16 v[92:95], v[166:169], v[190:193], v[92:95]
	v_mfma_f32_16x16x32_bf16 v[88:91], v[174:177], v[190:193], v[88:91]
	v_mfma_f32_16x16x32_bf16 v[76:79], v[166:169], v[198:201], v[76:79]
	v_mfma_f32_16x16x32_bf16 v[72:75], v[174:177], v[198:201], v[72:75]
	v_mfma_f32_16x16x32_bf16 v[68:71], v[166:169], v[206:209], v[68:71]
	v_mfma_f32_16x16x32_bf16 v[64:67], v[174:177], v[206:209], v[64:67]
	s_setprio 0
	s_barrier
; #define PG8_STAGE(bufoff, gbase, voff) do { _Pragma("unroll") for (int _i = 0; _i < 2; ++_i) \
;         __builtin_amdgcn_global_load_lds((const unsigned*)((const char*)(gbase) + (voff)[_i]), (LAS unsigned*)(lds + (bufoff) + ldsw + _i * 8192), 16, 0, 0); } while (0)
; #define PG8_LDA(dst, b, h) do { _Pragma("unroll") for (int m = 0; m < 4; ++m) _Pragma("unroll") for (int k = 0; k < 2; ++k) dst[m][k] = *(const LAS bf16x8*)(lds + PG8_SA(b, h) + aoff + m * 2048 + k * 1024); } while (0)
; #define PG8_MMA(ai, bj, At, Bt) do { __builtin_amdgcn_s_setprio(1); _Pragma("unroll") for (int m = 0; m < 4; ++m) _Pragma("unroll") for (int n = 0; n < 2; ++n) _Pragma("unroll") for (int k = 0; k < 2; ++k) \
;         acc[ai][bj][m][n] = __builtin_amdgcn_mfma_f32_16x16x32_bf16(Bt[n][k], At[m][k], acc[ai][bj][m][n], 0, 0, 0); __builtin_amdgcn_s_setprio(0); } while (0)
; #define PG8_WAIT_V(n) asm volatile("s_waitcnt vmcnt(" #n ")" ::: "memory")
; #define PG8_WAIT_L(n) asm volatile("s_waitcnt lgkmcnt(" #n ")" ::: "memory")
; #define PG8_BAR __builtin_amdgcn_s_barrier()
; #define PG8_SCHED __builtin_amdgcn_sched_barrier(0)
; template <class Epi, bool ALIGN_EPI = true>
; __device__ __forceinline__ void gemm_phase(LAS unsigned char* lds, const Gemm g, const StaticOrder& S, const Epi& E, int wave_k) {
;     ...
;             PG8_LDA(At, 1, 1); PG8_STAGE(PG8_SB(1, 0), b3, voffB); PG8_STAGE(PG8_SB(1, 1), b3 + hstepB, voffB); PG8_STAGE(PG8_SA(1, 0), a3, voffA);
;             PG8_WAIT_V(8); PG8_WAIT_L(0); PG8_BAR; PG8_MMA(1, 0, At, B0); PG8_MMA(1, 1, At, B1); PG8_BAR; PG8_SCHED;
;         }
;         if constexpr (ALIGN_EPI) { if (wr == 0) PG8_BAR; }
	s_add_i32 s24, s61, s46
	v_lshl_add_u64 v[158:159], v[158:159], 0, s[22:23]
	s_mov_b32 m0, s24
	ds_read_b128 v[178:181], v141 offset:49152
	ds_read_b128 v[182:185], v141 offset:50176
	ds_read_b128 v[186:189], v141 offset:51200
	ds_read_b128 v[190:193], v141 offset:52224
	ds_read_b128 v[194:197], v141 offset:53248
	ds_read_b128 v[198:201], v141 offset:54272
	ds_read_b128 v[202:205], v141 offset:55296
	ds_read_b128 v[206:209], v141 offset:56320
	global_load_lds_dwordx4 v[158:159], off
	s_add_i32 m0, s24, 0x2000
	s_add_u32 s24, s26, 0x18080
	v_lshl_add_u64 v[158:159], v[210:211], 0, s[22:23]
	s_addc_u32 s25, s27, 0
	s_add_i32 s26, s62, s46
	global_load_lds_dwordx4 v[158:159], off
	s_mov_b32 m0, s26
	s_nop 0
	global_load_lds_dwordx4 v160, s[24:25]
	s_add_i32 m0, s26, 0x2000
	s_nop 0
	global_load_lds_dwordx4 v128, s[24:25]
	v_lshl_add_u64 v[158:159], v[212:213], 0, s[22:23]
	s_mov_b32 m0, s52
	s_nop 0
	global_load_lds_dwordx4 v[158:159], off
	v_lshl_add_u64 v[158:159], v[218:219], 0, s[22:23]
	s_mov_b32 m0, s53
	s_nop 0
	global_load_lds_dwordx4 v[158:159], off
	s_waitcnt vmcnt(8)
	s_waitcnt lgkmcnt(0)
	s_barrier
	s_setprio 1
	s_waitcnt lgkmcnt(0)
	v_mfma_f32_16x16x32_bf16 v[60:63], v[142:145], v[178:181], v[60:63]
	v_mfma_f32_16x16x32_bf16 v[56:59], v[150:153], v[178:181], v[56:59]
	v_mfma_f32_16x16x32_bf16 v[52:55], v[142:145], v[186:189], v[52:55]
	v_mfma_f32_16x16x32_bf16 v[48:51], v[150:153], v[186:189], v[48:51]
	v_mfma_f32_16x16x32_bf16 v[36:39], v[142:145], v[194:197], v[36:39]
	v_mfma_f32_16x16x32_bf16 v[32:35], v[150:153], v[194:197], v[32:35]
	v_mfma_f32_16x16x32_bf16 v[20:23], v[142:145], v[202:205], v[20:23]
	v_mfma_f32_16x16x32_bf16 v[16:19], v[150:153], v[202:205], v[16:19]
	v_mfma_f32_16x16x32_bf16 v[60:63], v[146:149], v[182:185], v[60:63]
	v_mfma_f32_16x16x32_bf16 v[56:59], v[154:157], v[182:185], v[56:59]
	v_mfma_f32_16x16x32_bf16 v[52:55], v[146:149], v[190:193], v[52:55]
	v_mfma_f32_16x16x32_bf16 v[48:51], v[154:157], v[190:193], v[48:51]
	v_mfma_f32_16x16x32_bf16 v[36:39], v[146:149], v[198:201], v[36:39]
	v_mfma_f32_16x16x32_bf16 v[32:35], v[154:157], v[198:201], v[32:35]
	v_mfma_f32_16x16x32_bf16 v[20:23], v[146:149], v[206:209], v[20:23]
	v_mfma_f32_16x16x32_bf16 v[16:19], v[154:157], v[206:209], v[16:19]
	s_setprio 0
	s_setprio 1
	v_mfma_f32_16x16x32_bf16 v[44:47], v[162:165], v[178:181], v[44:47]
	v_mfma_f32_16x16x32_bf16 v[40:43], v[170:173], v[178:181], v[40:43]
	v_mfma_f32_16x16x32_bf16 v[28:31], v[162:165], v[186:189], v[28:31]
	v_mfma_f32_16x16x32_bf16 v[24:27], v[170:173], v[186:189], v[24:27]
	v_mfma_f32_16x16x32_bf16 v[12:15], v[162:165], v[194:197], v[12:15]
	v_mfma_f32_16x16x32_bf16 v[8:11], v[170:173], v[194:197], v[8:11]
	v_mfma_f32_16x16x32_bf16 v[4:7], v[162:165], v[202:205], v[4:7]
	v_mfma_f32_16x16x32_bf16 v[0:3], v[170:173], v[202:205], v[0:3]
	v_mfma_f32_16x16x32_bf16 v[44:47], v[166:169], v[182:185], v[44:47]
	v_mfma_f32_16x16x32_bf16 v[40:43], v[174:177], v[182:185], v[40:43]
	v_mfma_f32_16x16x32_bf16 v[28:31], v[166:169], v[190:193], v[28:31]
	v_mfma_f32_16x16x32_bf16 v[24:27], v[174:177], v[190:193], v[24:27]
	v_mfma_f32_16x16x32_bf16 v[12:15], v[166:169], v[198:201], v[12:15]
	v_mfma_f32_16x16x32_bf16 v[8:11], v[174:177], v[198:201], v[8:11]
	v_mfma_f32_16x16x32_bf16 v[4:7], v[166:169], v[206:209], v[4:7]
	v_mfma_f32_16x16x32_bf16 v[0:3], v[174:177], v[206:209], v[0:3]
	s_setprio 0
	s_barrier
	s_add_i32 s60, s60, 2
	s_add_u32 s44, s44, 0x100
	s_addc_u32 s45, s45, 0
	s_cmp_gt_u32 s60, 3
	s_mov_b64 s[24:25], s[16:17]
	s_cbranch_scc0 .LBB0_774
	s_and_b64 vcc, exec, s[14:15]
	s_cbranch_vccz .LBB0_777
	s_barrier

; #define PG8_STAGE(bufoff, gbase, voff) do { _Pragma("unroll") for (int _i = 0; _i < 2; ++_i) \
;         __builtin_amdgcn_global_load_lds((const unsigned*)((const char*)(gbase) + (voff)[_i]), (LAS unsigned*)(lds + (bufoff) + ldsw + _i * 8192), 16, 0, 0); } while (0)
; #define PG8_LDA(dst, b, h) do { _Pragma("unroll") for (int m = 0; m < 4; ++m) _Pragma("unroll") for (int k = 0; k < 2; ++k) dst[m][k] = *(const LAS bf16x8*)(lds + PG8_SA(b, h) + aoff + m * 2048 + k * 1024); } while (0)
; #define PG8_LDB(dst, b, h) do { _Pragma("unroll") for (int n = 0; n < 2; ++n) _Pragma("unroll") for (int k = 0; k < 2; ++k) dst[n][k] = *(const LAS bf16x8*)(lds + PG8_SB(b, h) + boff + n * 2048 + k * 1024); } while (0)
; #define PG8_MMA(ai, bj, At, Bt) do { __builtin_amdgcn_s_setprio(1); _Pragma("unroll") for (int m = 0; m < 4; ++m) _Pragma("unroll") for (int n = 0; n < 2; ++n) _Pragma("unroll") for (int k = 0; k < 2; ++k) \
;         acc[ai][bj][m][n] = __builtin_amdgcn_mfma_f32_16x16x32_bf16(Bt[n][k], At[m][k], acc[ai][bj][m][n], 0, 0, 0); __builtin_amdgcn_s_setprio(0); } while (0)
; #define PG8_WAIT_V(n) asm volatile("s_waitcnt vmcnt(" #n ")" ::: "memory")
; #define PG8_WAIT_L(n) asm volatile("s_waitcnt lgkmcnt(" #n ")" ::: "memory")
; #define PG8_BAR __builtin_amdgcn_s_barrier()
; #define PG8_SCHED __builtin_amdgcn_sched_barrier(0)
; template <class Epi, bool ALIGN_EPI = true>
; __device__ __forceinline__ void gemm_phase(LAS unsigned char* lds, const Gemm g, const StaticOrder& S, const Epi& E, int wave_k) {
;     ...
;         for (int t = 0; t < nt; t += 2) {
;             const bool last = (t == nt - 2);
;             const char* a1 = cA + (size_t)(t + 1) * kstep;
;             const char* a2 = last ? nA : cA + (size_t)(t + 2) * kstep; const char* b2 = last ? nB : cB + (size_t)(t + 2) * kstep;
;             const char* a3 = a2 + kstep; const char* b3 = b2 + kstep;
;             PG8_LDB(B0, 0, 0); PG8_LDB(B1, 0, 1); PG8_SCHED; PG8_LDA(At, 0, 0); PG8_STAGE(PG8_SA(1, 1), a1 + hstepA, voffA);
;             PG8_WAIT_V(8); PG8_WAIT_L(0); PG8_BAR; PG8_MMA(0, 0, At, B0); PG8_MMA(0, 1, At, B1); PG8_BAR; PG8_SCHED;
;             PG8_LDA(At, 0, 1); PG8_STAGE(PG8_SB(0, 0), b2, voffB); PG8_STAGE(PG8_SB(0, 1), b2 + hstepB, voffB); PG8_STAGE(PG8_SA(0, 0), a2, voffA);
;             PG8_WAIT_V(8); PG8_WAIT_L(0); PG8_BAR; PG8_MMA(1, 0, At, B0); PG8_MMA(1, 1, At, B1); PG8_BAR; PG8_SCHED;
.LBB0_800:
	s_add_u32 s25, s20, s24
	s_addc_u32 s46, s21, 0
	s_add_u32 s28, s25, 0x100
	s_addc_u32 s29, s46, 0
	s_and_b64 s[26:27], s[16:17], exec
	s_cselect_b32 s27, s37, s29
	s_cselect_b32 s26, s36, s28
	s_add_u32 s24, s18, s24
	s_addc_u32 s28, s19, 0
	s_add_u32 s24, s24, 0x100
	s_addc_u32 s28, s28, 0
	s_add_i32 s79, 0, 0x10000
	s_and_b64 s[16:17], s[16:17], exec
	s_cselect_b32 s29, s35, s28
	s_cselect_b32 s28, s70, s24
	s_add_i32 s17, 0, 0x14000
	s_add_u32 s48, s25, 0x28080
	s_addc_u32 s49, s46, 0
	s_add_i32 s78, s79, s57
	s_add_i32 m0, s58, 0xc000
	s_add_i32 s81, s58, 0xe000
	s_add_i32 s75, s78, 0x2000
	s_add_u32 s46, s28, 0x10000
	v_add_u32_e32 v150, s79, v135
	v_add_u32_e32 v158, s17, v135
	s_addc_u32 s47, s29, 0
	s_add_i32 s77, s17, s57
	ds_read_b128 v[138:141], v150
	ds_read_b128 v[142:145], v150 offset:1024
	ds_read_b128 v[146:149], v150 offset:2048
	ds_read_b128 v[150:153], v150 offset:3072
	ds_read_b128 v[154:157], v158
	ds_read_b128 v[162:165], v158 offset:1024
	ds_read_b128 v[166:169], v158 offset:2048
	ds_read_b128 v[170:173], v158 offset:3072
	s_add_i32 s76, s77, 0x2000
	s_add_i32 s74, 0, 0x18000
	s_add_i32 s73, 0, 0x1c000
	s_add_u32 s24, s26, 0x28000
	s_addc_u32 s25, s27, 0
	s_add_i32 s72, s74, s57
	s_add_i32 s71, s72, 0x2000
	s_add_u32 s16, s28, 0x10080
	s_addc_u32 s17, s29, 0
	s_add_i32 s80, s73, s57
	s_add_i32 s79, s80, 0x2000
	ds_read_b128 v[174:177], v137
	ds_read_b128 v[178:181], v137 offset:1024
	ds_read_b128 v[182:185], v137 offset:2048
	ds_read_b128 v[186:189], v137 offset:3072
	ds_read_b128 v[190:193], v137 offset:4096
	ds_read_b128 v[194:197], v137 offset:5120
	ds_read_b128 v[198:201], v137 offset:6144
	ds_read_b128 v[202:205], v137 offset:7168
	global_load_lds_dwordx4 v128, s[48:49]
	s_mov_b32 m0, s81
	s_nop 0
	global_load_lds_dwordx4 v130, s[48:49]
	s_waitcnt vmcnt(8)
	s_waitcnt lgkmcnt(0)
	s_barrier
	s_setprio 1
	s_waitcnt lgkmcnt(0)
	v_mfma_f32_16x16x32_bf16 v[124:127], v[138:141], v[174:177], v[124:127]
	v_mfma_f32_16x16x32_bf16 v[120:123], v[146:149], v[174:177], v[120:123]
	v_mfma_f32_16x16x32_bf16 v[116:119], v[138:141], v[182:185], v[116:119]
	v_mfma_f32_16x16x32_bf16 v[112:115], v[146:149], v[182:185], v[112:115]
	v_mfma_f32_16x16x32_bf16 v[100:103], v[138:141], v[190:193], v[100:103]
	v_mfma_f32_16x16x32_bf16 v[96:99], v[146:149], v[190:193], v[96:99]
	v_mfma_f32_16x16x32_bf16 v[84:87], v[138:141], v[198:201], v[84:87]
	v_mfma_f32_16x16x32_bf16 v[80:83], v[146:149], v[198:201], v[80:83]
	v_mfma_f32_16x16x32_bf16 v[124:127], v[142:145], v[178:181], v[124:127]
	v_mfma_f32_16x16x32_bf16 v[120:123], v[150:153], v[178:181], v[120:123]
	v_mfma_f32_16x16x32_bf16 v[116:119], v[142:145], v[186:189], v[116:119]
	v_mfma_f32_16x16x32_bf16 v[112:115], v[150:153], v[186:189], v[112:115]
	v_mfma_f32_16x16x32_bf16 v[100:103], v[142:145], v[194:197], v[100:103]
	v_mfma_f32_16x16x32_bf16 v[96:99], v[150:153], v[194:197], v[96:99]
	v_mfma_f32_16x16x32_bf16 v[84:87], v[142:145], v[202:205], v[84:87]
	v_mfma_f32_16x16x32_bf16 v[80:83], v[150:153], v[202:205], v[80:83]
	s_setprio 0
	s_setprio 1
	v_mfma_f32_16x16x32_bf16 v[108:111], v[154:157], v[174:177], v[108:111]
	v_mfma_f32_16x16x32_bf16 v[104:107], v[166:169], v[174:177], v[104:107]
	v_mfma_f32_16x16x32_bf16 v[92:95], v[154:157], v[182:185], v[92:95]
	v_mfma_f32_16x16x32_bf16 v[88:91], v[166:169], v[182:185], v[88:91]
	v_mfma_f32_16x16x32_bf16 v[76:79], v[154:157], v[190:193], v[76:79]
	v_mfma_f32_16x16x32_bf16 v[72:75], v[166:169], v[190:193], v[72:75]
	v_mfma_f32_16x16x32_bf16 v[68:71], v[154:157], v[198:201], v[68:71]
	v_mfma_f32_16x16x32_bf16 v[64:67], v[166:169], v[198:201], v[64:67]
	v_mfma_f32_16x16x32_bf16 v[108:111], v[162:165], v[178:181], v[108:111]
	v_mfma_f32_16x16x32_bf16 v[104:107], v[170:173], v[178:181], v[104:107]
	v_mfma_f32_16x16x32_bf16 v[92:95], v[162:165], v[186:189], v[92:95]
	v_mfma_f32_16x16x32_bf16 v[88:91], v[170:173], v[186:189], v[88:91]
	v_mfma_f32_16x16x32_bf16 v[76:79], v[162:165], v[194:197], v[76:79]
	v_mfma_f32_16x16x32_bf16 v[72:75], v[170:173], v[194:197], v[72:75]
	v_mfma_f32_16x16x32_bf16 v[68:71], v[162:165], v[202:205], v[68:71]
	v_mfma_f32_16x16x32_bf16 v[64:67], v[170:173], v[202:205], v[64:67]
	s_setprio 0
	s_barrier
	s_mov_b32 m0, s78
	v_lshl_add_u64 v[158:159], s[28:29], 0, v[160:161]
	ds_read_b128 v[174:177], v137 offset:16384
	ds_read_b128 v[178:181], v137 offset:17408
	ds_read_b128 v[182:185], v137 offset:18432
	ds_read_b128 v[186:189], v137 offset:19456
	ds_read_b128 v[190:193], v137 offset:20480
	ds_read_b128 v[194:197], v137 offset:21504
	ds_read_b128 v[198:201], v137 offset:22528
	ds_read_b128 v[202:205], v137 offset:23552
	global_load_lds_dwordx4 v[158:159], off
	v_lshl_add_u64 v[206:207], s[28:29], 0, v[132:133]
	s_mov_b32 m0, s75
	global_load_lds_dwordx4 v[206:207], off
	s_mov_b32 m0, s77
	v_lshl_add_u64 v[210:211], s[26:27], 0, v[130:131]
	global_load_lds_dwordx4 v160, s[46:47]
	s_mov_b32 m0, s76
	s_nop 0
	global_load_lds_dwordx4 v132, s[46:47]
	v_lshl_add_u64 v[208:209], s[26:27], 0, v[128:129]
	s_mov_b32 m0, s58
	s_nop 0
	global_load_lds_dwordx4 v[208:209], off
	s_mov_b32 m0, s59
	s_nop 0
	global_load_lds_dwordx4 v[210:211], off
	s_waitcnt vmcnt(8)
	s_waitcnt lgkmcnt(0)
	s_barrier
; #define PG8_STAGE(bufoff, gbase, voff) do { _Pragma("unroll") for (int _i = 0; _i < 2; ++_i) \
;         __builtin_amdgcn_global_load_lds((const unsigned*)((const char*)(gbase) + (voff)[_i]), (LAS unsigned*)(lds + (bufoff) + ldsw + _i * 8192), 16, 0, 0); } while (0)
; #define PG8_LDA(dst, b, h) do { _Pragma("unroll") for (int m = 0; m < 4; ++m) _Pragma("unroll") for (int k = 0; k < 2; ++k) dst[m][k] = *(const LAS bf16x8*)(lds + PG8_SA(b, h) + aoff + m * 2048 + k * 1024); } while (0)
; #define PG8_LDB(dst, b, h) do { _Pragma("unroll") for (int n = 0; n < 2; ++n) _Pragma("unroll") for (int k = 0; k < 2; ++k) dst[n][k] = *(const LAS bf16x8*)(lds + PG8_SB(b, h) + boff + n * 2048 + k * 1024); } while (0)
; #define PG8_MMA(ai, bj, At, Bt) do { __builtin_amdgcn_s_setprio(1); _Pragma("unroll") for (int m = 0; m < 4; ++m) _Pragma("unroll") for (int n = 0; n < 2; ++n) _Pragma("unroll") for (int k = 0; k < 2; ++k) \
;         acc[ai][bj][m][n] = __builtin_amdgcn_mfma_f32_16x16x32_bf16(Bt[n][k], At[m][k], acc[ai][bj][m][n], 0, 0, 0); __builtin_amdgcn_s_setprio(0); } while (0)
; #define PG8_WAIT_V(n) asm volatile("s_waitcnt vmcnt(" #n ")" ::: "memory")
; #define PG8_WAIT_L(n) asm volatile("s_waitcnt lgkmcnt(" #n ")" ::: "memory")
; #define PG8_BAR __builtin_amdgcn_s_barrier()
; #define PG8_SCHED __builtin_amdgcn_sched_barrier(0)
; template <class Epi, bool ALIGN_EPI = true>
; __device__ __forceinline__ void gemm_phase(LAS unsigned char* lds, const Gemm g, const StaticOrder& S, const Epi& E, int wave_k) {
;     ...
;             PG8_WAIT_V(8); PG8_WAIT_L(0); PG8_BAR; PG8_MMA(1, 0, At, B0); PG8_MMA(1, 1, At, B1); PG8_BAR; PG8_SCHED;
;             PG8_LDB(B0, 1, 0); PG8_LDB(B1, 1, 1); PG8_SCHED; PG8_LDA(At, 1, 0); PG8_STAGE(PG8_SA(0, 1), a2 + hstepA, voffA);
;             PG8_WAIT_V(8); PG8_WAIT_L(0); PG8_BAR; PG8_MMA(0, 0, At, B0); PG8_MMA(0, 1, At, B1); PG8_BAR; PG8_SCHED;
	s_setprio 1
	s_waitcnt lgkmcnt(0)
	v_mfma_f32_16x16x32_bf16 v[60:63], v[138:141], v[174:177], v[60:63]
	v_mfma_f32_16x16x32_bf16 v[56:59], v[146:149], v[174:177], v[56:59]
	v_mfma_f32_16x16x32_bf16 v[52:55], v[138:141], v[182:185], v[52:55]
	v_mfma_f32_16x16x32_bf16 v[48:51], v[146:149], v[182:185], v[48:51]
	v_mfma_f32_16x16x32_bf16 v[36:39], v[138:141], v[190:193], v[36:39]
	v_mfma_f32_16x16x32_bf16 v[32:35], v[146:149], v[190:193], v[32:35]
	v_mfma_f32_16x16x32_bf16 v[20:23], v[138:141], v[198:201], v[20:23]
	v_mfma_f32_16x16x32_bf16 v[16:19], v[146:149], v[198:201], v[16:19]
	v_mfma_f32_16x16x32_bf16 v[60:63], v[142:145], v[178:181], v[60:63]
	v_mfma_f32_16x16x32_bf16 v[56:59], v[150:153], v[178:181], v[56:59]
	v_mfma_f32_16x16x32_bf16 v[52:55], v[142:145], v[186:189], v[52:55]
	v_mfma_f32_16x16x32_bf16 v[48:51], v[150:153], v[186:189], v[48:51]
	v_mfma_f32_16x16x32_bf16 v[36:39], v[142:145], v[194:197], v[36:39]
	v_mfma_f32_16x16x32_bf16 v[32:35], v[150:153], v[194:197], v[32:35]
	v_mfma_f32_16x16x32_bf16 v[20:23], v[142:145], v[202:205], v[20:23]
	v_mfma_f32_16x16x32_bf16 v[16:19], v[150:153], v[202:205], v[16:19]
	s_setprio 0
	s_setprio 1
	v_mfma_f32_16x16x32_bf16 v[44:47], v[154:157], v[174:177], v[44:47]
	v_mfma_f32_16x16x32_bf16 v[40:43], v[166:169], v[174:177], v[40:43]
	v_mfma_f32_16x16x32_bf16 v[28:31], v[154:157], v[182:185], v[28:31]
	v_mfma_f32_16x16x32_bf16 v[24:27], v[166:169], v[182:185], v[24:27]
	v_mfma_f32_16x16x32_bf16 v[12:15], v[154:157], v[190:193], v[12:15]
	v_mfma_f32_16x16x32_bf16 v[8:11], v[166:169], v[190:193], v[8:11]
	v_mfma_f32_16x16x32_bf16 v[4:7], v[154:157], v[198:201], v[4:7]
	v_mfma_f32_16x16x32_bf16 v[0:3], v[166:169], v[198:201], v[0:3]
	v_mfma_f32_16x16x32_bf16 v[44:47], v[162:165], v[178:181], v[44:47]
	v_mfma_f32_16x16x32_bf16 v[40:43], v[170:173], v[178:181], v[40:43]
	v_mfma_f32_16x16x32_bf16 v[28:31], v[162:165], v[186:189], v[28:31]
	v_mfma_f32_16x16x32_bf16 v[24:27], v[170:173], v[186:189], v[24:27]
	v_mfma_f32_16x16x32_bf16 v[12:15], v[162:165], v[194:197], v[12:15]
	v_mfma_f32_16x16x32_bf16 v[8:11], v[170:173], v[194:197], v[8:11]
	v_mfma_f32_16x16x32_bf16 v[4:7], v[162:165], v[202:205], v[4:7]
	v_mfma_f32_16x16x32_bf16 v[0:3], v[170:173], v[202:205], v[0:3]
	s_setprio 0
	s_barrier
	v_add_u32_e32 v150, s74, v135
	v_add_u32_e32 v170, s73, v135
	ds_read_b128 v[138:141], v150
	ds_read_b128 v[142:145], v150 offset:1024
	ds_read_b128 v[146:149], v150 offset:2048
	ds_read_b128 v[150:153], v150 offset:3072
	ds_read_b128 v[154:157], v170
	ds_read_b128 v[162:165], v170 offset:1024
	ds_read_b128 v[166:169], v170 offset:2048
	ds_read_b128 v[170:173], v170 offset:3072
	s_mov_b32 m0, s60
	ds_read_b128 v[174:177], v137 offset:32768
	ds_read_b128 v[178:181], v137 offset:33792
	ds_read_b128 v[182:185], v137 offset:34816
	ds_read_b128 v[186:189], v137 offset:35840
	ds_read_b128 v[190:193], v137 offset:36864
	ds_read_b128 v[194:197], v137 offset:37888
	ds_read_b128 v[198:201], v137 offset:38912
	ds_read_b128 v[202:205], v137 offset:39936
	global_load_lds_dwordx4 v128, s[24:25]
	s_mov_b32 m0, s61
	s_nop 0
	global_load_lds_dwordx4 v130, s[24:25]
	s_waitcnt vmcnt(8)
	s_waitcnt lgkmcnt(0)
	s_barrier
	s_setprio 1
	s_waitcnt lgkmcnt(0)
	v_mfma_f32_16x16x32_bf16 v[124:127], v[138:141], v[174:177], v[124:127]
	v_mfma_f32_16x16x32_bf16 v[120:123], v[146:149], v[174:177], v[120:123]
	v_mfma_f32_16x16x32_bf16 v[116:119], v[138:141], v[182:185], v[116:119]
	v_mfma_f32_16x16x32_bf16 v[112:115], v[146:149], v[182:185], v[112:115]
	v_mfma_f32_16x16x32_bf16 v[100:103], v[138:141], v[190:193], v[100:103]
	v_mfma_f32_16x16x32_bf16 v[96:99], v[146:149], v[190:193], v[96:99]
	v_mfma_f32_16x16x32_bf16 v[84:87], v[138:141], v[198:201], v[84:87]
	v_mfma_f32_16x16x32_bf16 v[80:83], v[146:149], v[198:201], v[80:83]
	v_mfma_f32_16x16x32_bf16 v[124:127], v[142:145], v[178:181], v[124:127]
	v_mfma_f32_16x16x32_bf16 v[120:123], v[150:153], v[178:181], v[120:123]
	v_mfma_f32_16x16x32_bf16 v[116:119], v[142:145], v[186:189], v[116:119]
	v_mfma_f32_16x16x32_bf16 v[112:115], v[150:153], v[186:189], v[112:115]
	v_mfma_f32_16x16x32_bf16 v[100:103], v[142:145], v[194:197], v[100:103]
	v_mfma_f32_16x16x32_bf16 v[96:99], v[150:153], v[194:197], v[96:99]
	v_mfma_f32_16x16x32_bf16 v[84:87], v[142:145], v[202:205], v[84:87]
	v_mfma_f32_16x16x32_bf16 v[80:83], v[150:153], v[202:205], v[80:83]
	s_setprio 0
	s_setprio 1
	v_mfma_f32_16x16x32_bf16 v[108:111], v[154:157], v[174:177], v[108:111]
	v_mfma_f32_16x16x32_bf16 v[104:107], v[166:169], v[174:177], v[104:107]
	v_mfma_f32_16x16x32_bf16 v[92:95], v[154:157], v[182:185], v[92:95]
	v_mfma_f32_16x16x32_bf16 v[88:91], v[166:169], v[182:185], v[88:91]
	v_mfma_f32_16x16x32_bf16 v[76:79], v[154:157], v[190:193], v[76:79]
	v_mfma_f32_16x16x32_bf16 v[72:75], v[166:169], v[190:193], v[72:75]
	v_mfma_f32_16x16x32_bf16 v[68:71], v[154:157], v[198:201], v[68:71]
	v_mfma_f32_16x16x32_bf16 v[64:67], v[166:169], v[198:201], v[64:67]
	v_mfma_f32_16x16x32_bf16 v[108:111], v[162:165], v[178:181], v[108:111]
	v_mfma_f32_16x16x32_bf16 v[104:107], v[170:173], v[178:181], v[104:107]
	v_mfma_f32_16x16x32_bf16 v[92:95], v[162:165], v[186:189], v[92:95]
	v_mfma_f32_16x16x32_bf16 v[88:91], v[170:173], v[186:189], v[88:91]
	v_mfma_f32_16x16x32_bf16 v[76:79], v[162:165], v[194:197], v[76:79]
	v_mfma_f32_16x16x32_bf16 v[72:75], v[170:173], v[194:197], v[72:75]
	v_mfma_f32_16x16x32_bf16 v[68:71], v[162:165], v[202:205], v[68:71]
	v_mfma_f32_16x16x32_bf16 v[64:67], v[170:173], v[202:205], v[64:67]
	s_setprio 0
	s_barrier
; #define PG8_STAGE(bufoff, gbase, voff) do { _Pragma("unroll") for (int _i = 0; _i < 2; ++_i) \
;         __builtin_amdgcn_global_load_lds((const unsigned*)((const char*)(gbase) + (voff)[_i]), (LAS unsigned*)(lds + (bufoff) + ldsw + _i * 8192), 16, 0, 0); } while (0)
; #define PG8_LDA(dst, b, h) do { _Pragma("unroll") for (int m = 0; m < 4; ++m) _Pragma("unroll") for (int k = 0; k < 2; ++k) dst[m][k] = *(const LAS bf16x8*)(lds + PG8_SA(b, h) + aoff + m * 2048 + k * 1024); } while (0)
; #define PG8_MMA(ai, bj, At, Bt) do { __builtin_amdgcn_s_setprio(1); _Pragma("unroll") for (int m = 0; m < 4; ++m) _Pragma("unroll") for (int n = 0; n < 2; ++n) _Pragma("unroll") for (int k = 0; k < 2; ++k) \
;         acc[ai][bj][m][n] = __builtin_amdgcn_mfma_f32_16x16x32_bf16(Bt[n][k], At[m][k], acc[ai][bj][m][n], 0, 0, 0); __builtin_amdgcn_s_setprio(0); } while (0)
; #define PG8_WAIT_V(n) asm volatile("s_waitcnt vmcnt(" #n ")" ::: "memory")
; #define PG8_WAIT_L(n) asm volatile("s_waitcnt lgkmcnt(" #n ")" ::: "memory")
; #define PG8_BAR __builtin_amdgcn_s_barrier()
; #define PG8_SCHED __builtin_amdgcn_sched_barrier(0)
; template <class Epi, bool ALIGN_EPI = true>
; __device__ __forceinline__ void gemm_phase(LAS unsigned char* lds, const Gemm g, const StaticOrder& S, const Epi& E, int wave_k) {
;     ...
;             PG8_LDA(At, 1, 1); PG8_STAGE(PG8_SB(1, 0), b3, voffB); PG8_STAGE(PG8_SB(1, 1), b3 + hstepB, voffB); PG8_STAGE(PG8_SA(1, 0), a3, voffA);
;             PG8_WAIT_V(8); PG8_WAIT_L(0); PG8_BAR; PG8_MMA(1, 0, At, B0); PG8_MMA(1, 1, At, B1); PG8_BAR; PG8_SCHED;
;         }
;         if constexpr (ALIGN_EPI) { if (wr == 0) PG8_BAR; }
	s_mov_b32 m0, s72
	v_lshl_add_u64 v[158:159], v[158:159], 0, s[22:23]
	ds_read_b128 v[174:177], v137 offset:49152
	ds_read_b128 v[178:181], v137 offset:50176
	ds_read_b128 v[182:185], v137 offset:51200
	ds_read_b128 v[186:189], v137 offset:52224
	ds_read_b128 v[190:193], v137 offset:53248
	ds_read_b128 v[194:197], v137 offset:54272
	ds_read_b128 v[198:201], v137 offset:55296
	ds_read_b128 v[202:205], v137 offset:56320
	global_load_lds_dwordx4 v[158:159], off
	v_lshl_add_u64 v[158:159], v[206:207], 0, s[22:23]
	s_mov_b32 m0, s71
	s_nop 0
	global_load_lds_dwordx4 v[158:159], off
	s_mov_b32 m0, s80
	s_nop 0
	global_load_lds_dwordx4 v160, s[16:17]
	s_mov_b32 m0, s79
	s_nop 0
	global_load_lds_dwordx4 v132, s[16:17]
	v_lshl_add_u64 v[158:159], v[208:209], 0, s[22:23]
	s_mov_b32 m0, s62
	s_nop 0
	global_load_lds_dwordx4 v[158:159], off
	v_lshl_add_u64 v[158:159], v[210:211], 0, s[22:23]
	s_mov_b32 m0, s63
	s_nop 0
	global_load_lds_dwordx4 v[158:159], off
	s_waitcnt vmcnt(8)
	s_waitcnt lgkmcnt(0)
	s_barrier
	s_setprio 1
	s_waitcnt lgkmcnt(0)
	v_mfma_f32_16x16x32_bf16 v[60:63], v[138:141], v[174:177], v[60:63]
	v_mfma_f32_16x16x32_bf16 v[56:59], v[146:149], v[174:177], v[56:59]
	v_mfma_f32_16x16x32_bf16 v[52:55], v[138:141], v[182:185], v[52:55]
	v_mfma_f32_16x16x32_bf16 v[48:51], v[146:149], v[182:185], v[48:51]
	v_mfma_f32_16x16x32_bf16 v[36:39], v[138:141], v[190:193], v[36:39]
	v_mfma_f32_16x16x32_bf16 v[32:35], v[146:149], v[190:193], v[32:35]
	v_mfma_f32_16x16x32_bf16 v[20:23], v[138:141], v[198:201], v[20:23]
	v_mfma_f32_16x16x32_bf16 v[16:19], v[146:149], v[198:201], v[16:19]
	v_mfma_f32_16x16x32_bf16 v[60:63], v[142:145], v[178:181], v[60:63]
	v_mfma_f32_16x16x32_bf16 v[56:59], v[150:153], v[178:181], v[56:59]
	v_mfma_f32_16x16x32_bf16 v[52:55], v[142:145], v[186:189], v[52:55]
	v_mfma_f32_16x16x32_bf16 v[48:51], v[150:153], v[186:189], v[48:51]
	v_mfma_f32_16x16x32_bf16 v[36:39], v[142:145], v[194:197], v[36:39]
	v_mfma_f32_16x16x32_bf16 v[32:35], v[150:153], v[194:197], v[32:35]
	v_mfma_f32_16x16x32_bf16 v[20:23], v[142:145], v[202:205], v[20:23]
	v_mfma_f32_16x16x32_bf16 v[16:19], v[150:153], v[202:205], v[16:19]
	s_setprio 0
	s_setprio 1
	v_mfma_f32_16x16x32_bf16 v[44:47], v[154:157], v[174:177], v[44:47]
	v_mfma_f32_16x16x32_bf16 v[40:43], v[166:169], v[174:177], v[40:43]
	v_mfma_f32_16x16x32_bf16 v[28:31], v[154:157], v[182:185], v[28:31]
	v_mfma_f32_16x16x32_bf16 v[24:27], v[166:169], v[182:185], v[24:27]
	v_mfma_f32_16x16x32_bf16 v[12:15], v[154:157], v[190:193], v[12:15]
	v_mfma_f32_16x16x32_bf16 v[8:11], v[166:169], v[190:193], v[8:11]
	v_mfma_f32_16x16x32_bf16 v[4:7], v[154:157], v[198:201], v[4:7]
	v_mfma_f32_16x16x32_bf16 v[0:3], v[166:169], v[198:201], v[0:3]
	v_mfma_f32_16x16x32_bf16 v[44:47], v[162:165], v[178:181], v[44:47]
	v_mfma_f32_16x16x32_bf16 v[40:43], v[170:173], v[178:181], v[40:43]
	v_mfma_f32_16x16x32_bf16 v[28:31], v[162:165], v[186:189], v[28:31]
	v_mfma_f32_16x16x32_bf16 v[24:27], v[170:173], v[186:189], v[24:27]
	v_mfma_f32_16x16x32_bf16 v[12:15], v[162:165], v[194:197], v[12:15]
	v_mfma_f32_16x16x32_bf16 v[8:11], v[170:173], v[194:197], v[8:11]
	v_mfma_f32_16x16x32_bf16 v[4:7], v[162:165], v[202:205], v[4:7]
	v_mfma_f32_16x16x32_bf16 v[0:3], v[170:173], v[202:205], v[0:3]
	s_setprio 0
	s_barrier
	s_movk_i32 s24, 0x100
	s_andn2_b64 vcc, exec, s[44:45]
	s_mov_b64 s[16:17], -1
	s_mov_b64 s[44:45], 0
	s_cbranch_vccz .LBB0_800
	s_and_b64 vcc, exec, s[14:15]
	s_cbranch_vccz .LBB0_803
	s_barrier

; #define PG8_STAGE(bufoff, gbase, voff) do { _Pragma("unroll") for (int _i = 0; _i < 2; ++_i) \
;         __builtin_amdgcn_global_load_lds((const unsigned*)((const char*)(gbase) + (voff)[_i]), (LAS unsigned*)(lds + (bufoff) + ldsw + _i * 8192), 16, 0, 0); } while (0)
; #define PG8_LDA(dst, b, h) do { _Pragma("unroll") for (int m = 0; m < 4; ++m) _Pragma("unroll") for (int k = 0; k < 2; ++k) dst[m][k] = *(const LAS bf16x8*)(lds + PG8_SA(b, h) + aoff + m * 2048 + k * 1024); } while (0)
; #define PG8_LDB(dst, b, h) do { _Pragma("unroll") for (int n = 0; n < 2; ++n) _Pragma("unroll") for (int k = 0; k < 2; ++k) dst[n][k] = *(const LAS bf16x8*)(lds + PG8_SB(b, h) + boff + n * 2048 + k * 1024); } while (0)
; #define PG8_MMA(ai, bj, At, Bt) do { __builtin_amdgcn_s_setprio(1); _Pragma("unroll") for (int m = 0; m < 4; ++m) _Pragma("unroll") for (int n = 0; n < 2; ++n) _Pragma("unroll") for (int k = 0; k < 2; ++k) \
;         acc[ai][bj][m][n] = __builtin_amdgcn_mfma_f32_16x16x32_bf16(Bt[n][k], At[m][k], acc[ai][bj][m][n], 0, 0, 0); __builtin_amdgcn_s_setprio(0); } while (0)
; #define PG8_WAIT_V(n) asm volatile("s_waitcnt vmcnt(" #n ")" ::: "memory")
; #define PG8_WAIT_L(n) asm volatile("s_waitcnt lgkmcnt(" #n ")" ::: "memory")
; #define PG8_BAR __builtin_amdgcn_s_barrier()
; #define PG8_SCHED __builtin_amdgcn_sched_barrier(0)
; template <class Epi, bool ALIGN_EPI = true>
; __device__ __forceinline__ void gemm_phase(LAS unsigned char* lds, const Gemm g, const StaticOrder& S, const Epi& E, int wave_k) {
;     ...
;         for (int t = 0; t < nt; t += 2) {
;             const bool last = (t == nt - 2);
;             const char* a1 = cA + (size_t)(t + 1) * kstep;
;             const char* a2 = last ? nA : cA + (size_t)(t + 2) * kstep; const char* b2 = last ? nB : cB + (size_t)(t + 2) * kstep;
;             const char* a3 = a2 + kstep; const char* b3 = b2 + kstep;
;             PG8_LDB(B0, 0, 0); PG8_LDB(B1, 0, 1); PG8_SCHED; PG8_LDA(At, 0, 0); PG8_STAGE(PG8_SA(1, 1), a1 + hstepA, voffA);
;             PG8_WAIT_V(8); PG8_WAIT_L(0); PG8_BAR; PG8_MMA(0, 0, At, B0); PG8_MMA(0, 1, At, B1); PG8_BAR; PG8_SCHED;
;             PG8_LDA(At, 0, 1); PG8_STAGE(PG8_SB(0, 0), b2, voffB); PG8_STAGE(PG8_SB(0, 1), b2 + hstepB, voffB); PG8_STAGE(PG8_SA(0, 0), a2, voffA);
;             PG8_WAIT_V(8); PG8_WAIT_L(0); PG8_BAR; PG8_MMA(1, 0, At, B0); PG8_MMA(1, 1, At, B1); PG8_BAR; PG8_SCHED;
.LBB0_886:
	s_add_u32 s16, s46, 0xfffe0080
	s_addc_u32 s17, s47, -1
	s_add_i32 s65, 0, 0x10000
	s_cmp_eq_u32 s64, 4
	s_cselect_b32 s25, s26, s17
	s_cselect_b32 s24, s27, s16
	s_cselect_b32 s17, s21, s63
	s_cselect_b32 s16, s35, s62
	s_add_i32 s68, 0, 0x14000
	v_add_u32_e32 v154, s65, v143
	v_add_u32_e32 v158, s68, v143
	ds_read_b128 v[138:141], v154
	ds_read_b128 v[146:149], v154 offset:1024
	ds_read_b128 v[150:153], v154 offset:2048
	ds_read_b128 v[154:157], v154 offset:3072
	ds_read_b128 v[162:165], v158
	ds_read_b128 v[166:169], v158 offset:1024
	ds_read_b128 v[170:173], v158 offset:2048
	ds_read_b128 v[174:177], v158 offset:3072
	s_add_i32 m0, s45, 0xc000
	ds_read_b128 v[178:181], v145
	ds_read_b128 v[182:185], v145 offset:1024
	ds_read_b128 v[186:189], v145 offset:2048
	ds_read_b128 v[190:193], v145 offset:3072
	ds_read_b128 v[194:197], v145 offset:4096
	ds_read_b128 v[198:201], v145 offset:5120
	ds_read_b128 v[202:205], v145 offset:6144
	ds_read_b128 v[206:209], v145 offset:7168
	global_load_lds_dwordx4 v134, s[46:47]
	s_add_i32 m0, s45, 0xe000
	s_nop 0
	global_load_lds_dwordx4 v136, s[46:47]
	s_waitcnt vmcnt(8)
	s_waitcnt lgkmcnt(0)
	s_barrier
	s_setprio 1
	s_waitcnt lgkmcnt(0)
	v_mfma_f32_16x16x32_bf16 v[124:127], v[138:141], v[178:181], v[124:127]
	v_mfma_f32_16x16x32_bf16 v[120:123], v[150:153], v[178:181], v[120:123]
	v_mfma_f32_16x16x32_bf16 v[108:111], v[138:141], v[186:189], v[108:111]
	v_mfma_f32_16x16x32_bf16 v[104:107], v[150:153], v[186:189], v[104:107]
	v_mfma_f32_16x16x32_bf16 v[92:95], v[138:141], v[194:197], v[92:95]
	v_mfma_f32_16x16x32_bf16 v[88:91], v[150:153], v[194:197], v[88:91]
	v_mfma_f32_16x16x32_bf16 v[76:79], v[138:141], v[202:205], v[76:79]
	v_mfma_f32_16x16x32_bf16 v[72:75], v[150:153], v[202:205], v[72:75]
	v_mfma_f32_16x16x32_bf16 v[124:127], v[146:149], v[182:185], v[124:127]
	v_mfma_f32_16x16x32_bf16 v[120:123], v[154:157], v[182:185], v[120:123]
	v_mfma_f32_16x16x32_bf16 v[108:111], v[146:149], v[190:193], v[108:111]
	v_mfma_f32_16x16x32_bf16 v[104:107], v[154:157], v[190:193], v[104:107]
	v_mfma_f32_16x16x32_bf16 v[92:95], v[146:149], v[198:201], v[92:95]
	v_mfma_f32_16x16x32_bf16 v[88:91], v[154:157], v[198:201], v[88:91]
	v_mfma_f32_16x16x32_bf16 v[76:79], v[146:149], v[206:209], v[76:79]
	v_mfma_f32_16x16x32_bf16 v[72:75], v[154:157], v[206:209], v[72:75]
	s_setprio 0
	s_setprio 1
	v_mfma_f32_16x16x32_bf16 v[116:119], v[162:165], v[178:181], v[116:119]
	v_mfma_f32_16x16x32_bf16 v[112:115], v[170:173], v[178:181], v[112:115]
	v_mfma_f32_16x16x32_bf16 v[100:103], v[162:165], v[186:189], v[100:103]
	v_mfma_f32_16x16x32_bf16 v[96:99], v[170:173], v[186:189], v[96:99]
	v_mfma_f32_16x16x32_bf16 v[84:87], v[162:165], v[194:197], v[84:87]
	v_mfma_f32_16x16x32_bf16 v[80:83], v[170:173], v[194:197], v[80:83]
	v_mfma_f32_16x16x32_bf16 v[68:71], v[162:165], v[202:205], v[68:71]
	v_mfma_f32_16x16x32_bf16 v[64:67], v[170:173], v[202:205], v[64:67]
	v_mfma_f32_16x16x32_bf16 v[116:119], v[166:169], v[182:185], v[116:119]
	v_mfma_f32_16x16x32_bf16 v[112:115], v[174:177], v[182:185], v[112:115]
	v_mfma_f32_16x16x32_bf16 v[100:103], v[166:169], v[190:193], v[100:103]
	v_mfma_f32_16x16x32_bf16 v[96:99], v[174:177], v[190:193], v[96:99]
	v_mfma_f32_16x16x32_bf16 v[84:87], v[166:169], v[198:201], v[84:87]
	v_mfma_f32_16x16x32_bf16 v[80:83], v[174:177], v[198:201], v[80:83]
	v_mfma_f32_16x16x32_bf16 v[68:71], v[166:169], v[206:209], v[68:71]
	v_mfma_f32_16x16x32_bf16 v[64:67], v[174:177], v[206:209], v[64:67]
	s_setprio 0
	s_barrier
	s_add_i32 s65, s65, s53
	v_lshl_add_u64 v[158:159], s[16:17], 0, v[160:161]
	s_mov_b32 m0, s65
	ds_read_b128 v[178:181], v145 offset:16384
	ds_read_b128 v[182:185], v145 offset:17408
	ds_read_b128 v[186:189], v145 offset:18432
	ds_read_b128 v[190:193], v145 offset:19456
	ds_read_b128 v[194:197], v145 offset:20480
	ds_read_b128 v[198:201], v145 offset:21504
	ds_read_b128 v[202:205], v145 offset:22528
	ds_read_b128 v[206:209], v145 offset:23552
	global_load_lds_dwordx4 v[158:159], off
	s_add_i32 m0, s65, 0x2000
	s_add_u32 s66, s16, 0x20000
	v_lshl_add_u64 v[210:211], s[16:17], 0, v[132:133]
	s_addc_u32 s67, s17, 0
	s_add_i32 s65, s68, s53
	global_load_lds_dwordx4 v[210:211], off
	s_mov_b32 m0, s65
	v_lshl_add_u64 v[218:219], s[24:25], 0, v[130:131]
	global_load_lds_dwordx4 v160, s[66:67]
	s_add_i32 m0, s65, 0x2000
	s_nop 0
	global_load_lds_dwordx4 v132, s[66:67]
	v_lshl_add_u64 v[212:213], s[24:25], 0, v[128:129]
	s_mov_b32 m0, s45
	s_nop 0
	global_load_lds_dwordx4 v[212:213], off
	s_mov_b32 m0, s54
	s_nop 0
	global_load_lds_dwordx4 v[218:219], off
	s_waitcnt vmcnt(8)
	s_waitcnt lgkmcnt(0)
	s_barrier
; #define PG8_STAGE(bufoff, gbase, voff) do { _Pragma("unroll") for (int _i = 0; _i < 2; ++_i) \
;         __builtin_amdgcn_global_load_lds((const unsigned*)((const char*)(gbase) + (voff)[_i]), (LAS unsigned*)(lds + (bufoff) + ldsw + _i * 8192), 16, 0, 0); } while (0)
; #define PG8_LDA(dst, b, h) do { _Pragma("unroll") for (int m = 0; m < 4; ++m) _Pragma("unroll") for (int k = 0; k < 2; ++k) dst[m][k] = *(const LAS bf16x8*)(lds + PG8_SA(b, h) + aoff + m * 2048 + k * 1024); } while (0)
; #define PG8_LDB(dst, b, h) do { _Pragma("unroll") for (int n = 0; n < 2; ++n) _Pragma("unroll") for (int k = 0; k < 2; ++k) dst[n][k] = *(const LAS bf16x8*)(lds + PG8_SB(b, h) + boff + n * 2048 + k * 1024); } while (0)
; #define PG8_MMA(ai, bj, At, Bt) do { __builtin_amdgcn_s_setprio(1); _Pragma("unroll") for (int m = 0; m < 4; ++m) _Pragma("unroll") for (int n = 0; n < 2; ++n) _Pragma("unroll") for (int k = 0; k < 2; ++k) \
;         acc[ai][bj][m][n] = __builtin_amdgcn_mfma_f32_16x16x32_bf16(Bt[n][k], At[m][k], acc[ai][bj][m][n], 0, 0, 0); __builtin_amdgcn_s_setprio(0); } while (0)
; #define PG8_WAIT_V(n) asm volatile("s_waitcnt vmcnt(" #n ")" ::: "memory")
; #define PG8_WAIT_L(n) asm volatile("s_waitcnt lgkmcnt(" #n ")" ::: "memory")
; #define PG8_BAR __builtin_amdgcn_s_barrier()
; #define PG8_SCHED __builtin_amdgcn_sched_barrier(0)
; template <class Epi, bool ALIGN_EPI = true>
; __device__ __forceinline__ void gemm_phase(LAS unsigned char* lds, const Gemm g, const StaticOrder& S, const Epi& E, int wave_k) {
;     ...
;             PG8_WAIT_V(8); PG8_WAIT_L(0); PG8_BAR; PG8_MMA(1, 0, At, B0); PG8_MMA(1, 1, At, B1); PG8_BAR; PG8_SCHED;
;             PG8_LDB(B0, 1, 0); PG8_LDB(B1, 1, 1); PG8_SCHED; PG8_LDA(At, 1, 0); PG8_STAGE(PG8_SA(0, 1), a2 + hstepA, voffA);
;             PG8_WAIT_V(8); PG8_WAIT_L(0); PG8_BAR; PG8_MMA(0, 0, At, B0); PG8_MMA(0, 1, At, B1); PG8_BAR; PG8_SCHED;
	s_setprio 1
	s_waitcnt lgkmcnt(0)
	v_mfma_f32_16x16x32_bf16 v[60:63], v[138:141], v[178:181], v[60:63]
	v_mfma_f32_16x16x32_bf16 v[56:59], v[150:153], v[178:181], v[56:59]
	v_mfma_f32_16x16x32_bf16 v[44:47], v[138:141], v[186:189], v[44:47]
	v_mfma_f32_16x16x32_bf16 v[40:43], v[150:153], v[186:189], v[40:43]
	v_mfma_f32_16x16x32_bf16 v[28:31], v[138:141], v[194:197], v[28:31]
	v_mfma_f32_16x16x32_bf16 v[24:27], v[150:153], v[194:197], v[24:27]
	v_mfma_f32_16x16x32_bf16 v[12:15], v[138:141], v[202:205], v[12:15]
	v_mfma_f32_16x16x32_bf16 v[8:11], v[150:153], v[202:205], v[8:11]
	v_mfma_f32_16x16x32_bf16 v[60:63], v[146:149], v[182:185], v[60:63]
	v_mfma_f32_16x16x32_bf16 v[56:59], v[154:157], v[182:185], v[56:59]
	v_mfma_f32_16x16x32_bf16 v[44:47], v[146:149], v[190:193], v[44:47]
	v_mfma_f32_16x16x32_bf16 v[40:43], v[154:157], v[190:193], v[40:43]
	v_mfma_f32_16x16x32_bf16 v[28:31], v[146:149], v[198:201], v[28:31]
	v_mfma_f32_16x16x32_bf16 v[24:27], v[154:157], v[198:201], v[24:27]
	v_mfma_f32_16x16x32_bf16 v[12:15], v[146:149], v[206:209], v[12:15]
	v_mfma_f32_16x16x32_bf16 v[8:11], v[154:157], v[206:209], v[8:11]
	s_setprio 0
	s_setprio 1
	v_mfma_f32_16x16x32_bf16 v[52:55], v[162:165], v[178:181], v[52:55]
	v_mfma_f32_16x16x32_bf16 v[48:51], v[170:173], v[178:181], v[48:51]
	v_mfma_f32_16x16x32_bf16 v[36:39], v[162:165], v[186:189], v[36:39]
	v_mfma_f32_16x16x32_bf16 v[32:35], v[170:173], v[186:189], v[32:35]
	v_mfma_f32_16x16x32_bf16 v[20:23], v[162:165], v[194:197], v[20:23]
	v_mfma_f32_16x16x32_bf16 v[16:19], v[170:173], v[194:197], v[16:19]
	v_mfma_f32_16x16x32_bf16 v[4:7], v[162:165], v[202:205], v[4:7]
	v_mfma_f32_16x16x32_bf16 v[0:3], v[170:173], v[202:205], v[0:3]
	v_mfma_f32_16x16x32_bf16 v[52:55], v[166:169], v[182:185], v[52:55]
	v_mfma_f32_16x16x32_bf16 v[48:51], v[174:177], v[182:185], v[48:51]
	v_mfma_f32_16x16x32_bf16 v[36:39], v[166:169], v[190:193], v[36:39]
	v_mfma_f32_16x16x32_bf16 v[32:35], v[174:177], v[190:193], v[32:35]
	v_mfma_f32_16x16x32_bf16 v[20:23], v[166:169], v[198:201], v[20:23]
	v_mfma_f32_16x16x32_bf16 v[16:19], v[174:177], v[198:201], v[16:19]
	v_mfma_f32_16x16x32_bf16 v[4:7], v[166:169], v[206:209], v[4:7]
	v_mfma_f32_16x16x32_bf16 v[0:3], v[174:177], v[206:209], v[0:3]
	s_setprio 0
	s_barrier
	s_add_i32 s65, 0, 0x18000
	s_add_i32 s66, 0, 0x1c000
	v_add_u32_e32 v154, s65, v143
	v_add_u32_e32 v174, s66, v143
	ds_read_b128 v[138:141], v154
	ds_read_b128 v[146:149], v154 offset:1024
	ds_read_b128 v[150:153], v154 offset:2048
	ds_read_b128 v[154:157], v154 offset:3072
	ds_read_b128 v[162:165], v174
	ds_read_b128 v[166:169], v174 offset:1024
	ds_read_b128 v[170:173], v174 offset:2048
	ds_read_b128 v[174:177], v174 offset:3072
	s_add_u32 s24, s24, 0x20000
	s_addc_u32 s25, s25, 0
	s_mov_b32 m0, s55
	ds_read_b128 v[178:181], v145 offset:32768
	ds_read_b128 v[182:185], v145 offset:33792
	ds_read_b128 v[186:189], v145 offset:34816
	ds_read_b128 v[190:193], v145 offset:35840
	ds_read_b128 v[194:197], v145 offset:36864
	ds_read_b128 v[198:201], v145 offset:37888
	ds_read_b128 v[202:205], v145 offset:38912
	ds_read_b128 v[206:209], v145 offset:39936
	global_load_lds_dwordx4 v128, s[24:25]
	s_mov_b32 m0, s56
	s_nop 0
	global_load_lds_dwordx4 v130, s[24:25]
	s_waitcnt vmcnt(8)
	s_waitcnt lgkmcnt(0)
	s_barrier
	s_setprio 1
	s_waitcnt lgkmcnt(0)
	v_mfma_f32_16x16x32_bf16 v[124:127], v[138:141], v[178:181], v[124:127]
	v_mfma_f32_16x16x32_bf16 v[120:123], v[150:153], v[178:181], v[120:123]
	v_mfma_f32_16x16x32_bf16 v[108:111], v[138:141], v[186:189], v[108:111]
	v_mfma_f32_16x16x32_bf16 v[104:107], v[150:153], v[186:189], v[104:107]
	v_mfma_f32_16x16x32_bf16 v[92:95], v[138:141], v[194:197], v[92:95]
	v_mfma_f32_16x16x32_bf16 v[88:91], v[150:153], v[194:197], v[88:91]
	v_mfma_f32_16x16x32_bf16 v[76:79], v[138:141], v[202:205], v[76:79]
	v_mfma_f32_16x16x32_bf16 v[72:75], v[150:153], v[202:205], v[72:75]
	v_mfma_f32_16x16x32_bf16 v[124:127], v[146:149], v[182:185], v[124:127]
	v_mfma_f32_16x16x32_bf16 v[120:123], v[154:157], v[182:185], v[120:123]
	v_mfma_f32_16x16x32_bf16 v[108:111], v[146:149], v[190:193], v[108:111]
	v_mfma_f32_16x16x32_bf16 v[104:107], v[154:157], v[190:193], v[104:107]
	v_mfma_f32_16x16x32_bf16 v[92:95], v[146:149], v[198:201], v[92:95]
	v_mfma_f32_16x16x32_bf16 v[88:91], v[154:157], v[198:201], v[88:91]
	v_mfma_f32_16x16x32_bf16 v[76:79], v[146:149], v[206:209], v[76:79]
	v_mfma_f32_16x16x32_bf16 v[72:75], v[154:157], v[206:209], v[72:75]
	s_setprio 0
	s_setprio 1
	v_mfma_f32_16x16x32_bf16 v[116:119], v[162:165], v[178:181], v[116:119]
	v_mfma_f32_16x16x32_bf16 v[112:115], v[170:173], v[178:181], v[112:115]
	v_mfma_f32_16x16x32_bf16 v[100:103], v[162:165], v[186:189], v[100:103]
	v_mfma_f32_16x16x32_bf16 v[96:99], v[170:173], v[186:189], v[96:99]
	v_mfma_f32_16x16x32_bf16 v[84:87], v[162:165], v[194:197], v[84:87]
	v_mfma_f32_16x16x32_bf16 v[80:83], v[170:173], v[194:197], v[80:83]
	v_mfma_f32_16x16x32_bf16 v[68:71], v[162:165], v[202:205], v[68:71]
	v_mfma_f32_16x16x32_bf16 v[64:67], v[170:173], v[202:205], v[64:67]
	v_mfma_f32_16x16x32_bf16 v[116:119], v[166:169], v[182:185], v[116:119]
	v_mfma_f32_16x16x32_bf16 v[112:115], v[174:177], v[182:185], v[112:115]
	v_mfma_f32_16x16x32_bf16 v[100:103], v[166:169], v[190:193], v[100:103]
	v_mfma_f32_16x16x32_bf16 v[96:99], v[174:177], v[190:193], v[96:99]
	v_mfma_f32_16x16x32_bf16 v[84:87], v[166:169], v[198:201], v[84:87]
	v_mfma_f32_16x16x32_bf16 v[80:83], v[174:177], v[198:201], v[80:83]
	v_mfma_f32_16x16x32_bf16 v[68:71], v[166:169], v[206:209], v[68:71]
	v_mfma_f32_16x16x32_bf16 v[64:67], v[174:177], v[206:209], v[64:67]
	s_setprio 0
	s_barrier
; #define PG8_STAGE(bufoff, gbase, voff) do { _Pragma("unroll") for (int _i = 0; _i < 2; ++_i) \
;         __builtin_amdgcn_global_load_lds((const unsigned*)((const char*)(gbase) + (voff)[_i]), (LAS unsigned*)(lds + (bufoff) + ldsw + _i * 8192), 16, 0, 0); } while (0)
; #define PG8_LDA(dst, b, h) do { _Pragma("unroll") for (int m = 0; m < 4; ++m) _Pragma("unroll") for (int k = 0; k < 2; ++k) dst[m][k] = *(const LAS bf16x8*)(lds + PG8_SA(b, h) + aoff + m * 2048 + k * 1024); } while (0)
; #define PG8_MMA(ai, bj, At, Bt) do { __builtin_amdgcn_s_setprio(1); _Pragma("unroll") for (int m = 0; m < 4; ++m) _Pragma("unroll") for (int n = 0; n < 2; ++n) _Pragma("unroll") for (int k = 0; k < 2; ++k) \
;         acc[ai][bj][m][n] = __builtin_amdgcn_mfma_f32_16x16x32_bf16(Bt[n][k], At[m][k], acc[ai][bj][m][n], 0, 0, 0); __builtin_amdgcn_s_setprio(0); } while (0)
; #define PG8_WAIT_V(n) asm volatile("s_waitcnt vmcnt(" #n ")" ::: "memory")
; #define PG8_WAIT_L(n) asm volatile("s_waitcnt lgkmcnt(" #n ")" ::: "memory")
; #define PG8_BAR __builtin_amdgcn_s_barrier()
; #define PG8_SCHED __builtin_amdgcn_sched_barrier(0)
; template <class Epi, bool ALIGN_EPI = true>
; __device__ __forceinline__ void gemm_phase(LAS unsigned char* lds, const Gemm g, const StaticOrder& S, const Epi& E, int wave_k) {
;     ...
;             PG8_LDA(At, 1, 1); PG8_STAGE(PG8_SB(1, 0), b3, voffB); PG8_STAGE(PG8_SB(1, 1), b3 + hstepB, voffB); PG8_STAGE(PG8_SA(1, 0), a3, voffA);
;             PG8_WAIT_V(8); PG8_WAIT_L(0); PG8_BAR; PG8_MMA(1, 0, At, B0); PG8_MMA(1, 1, At, B1); PG8_BAR; PG8_SCHED;
;         }
;         if constexpr (ALIGN_EPI) { if (wr == 0) PG8_BAR; }
	s_add_i32 s24, s65, s53
	v_lshl_add_u64 v[158:159], v[158:159], 0, s[22:23]
	s_mov_b32 m0, s24
	ds_read_b128 v[178:181], v145 offset:49152
	ds_read_b128 v[182:185], v145 offset:50176
	ds_read_b128 v[186:189], v145 offset:51200
	ds_read_b128 v[190:193], v145 offset:52224
	ds_read_b128 v[194:197], v145 offset:53248
	ds_read_b128 v[198:201], v145 offset:54272
	ds_read_b128 v[202:205], v145 offset:55296
	ds_read_b128 v[206:209], v145 offset:56320
	global_load_lds_dwordx4 v[158:159], off
	s_add_i32 m0, s24, 0x2000
	s_add_u32 s16, s16, 0x20080
	v_lshl_add_u64 v[158:159], v[210:211], 0, s[22:23]
	s_addc_u32 s17, s17, 0
	s_add_i32 s24, s66, s53
	global_load_lds_dwordx4 v[158:159], off
	s_mov_b32 m0, s24
	s_nop 0
	global_load_lds_dwordx4 v160, s[16:17]
	s_add_i32 m0, s24, 0x2000
	s_nop 0
	global_load_lds_dwordx4 v132, s[16:17]
	v_lshl_add_u64 v[158:159], v[212:213], 0, s[22:23]
	s_mov_b32 m0, s57
	s_nop 0
	global_load_lds_dwordx4 v[158:159], off
	v_lshl_add_u64 v[158:159], v[218:219], 0, s[22:23]
	s_mov_b32 m0, s58
	s_nop 0
	global_load_lds_dwordx4 v[158:159], off
	s_waitcnt vmcnt(8)
	s_waitcnt lgkmcnt(0)
	s_barrier
	s_setprio 1
	s_waitcnt lgkmcnt(0)
	v_mfma_f32_16x16x32_bf16 v[60:63], v[138:141], v[178:181], v[60:63]
	v_mfma_f32_16x16x32_bf16 v[56:59], v[150:153], v[178:181], v[56:59]
	v_mfma_f32_16x16x32_bf16 v[44:47], v[138:141], v[186:189], v[44:47]
	v_mfma_f32_16x16x32_bf16 v[40:43], v[150:153], v[186:189], v[40:43]
	v_mfma_f32_16x16x32_bf16 v[28:31], v[138:141], v[194:197], v[28:31]
	v_mfma_f32_16x16x32_bf16 v[24:27], v[150:153], v[194:197], v[24:27]
	v_mfma_f32_16x16x32_bf16 v[12:15], v[138:141], v[202:205], v[12:15]
	v_mfma_f32_16x16x32_bf16 v[8:11], v[150:153], v[202:205], v[8:11]
	v_mfma_f32_16x16x32_bf16 v[60:63], v[146:149], v[182:185], v[60:63]
	v_mfma_f32_16x16x32_bf16 v[56:59], v[154:157], v[182:185], v[56:59]
	v_mfma_f32_16x16x32_bf16 v[44:47], v[146:149], v[190:193], v[44:47]
	v_mfma_f32_16x16x32_bf16 v[40:43], v[154:157], v[190:193], v[40:43]
	v_mfma_f32_16x16x32_bf16 v[28:31], v[146:149], v[198:201], v[28:31]
	v_mfma_f32_16x16x32_bf16 v[24:27], v[154:157], v[198:201], v[24:27]
	v_mfma_f32_16x16x32_bf16 v[12:15], v[146:149], v[206:209], v[12:15]
	v_mfma_f32_16x16x32_bf16 v[8:11], v[154:157], v[206:209], v[8:11]
	s_setprio 0
	s_setprio 1
	v_mfma_f32_16x16x32_bf16 v[52:55], v[162:165], v[178:181], v[52:55]
	v_mfma_f32_16x16x32_bf16 v[48:51], v[170:173], v[178:181], v[48:51]
	v_mfma_f32_16x16x32_bf16 v[36:39], v[162:165], v[186:189], v[36:39]
	v_mfma_f32_16x16x32_bf16 v[32:35], v[170:173], v[186:189], v[32:35]
	v_mfma_f32_16x16x32_bf16 v[20:23], v[162:165], v[194:197], v[20:23]
	v_mfma_f32_16x16x32_bf16 v[16:19], v[170:173], v[194:197], v[16:19]
	v_mfma_f32_16x16x32_bf16 v[4:7], v[162:165], v[202:205], v[4:7]
	v_mfma_f32_16x16x32_bf16 v[0:3], v[170:173], v[202:205], v[0:3]
	v_mfma_f32_16x16x32_bf16 v[52:55], v[166:169], v[182:185], v[52:55]
	v_mfma_f32_16x16x32_bf16 v[48:51], v[174:177], v[182:185], v[48:51]
	v_mfma_f32_16x16x32_bf16 v[36:39], v[166:169], v[190:193], v[36:39]
	v_mfma_f32_16x16x32_bf16 v[32:35], v[174:177], v[190:193], v[32:35]
	v_mfma_f32_16x16x32_bf16 v[20:23], v[166:169], v[198:201], v[20:23]
	v_mfma_f32_16x16x32_bf16 v[16:19], v[174:177], v[198:201], v[16:19]
	v_mfma_f32_16x16x32_bf16 v[4:7], v[166:169], v[206:209], v[4:7]
	v_mfma_f32_16x16x32_bf16 v[0:3], v[174:177], v[206:209], v[0:3]
	s_setprio 0
	s_barrier
	s_add_i32 s64, s64, 2
	s_add_u32 s46, s46, 0x100
	s_addc_u32 s47, s47, 0
	s_add_u32 s62, s62, 0x100
	s_addc_u32 s63, s63, 0
	s_cmp_gt_u32 s64, 5
	s_cbranch_scc0 .LBB0_886
	s_and_b64 vcc, exec, s[18:19]
	s_cbranch_vccz .LBB0_889
	s_barrier

; #define PG8_STAGE(bufoff, gbase, voff) do { _Pragma("unroll") for (int _i = 0; _i < 2; ++_i) \
;         __builtin_amdgcn_global_load_lds((const unsigned*)((const char*)(gbase) + (voff)[_i]), (LAS unsigned*)(lds + (bufoff) + ldsw + _i * 8192), 16, 0, 0); } while (0)
; #define PG8_LDA(dst, b, h) do { _Pragma("unroll") for (int m = 0; m < 4; ++m) _Pragma("unroll") for (int k = 0; k < 2; ++k) dst[m][k] = *(const LAS bf16x8*)(lds + PG8_SA(b, h) + aoff + m * 2048 + k * 1024); } while (0)
; #define PG8_LDB(dst, b, h) do { _Pragma("unroll") for (int n = 0; n < 2; ++n) _Pragma("unroll") for (int k = 0; k < 2; ++k) dst[n][k] = *(const LAS bf16x8*)(lds + PG8_SB(b, h) + boff + n * 2048 + k * 1024); } while (0)
; #define PG8_MMA(ai, bj, At, Bt) do { __builtin_amdgcn_s_setprio(1); _Pragma("unroll") for (int m = 0; m < 4; ++m) _Pragma("unroll") for (int n = 0; n < 2; ++n) _Pragma("unroll") for (int k = 0; k < 2; ++k) \
;         acc[ai][bj][m][n] = __builtin_amdgcn_mfma_f32_16x16x32_bf16(Bt[n][k], At[m][k], acc[ai][bj][m][n], 0, 0, 0); __builtin_amdgcn_s_setprio(0); } while (0)
; #define PG8_WAIT_V(n) asm volatile("s_waitcnt vmcnt(" #n ")" ::: "memory")
; #define PG8_WAIT_L(n) asm volatile("s_waitcnt lgkmcnt(" #n ")" ::: "memory")
; #define PG8_BAR __builtin_amdgcn_s_barrier()
; #define PG8_SCHED __builtin_amdgcn_sched_barrier(0)
; template <class Epi, bool ALIGN_EPI = true>
; __device__ __forceinline__ void gemm_phase(LAS unsigned char* lds, const Gemm g, const StaticOrder& S, const Epi& E, int wave_k) {
;     ...
;         for (int t = 0; t < nt; t += 2) {
;             const bool last = (t == nt - 2);
;             const char* a1 = cA + (size_t)(t + 1) * kstep;
;             const char* a2 = last ? nA : cA + (size_t)(t + 2) * kstep; const char* b2 = last ? nB : cB + (size_t)(t + 2) * kstep;
;             const char* a3 = a2 + kstep; const char* b3 = b2 + kstep;
;             PG8_LDB(B0, 0, 0); PG8_LDB(B1, 0, 1); PG8_SCHED; PG8_LDA(At, 0, 0); PG8_STAGE(PG8_SA(1, 1), a1 + hstepA, voffA);
;             PG8_WAIT_V(8); PG8_WAIT_L(0); PG8_BAR; PG8_MMA(0, 0, At, B0); PG8_MMA(0, 1, At, B1); PG8_BAR; PG8_SCHED;
;             PG8_LDA(At, 0, 1); PG8_STAGE(PG8_SB(0, 0), b2, voffB); PG8_STAGE(PG8_SB(0, 1), b2 + hstepB, voffB); PG8_STAGE(PG8_SA(0, 0), a2, voffA);
;             PG8_WAIT_V(8); PG8_WAIT_L(0); PG8_BAR; PG8_MMA(1, 0, At, B0); PG8_MMA(1, 1, At, B1); PG8_BAR; PG8_SCHED;
.LBB0_1057:
	s_add_u32 s16, s50, 0xfffc0080
	s_addc_u32 s17, s51, -1
	s_add_i32 s71, 0, 0x10000
	s_cmp_eq_u32 s70, 12
	s_cselect_b32 s25, s26, s17
	s_cselect_b32 s24, s27, s16
	s_cselect_b32 s17, s1, s67
	s_cselect_b32 s16, s35, s66
	s_add_i32 s74, 0, 0x14000
	v_add_u32_e32 v154, s71, v143
	v_add_u32_e32 v158, s74, v143
	ds_read_b128 v[138:141], v154
	ds_read_b128 v[146:149], v154 offset:1024
	ds_read_b128 v[150:153], v154 offset:2048
	ds_read_b128 v[154:157], v154 offset:3072
	ds_read_b128 v[162:165], v158
	ds_read_b128 v[166:169], v158 offset:1024
	ds_read_b128 v[170:173], v158 offset:2048
	ds_read_b128 v[174:177], v158 offset:3072
	s_add_i32 m0, s47, 0xc000
	ds_read_b128 v[178:181], v145
	ds_read_b128 v[182:185], v145 offset:1024
	ds_read_b128 v[186:189], v145 offset:2048
	ds_read_b128 v[190:193], v145 offset:3072
	ds_read_b128 v[194:197], v145 offset:4096
	ds_read_b128 v[198:201], v145 offset:5120
	ds_read_b128 v[202:205], v145 offset:6144
	ds_read_b128 v[206:209], v145 offset:7168
	global_load_lds_dwordx4 v134, s[50:51]
	s_add_i32 m0, s47, 0xe000
	s_nop 0
	global_load_lds_dwordx4 v136, s[50:51]
	s_waitcnt vmcnt(8)
	s_waitcnt lgkmcnt(0)
	s_barrier
	s_setprio 1
	s_waitcnt lgkmcnt(0)
	v_mfma_f32_16x16x32_bf16 v[124:127], v[138:141], v[178:181], v[124:127]
	v_mfma_f32_16x16x32_bf16 v[120:123], v[150:153], v[178:181], v[120:123]
	v_mfma_f32_16x16x32_bf16 v[108:111], v[138:141], v[186:189], v[108:111]
	v_mfma_f32_16x16x32_bf16 v[104:107], v[150:153], v[186:189], v[104:107]
	v_mfma_f32_16x16x32_bf16 v[92:95], v[138:141], v[194:197], v[92:95]
	v_mfma_f32_16x16x32_bf16 v[88:91], v[150:153], v[194:197], v[88:91]
	v_mfma_f32_16x16x32_bf16 v[76:79], v[138:141], v[202:205], v[76:79]
	v_mfma_f32_16x16x32_bf16 v[72:75], v[150:153], v[202:205], v[72:75]
	v_mfma_f32_16x16x32_bf16 v[124:127], v[146:149], v[182:185], v[124:127]
	v_mfma_f32_16x16x32_bf16 v[120:123], v[154:157], v[182:185], v[120:123]
	v_mfma_f32_16x16x32_bf16 v[108:111], v[146:149], v[190:193], v[108:111]
	v_mfma_f32_16x16x32_bf16 v[104:107], v[154:157], v[190:193], v[104:107]
	v_mfma_f32_16x16x32_bf16 v[92:95], v[146:149], v[198:201], v[92:95]
	v_mfma_f32_16x16x32_bf16 v[88:91], v[154:157], v[198:201], v[88:91]
	v_mfma_f32_16x16x32_bf16 v[76:79], v[146:149], v[206:209], v[76:79]
	v_mfma_f32_16x16x32_bf16 v[72:75], v[154:157], v[206:209], v[72:75]
	s_setprio 0
	s_setprio 1
	v_mfma_f32_16x16x32_bf16 v[116:119], v[162:165], v[178:181], v[116:119]
	v_mfma_f32_16x16x32_bf16 v[112:115], v[170:173], v[178:181], v[112:115]
	v_mfma_f32_16x16x32_bf16 v[100:103], v[162:165], v[186:189], v[100:103]
	v_mfma_f32_16x16x32_bf16 v[96:99], v[170:173], v[186:189], v[96:99]
	v_mfma_f32_16x16x32_bf16 v[84:87], v[162:165], v[194:197], v[84:87]
	v_mfma_f32_16x16x32_bf16 v[80:83], v[170:173], v[194:197], v[80:83]
	v_mfma_f32_16x16x32_bf16 v[68:71], v[162:165], v[202:205], v[68:71]
	v_mfma_f32_16x16x32_bf16 v[64:67], v[170:173], v[202:205], v[64:67]
	v_mfma_f32_16x16x32_bf16 v[116:119], v[166:169], v[182:185], v[116:119]
	v_mfma_f32_16x16x32_bf16 v[112:115], v[174:177], v[182:185], v[112:115]
	v_mfma_f32_16x16x32_bf16 v[100:103], v[166:169], v[190:193], v[100:103]
	v_mfma_f32_16x16x32_bf16 v[96:99], v[174:177], v[190:193], v[96:99]
	v_mfma_f32_16x16x32_bf16 v[84:87], v[166:169], v[198:201], v[84:87]
	v_mfma_f32_16x16x32_bf16 v[80:83], v[174:177], v[198:201], v[80:83]
	v_mfma_f32_16x16x32_bf16 v[68:71], v[166:169], v[206:209], v[68:71]
	v_mfma_f32_16x16x32_bf16 v[64:67], v[174:177], v[206:209], v[64:67]
	s_setprio 0
	s_barrier
	s_add_i32 s71, s71, s58
	v_lshl_add_u64 v[158:159], s[16:17], 0, v[160:161]
	s_mov_b32 m0, s71
	ds_read_b128 v[178:181], v145 offset:16384
	ds_read_b128 v[182:185], v145 offset:17408
	ds_read_b128 v[186:189], v145 offset:18432
	ds_read_b128 v[190:193], v145 offset:19456
	ds_read_b128 v[194:197], v145 offset:20480
	ds_read_b128 v[198:201], v145 offset:21504
	ds_read_b128 v[202:205], v145 offset:22528
	ds_read_b128 v[206:209], v145 offset:23552
	global_load_lds_dwordx4 v[158:159], off
	s_add_i32 m0, s71, 0x2000
	s_add_u32 s72, s16, 0x40000
	v_lshl_add_u64 v[210:211], s[16:17], 0, v[132:133]
	s_addc_u32 s73, s17, 0
	s_add_i32 s71, s74, s58
	global_load_lds_dwordx4 v[210:211], off
	s_mov_b32 m0, s71
	v_lshl_add_u64 v[218:219], s[24:25], 0, v[130:131]
	global_load_lds_dwordx4 v160, s[72:73]
	s_add_i32 m0, s71, 0x2000
	s_nop 0
	global_load_lds_dwordx4 v132, s[72:73]
	v_lshl_add_u64 v[212:213], s[24:25], 0, v[128:129]
	s_mov_b32 m0, s47
	s_nop 0
	global_load_lds_dwordx4 v[212:213], off
	s_mov_b32 m0, s53
	s_nop 0
	global_load_lds_dwordx4 v[218:219], off
	s_waitcnt vmcnt(8)
	s_waitcnt lgkmcnt(0)
	s_barrier
; #define PG8_STAGE(bufoff, gbase, voff) do { _Pragma("unroll") for (int _i = 0; _i < 2; ++_i) \
;         __builtin_amdgcn_global_load_lds((const unsigned*)((const char*)(gbase) + (voff)[_i]), (LAS unsigned*)(lds + (bufoff) + ldsw + _i * 8192), 16, 0, 0); } while (0)
; #define PG8_LDA(dst, b, h) do { _Pragma("unroll") for (int m = 0; m < 4; ++m) _Pragma("unroll") for (int k = 0; k < 2; ++k) dst[m][k] = *(const LAS bf16x8*)(lds + PG8_SA(b, h) + aoff + m * 2048 + k * 1024); } while (0)
; #define PG8_LDB(dst, b, h) do { _Pragma("unroll") for (int n = 0; n < 2; ++n) _Pragma("unroll") for (int k = 0; k < 2; ++k) dst[n][k] = *(const LAS bf16x8*)(lds + PG8_SB(b, h) + boff + n * 2048 + k * 1024); } while (0)
; #define PG8_MMA(ai, bj, At, Bt) do { __builtin_amdgcn_s_setprio(1); _Pragma("unroll") for (int m = 0; m < 4; ++m) _Pragma("unroll") for (int n = 0; n < 2; ++n) _Pragma("unroll") for (int k = 0; k < 2; ++k) \
;         acc[ai][bj][m][n] = __builtin_amdgcn_mfma_f32_16x16x32_bf16(Bt[n][k], At[m][k], acc[ai][bj][m][n], 0, 0, 0); __builtin_amdgcn_s_setprio(0); } while (0)
; #define PG8_WAIT_V(n) asm volatile("s_waitcnt vmcnt(" #n ")" ::: "memory")
; #define PG8_WAIT_L(n) asm volatile("s_waitcnt lgkmcnt(" #n ")" ::: "memory")
; #define PG8_BAR __builtin_amdgcn_s_barrier()
; #define PG8_SCHED __builtin_amdgcn_sched_barrier(0)
; template <class Epi, bool ALIGN_EPI = true>
; __device__ __forceinline__ void gemm_phase(LAS unsigned char* lds, const Gemm g, const StaticOrder& S, const Epi& E, int wave_k) {
;     ...
;             PG8_WAIT_V(8); PG8_WAIT_L(0); PG8_BAR; PG8_MMA(1, 0, At, B0); PG8_MMA(1, 1, At, B1); PG8_BAR; PG8_SCHED;
;             PG8_LDB(B0, 1, 0); PG8_LDB(B1, 1, 1); PG8_SCHED; PG8_LDA(At, 1, 0); PG8_STAGE(PG8_SA(0, 1), a2 + hstepA, voffA);
;             PG8_WAIT_V(8); PG8_WAIT_L(0); PG8_BAR; PG8_MMA(0, 0, At, B0); PG8_MMA(0, 1, At, B1); PG8_BAR; PG8_SCHED;
	s_setprio 1
	s_waitcnt lgkmcnt(0)
	v_mfma_f32_16x16x32_bf16 v[60:63], v[138:141], v[178:181], v[60:63]
	v_mfma_f32_16x16x32_bf16 v[56:59], v[150:153], v[178:181], v[56:59]
	v_mfma_f32_16x16x32_bf16 v[44:47], v[138:141], v[186:189], v[44:47]
	v_mfma_f32_16x16x32_bf16 v[40:43], v[150:153], v[186:189], v[40:43]
	v_mfma_f32_16x16x32_bf16 v[28:31], v[138:141], v[194:197], v[28:31]
	v_mfma_f32_16x16x32_bf16 v[24:27], v[150:153], v[194:197], v[24:27]
	v_mfma_f32_16x16x32_bf16 v[12:15], v[138:141], v[202:205], v[12:15]
	v_mfma_f32_16x16x32_bf16 v[8:11], v[150:153], v[202:205], v[8:11]
	v_mfma_f32_16x16x32_bf16 v[60:63], v[146:149], v[182:185], v[60:63]
	v_mfma_f32_16x16x32_bf16 v[56:59], v[154:157], v[182:185], v[56:59]
	v_mfma_f32_16x16x32_bf16 v[44:47], v[146:149], v[190:193], v[44:47]
	v_mfma_f32_16x16x32_bf16 v[40:43], v[154:157], v[190:193], v[40:43]
	v_mfma_f32_16x16x32_bf16 v[28:31], v[146:149], v[198:201], v[28:31]
	v_mfma_f32_16x16x32_bf16 v[24:27], v[154:157], v[198:201], v[24:27]
	v_mfma_f32_16x16x32_bf16 v[12:15], v[146:149], v[206:209], v[12:15]
	v_mfma_f32_16x16x32_bf16 v[8:11], v[154:157], v[206:209], v[8:11]
	s_setprio 0
	s_setprio 1
	v_mfma_f32_16x16x32_bf16 v[52:55], v[162:165], v[178:181], v[52:55]
	v_mfma_f32_16x16x32_bf16 v[48:51], v[170:173], v[178:181], v[48:51]
	v_mfma_f32_16x16x32_bf16 v[36:39], v[162:165], v[186:189], v[36:39]
	v_mfma_f32_16x16x32_bf16 v[32:35], v[170:173], v[186:189], v[32:35]
	v_mfma_f32_16x16x32_bf16 v[20:23], v[162:165], v[194:197], v[20:23]
	v_mfma_f32_16x16x32_bf16 v[16:19], v[170:173], v[194:197], v[16:19]
	v_mfma_f32_16x16x32_bf16 v[4:7], v[162:165], v[202:205], v[4:7]
	v_mfma_f32_16x16x32_bf16 v[0:3], v[170:173], v[202:205], v[0:3]
	v_mfma_f32_16x16x32_bf16 v[52:55], v[166:169], v[182:185], v[52:55]
	v_mfma_f32_16x16x32_bf16 v[48:51], v[174:177], v[182:185], v[48:51]
	v_mfma_f32_16x16x32_bf16 v[36:39], v[166:169], v[190:193], v[36:39]
	v_mfma_f32_16x16x32_bf16 v[32:35], v[174:177], v[190:193], v[32:35]
	v_mfma_f32_16x16x32_bf16 v[20:23], v[166:169], v[198:201], v[20:23]
	v_mfma_f32_16x16x32_bf16 v[16:19], v[174:177], v[198:201], v[16:19]
	v_mfma_f32_16x16x32_bf16 v[4:7], v[166:169], v[206:209], v[4:7]
	v_mfma_f32_16x16x32_bf16 v[0:3], v[174:177], v[206:209], v[0:3]
	s_setprio 0
	s_barrier
	s_add_i32 s71, 0, 0x18000
	s_add_i32 s72, 0, 0x1c000
	v_add_u32_e32 v154, s71, v143
	v_add_u32_e32 v174, s72, v143
	ds_read_b128 v[138:141], v154
	ds_read_b128 v[146:149], v154 offset:1024
	ds_read_b128 v[150:153], v154 offset:2048
	ds_read_b128 v[154:157], v154 offset:3072
	ds_read_b128 v[162:165], v174
	ds_read_b128 v[166:169], v174 offset:1024
	ds_read_b128 v[170:173], v174 offset:2048
	ds_read_b128 v[174:177], v174 offset:3072
	s_add_u32 s24, s24, 0x40000
	s_addc_u32 s25, s25, 0
	s_mov_b32 m0, s59
	ds_read_b128 v[178:181], v145 offset:32768
	ds_read_b128 v[182:185], v145 offset:33792
	ds_read_b128 v[186:189], v145 offset:34816
	ds_read_b128 v[190:193], v145 offset:35840
	ds_read_b128 v[194:197], v145 offset:36864
	ds_read_b128 v[198:201], v145 offset:37888
	ds_read_b128 v[202:205], v145 offset:38912
	ds_read_b128 v[206:209], v145 offset:39936
	global_load_lds_dwordx4 v128, s[24:25]
	s_mov_b32 m0, s60
	s_nop 0
	global_load_lds_dwordx4 v130, s[24:25]
	s_waitcnt vmcnt(8)
	s_waitcnt lgkmcnt(0)
	s_barrier
	s_setprio 1
	s_waitcnt lgkmcnt(0)
	v_mfma_f32_16x16x32_bf16 v[124:127], v[138:141], v[178:181], v[124:127]
	v_mfma_f32_16x16x32_bf16 v[120:123], v[150:153], v[178:181], v[120:123]
	v_mfma_f32_16x16x32_bf16 v[108:111], v[138:141], v[186:189], v[108:111]
	v_mfma_f32_16x16x32_bf16 v[104:107], v[150:153], v[186:189], v[104:107]
	v_mfma_f32_16x16x32_bf16 v[92:95], v[138:141], v[194:197], v[92:95]
	v_mfma_f32_16x16x32_bf16 v[88:91], v[150:153], v[194:197], v[88:91]
	v_mfma_f32_16x16x32_bf16 v[76:79], v[138:141], v[202:205], v[76:79]
	v_mfma_f32_16x16x32_bf16 v[72:75], v[150:153], v[202:205], v[72:75]
	v_mfma_f32_16x16x32_bf16 v[124:127], v[146:149], v[182:185], v[124:127]
	v_mfma_f32_16x16x32_bf16 v[120:123], v[154:157], v[182:185], v[120:123]
	v_mfma_f32_16x16x32_bf16 v[108:111], v[146:149], v[190:193], v[108:111]
	v_mfma_f32_16x16x32_bf16 v[104:107], v[154:157], v[190:193], v[104:107]
	v_mfma_f32_16x16x32_bf16 v[92:95], v[146:149], v[198:201], v[92:95]
	v_mfma_f32_16x16x32_bf16 v[88:91], v[154:157], v[198:201], v[88:91]
	v_mfma_f32_16x16x32_bf16 v[76:79], v[146:149], v[206:209], v[76:79]
	v_mfma_f32_16x16x32_bf16 v[72:75], v[154:157], v[206:209], v[72:75]
	s_setprio 0
	s_setprio 1
	v_mfma_f32_16x16x32_bf16 v[116:119], v[162:165], v[178:181], v[116:119]
	v_mfma_f32_16x16x32_bf16 v[112:115], v[170:173], v[178:181], v[112:115]
	v_mfma_f32_16x16x32_bf16 v[100:103], v[162:165], v[186:189], v[100:103]
	v_mfma_f32_16x16x32_bf16 v[96:99], v[170:173], v[186:189], v[96:99]
	v_mfma_f32_16x16x32_bf16 v[84:87], v[162:165], v[194:197], v[84:87]
	v_mfma_f32_16x16x32_bf16 v[80:83], v[170:173], v[194:197], v[80:83]
	v_mfma_f32_16x16x32_bf16 v[68:71], v[162:165], v[202:205], v[68:71]
	v_mfma_f32_16x16x32_bf16 v[64:67], v[170:173], v[202:205], v[64:67]
	v_mfma_f32_16x16x32_bf16 v[116:119], v[166:169], v[182:185], v[116:119]
	v_mfma_f32_16x16x32_bf16 v[112:115], v[174:177], v[182:185], v[112:115]
	v_mfma_f32_16x16x32_bf16 v[100:103], v[166:169], v[190:193], v[100:103]
	v_mfma_f32_16x16x32_bf16 v[96:99], v[174:177], v[190:193], v[96:99]
	v_mfma_f32_16x16x32_bf16 v[84:87], v[166:169], v[198:201], v[84:87]
	v_mfma_f32_16x16x32_bf16 v[80:83], v[174:177], v[198:201], v[80:83]
	v_mfma_f32_16x16x32_bf16 v[68:71], v[166:169], v[206:209], v[68:71]
	v_mfma_f32_16x16x32_bf16 v[64:67], v[174:177], v[206:209], v[64:67]
	s_setprio 0
	s_barrier
; #define PG8_STAGE(bufoff, gbase, voff) do { _Pragma("unroll") for (int _i = 0; _i < 2; ++_i) \
;         __builtin_amdgcn_global_load_lds((const unsigned*)((const char*)(gbase) + (voff)[_i]), (LAS unsigned*)(lds + (bufoff) + ldsw + _i * 8192), 16, 0, 0); } while (0)
; #define PG8_LDA(dst, b, h) do { _Pragma("unroll") for (int m = 0; m < 4; ++m) _Pragma("unroll") for (int k = 0; k < 2; ++k) dst[m][k] = *(const LAS bf16x8*)(lds + PG8_SA(b, h) + aoff + m * 2048 + k * 1024); } while (0)
; #define PG8_MMA(ai, bj, At, Bt) do { __builtin_amdgcn_s_setprio(1); _Pragma("unroll") for (int m = 0; m < 4; ++m) _Pragma("unroll") for (int n = 0; n < 2; ++n) _Pragma("unroll") for (int k = 0; k < 2; ++k) \
;         acc[ai][bj][m][n] = __builtin_amdgcn_mfma_f32_16x16x32_bf16(Bt[n][k], At[m][k], acc[ai][bj][m][n], 0, 0, 0); __builtin_amdgcn_s_setprio(0); } while (0)
; #define PG8_WAIT_V(n) asm volatile("s_waitcnt vmcnt(" #n ")" ::: "memory")
; #define PG8_WAIT_L(n) asm volatile("s_waitcnt lgkmcnt(" #n ")" ::: "memory")
; #define PG8_BAR __builtin_amdgcn_s_barrier()
; #define PG8_SCHED __builtin_amdgcn_sched_barrier(0)
; template <class Epi, bool ALIGN_EPI = true>
; __device__ __forceinline__ void gemm_phase(LAS unsigned char* lds, const Gemm g, const StaticOrder& S, const Epi& E, int wave_k) {
;     ...
;             PG8_LDA(At, 1, 1); PG8_STAGE(PG8_SB(1, 0), b3, voffB); PG8_STAGE(PG8_SB(1, 1), b3 + hstepB, voffB); PG8_STAGE(PG8_SA(1, 0), a3, voffA);
;             PG8_WAIT_V(8); PG8_WAIT_L(0); PG8_BAR; PG8_MMA(1, 0, At, B0); PG8_MMA(1, 1, At, B1); PG8_BAR; PG8_SCHED;
;         }
;         if constexpr (ALIGN_EPI) { if (wr == 0) PG8_BAR; }
	s_add_i32 s24, s71, s58
	v_lshl_add_u64 v[158:159], v[158:159], 0, s[22:23]
	s_mov_b32 m0, s24
	ds_read_b128 v[178:181], v145 offset:49152
	ds_read_b128 v[182:185], v145 offset:50176
	ds_read_b128 v[186:189], v145 offset:51200
	ds_read_b128 v[190:193], v145 offset:52224
	ds_read_b128 v[194:197], v145 offset:53248
	ds_read_b128 v[198:201], v145 offset:54272
	ds_read_b128 v[202:205], v145 offset:55296
	ds_read_b128 v[206:209], v145 offset:56320
	global_load_lds_dwordx4 v[158:159], off
	s_add_i32 m0, s24, 0x2000
	s_add_u32 s16, s16, 0x40080
	v_lshl_add_u64 v[158:159], v[210:211], 0, s[22:23]
	s_addc_u32 s17, s17, 0
	s_add_i32 s24, s72, s58
	global_load_lds_dwordx4 v[158:159], off
	s_mov_b32 m0, s24
	s_nop 0
	global_load_lds_dwordx4 v160, s[16:17]
	s_add_i32 m0, s24, 0x2000
	s_nop 0
	global_load_lds_dwordx4 v132, s[16:17]
	v_lshl_add_u64 v[158:159], v[212:213], 0, s[22:23]
	s_mov_b32 m0, s61
	s_nop 0
	global_load_lds_dwordx4 v[158:159], off
	v_lshl_add_u64 v[158:159], v[218:219], 0, s[22:23]
	s_mov_b32 m0, s62
	s_nop 0
	global_load_lds_dwordx4 v[158:159], off
	s_waitcnt vmcnt(8)
	s_waitcnt lgkmcnt(0)
	s_barrier
	s_setprio 1
	s_waitcnt lgkmcnt(0)
	v_mfma_f32_16x16x32_bf16 v[60:63], v[138:141], v[178:181], v[60:63]
	v_mfma_f32_16x16x32_bf16 v[56:59], v[150:153], v[178:181], v[56:59]
	v_mfma_f32_16x16x32_bf16 v[44:47], v[138:141], v[186:189], v[44:47]
	v_mfma_f32_16x16x32_bf16 v[40:43], v[150:153], v[186:189], v[40:43]
	v_mfma_f32_16x16x32_bf16 v[28:31], v[138:141], v[194:197], v[28:31]
	v_mfma_f32_16x16x32_bf16 v[24:27], v[150:153], v[194:197], v[24:27]
	v_mfma_f32_16x16x32_bf16 v[12:15], v[138:141], v[202:205], v[12:15]
	v_mfma_f32_16x16x32_bf16 v[8:11], v[150:153], v[202:205], v[8:11]
	v_mfma_f32_16x16x32_bf16 v[60:63], v[146:149], v[182:185], v[60:63]
	v_mfma_f32_16x16x32_bf16 v[56:59], v[154:157], v[182:185], v[56:59]
	v_mfma_f32_16x16x32_bf16 v[44:47], v[146:149], v[190:193], v[44:47]
	v_mfma_f32_16x16x32_bf16 v[40:43], v[154:157], v[190:193], v[40:43]
	v_mfma_f32_16x16x32_bf16 v[28:31], v[146:149], v[198:201], v[28:31]
	v_mfma_f32_16x16x32_bf16 v[24:27], v[154:157], v[198:201], v[24:27]
	v_mfma_f32_16x16x32_bf16 v[12:15], v[146:149], v[206:209], v[12:15]
	v_mfma_f32_16x16x32_bf16 v[8:11], v[154:157], v[206:209], v[8:11]
	s_setprio 0
	s_setprio 1
	v_mfma_f32_16x16x32_bf16 v[52:55], v[162:165], v[178:181], v[52:55]
	v_mfma_f32_16x16x32_bf16 v[48:51], v[170:173], v[178:181], v[48:51]
	v_mfma_f32_16x16x32_bf16 v[36:39], v[162:165], v[186:189], v[36:39]
	v_mfma_f32_16x16x32_bf16 v[32:35], v[170:173], v[186:189], v[32:35]
	v_mfma_f32_16x16x32_bf16 v[20:23], v[162:165], v[194:197], v[20:23]
	v_mfma_f32_16x16x32_bf16 v[16:19], v[170:173], v[194:197], v[16:19]
	v_mfma_f32_16x16x32_bf16 v[4:7], v[162:165], v[202:205], v[4:7]
	v_mfma_f32_16x16x32_bf16 v[0:3], v[170:173], v[202:205], v[0:3]
	v_mfma_f32_16x16x32_bf16 v[52:55], v[166:169], v[182:185], v[52:55]
	v_mfma_f32_16x16x32_bf16 v[48:51], v[174:177], v[182:185], v[48:51]
	v_mfma_f32_16x16x32_bf16 v[36:39], v[166:169], v[190:193], v[36:39]
	v_mfma_f32_16x16x32_bf16 v[32:35], v[174:177], v[190:193], v[32:35]
	v_mfma_f32_16x16x32_bf16 v[20:23], v[166:169], v[198:201], v[20:23]
	v_mfma_f32_16x16x32_bf16 v[16:19], v[174:177], v[198:201], v[16:19]
	v_mfma_f32_16x16x32_bf16 v[4:7], v[166:169], v[206:209], v[4:7]
	v_mfma_f32_16x16x32_bf16 v[0:3], v[174:177], v[206:209], v[0:3]
	s_setprio 0
	s_barrier
	s_add_i32 s70, s70, 2
	s_add_u32 s50, s50, 0x100
	s_addc_u32 s51, s51, 0
	s_add_u32 s66, s66, 0x100
	s_addc_u32 s67, s67, 0
	s_cmp_gt_u32 s70, 13
	s_cbranch_scc0 .LBB0_1057
	s_and_b64 vcc, exec, s[20:21]
	s_cbranch_vccz .LBB0_1060
	s_barrier

; #define PG8_STAGE(bufoff, gbase, voff) do { _Pragma("unroll") for (int _i = 0; _i < 2; ++_i) \
;         __builtin_amdgcn_global_load_lds((const unsigned*)((const char*)(gbase) + (voff)[_i]), (LAS unsigned*)(lds + (bufoff) + ldsw + _i * 8192), 16, 0, 0); } while (0)
; #define PG8_LDA(dst, b, h) do { _Pragma("unroll") for (int m = 0; m < 4; ++m) _Pragma("unroll") for (int k = 0; k < 2; ++k) dst[m][k] = *(const LAS bf16x8*)(lds + PG8_SA(b, h) + aoff + m * 2048 + k * 1024); } while (0)
; #define PG8_LDB(dst, b, h) do { _Pragma("unroll") for (int n = 0; n < 2; ++n) _Pragma("unroll") for (int k = 0; k < 2; ++k) dst[n][k] = *(const LAS bf16x8*)(lds + PG8_SB(b, h) + boff + n * 2048 + k * 1024); } while (0)
; #define PG8_MMA(ai, bj, At, Bt) do { __builtin_amdgcn_s_setprio(1); _Pragma("unroll") for (int m = 0; m < 4; ++m) _Pragma("unroll") for (int n = 0; n < 2; ++n) _Pragma("unroll") for (int k = 0; k < 2; ++k) \
;         acc[ai][bj][m][n] = __builtin_amdgcn_mfma_f32_16x16x32_bf16(Bt[n][k], At[m][k], acc[ai][bj][m][n], 0, 0, 0); __builtin_amdgcn_s_setprio(0); } while (0)
; #define PG8_WAIT_V(n) asm volatile("s_waitcnt vmcnt(" #n ")" ::: "memory")
; #define PG8_WAIT_L(n) asm volatile("s_waitcnt lgkmcnt(" #n ")" ::: "memory")
; #define PG8_BAR __builtin_amdgcn_s_barrier()
; #define PG8_SCHED __builtin_amdgcn_sched_barrier(0)
; template <class Epi, bool ALIGN_EPI = true>
; __device__ __forceinline__ void gemm_phase(LAS unsigned char* lds, const Gemm g, const StaticOrder& S, const Epi& E, int wave_k) {
;     ...
;         for (int t = 0; t < nt; t += 2) {
;             const bool last = (t == nt - 2);
;             const char* a1 = cA + (size_t)(t + 1) * kstep;
;             const char* a2 = last ? nA : cA + (size_t)(t + 2) * kstep; const char* b2 = last ? nB : cB + (size_t)(t + 2) * kstep;
;             const char* a3 = a2 + kstep; const char* b3 = b2 + kstep;
;             PG8_LDB(B0, 0, 0); PG8_LDB(B1, 0, 1); PG8_SCHED; PG8_LDA(At, 0, 0); PG8_STAGE(PG8_SA(1, 1), a1 + hstepA, voffA);
;             PG8_WAIT_V(8); PG8_WAIT_L(0); PG8_BAR; PG8_MMA(0, 0, At, B0); PG8_MMA(0, 1, At, B1); PG8_BAR; PG8_SCHED;
;             PG8_LDA(At, 0, 1); PG8_STAGE(PG8_SB(0, 0), b2, voffB); PG8_STAGE(PG8_SB(0, 1), b2 + hstepB, voffB); PG8_STAGE(PG8_SA(0, 0), a2, voffA);
;             PG8_WAIT_V(8); PG8_WAIT_L(0); PG8_BAR; PG8_MMA(1, 0, At, B0); PG8_MMA(1, 1, At, B1); PG8_BAR; PG8_SCHED;
.LBB0_1141:
	s_add_u32 s16, s2, 0xfffc0080
	s_addc_u32 s17, s3, -1
	s_add_i32 s65, 0, 0x10000
	s_cmp_eq_u32 s64, 12
	s_cselect_b32 s19, s44, s17
	s_cselect_b32 s18, s45, s16
	s_cselect_b32 s17, s47, s63
	s_cselect_b32 s16, s49, s62
	s_add_i32 s68, 0, 0x14000
	v_add_u32_e32 v150, s65, v157
	v_add_u32_e32 v154, s68, v157
	ds_read_b128 v[138:141], v150
	ds_read_b128 v[142:145], v150 offset:1024
	ds_read_b128 v[146:149], v150 offset:2048
	ds_read_b128 v[150:153], v150 offset:3072
	ds_read_b128 v[162:165], v154
	ds_read_b128 v[166:169], v154 offset:1024
	ds_read_b128 v[170:173], v154 offset:2048
	ds_read_b128 v[174:177], v154 offset:3072
	s_add_i32 m0, s55, 0xc000
	ds_read_b128 v[178:181], v159
	ds_read_b128 v[182:185], v159 offset:1024
	ds_read_b128 v[186:189], v159 offset:2048
	ds_read_b128 v[190:193], v159 offset:3072
	ds_read_b128 v[194:197], v159 offset:4096
	ds_read_b128 v[198:201], v159 offset:5120
	ds_read_b128 v[202:205], v159 offset:6144
	ds_read_b128 v[206:209], v159 offset:7168
	global_load_lds_dwordx4 v134, s[2:3]
	s_add_i32 m0, s55, 0xe000
	s_nop 0
	global_load_lds_dwordx4 v136, s[2:3]
	s_waitcnt vmcnt(8)
	s_waitcnt lgkmcnt(0)
	s_barrier
	s_setprio 1
	s_waitcnt lgkmcnt(0)
	v_mfma_f32_16x16x32_bf16 v[124:127], v[138:141], v[178:181], v[124:127]
	v_mfma_f32_16x16x32_bf16 v[120:123], v[146:149], v[178:181], v[120:123]
	v_mfma_f32_16x16x32_bf16 v[108:111], v[138:141], v[186:189], v[108:111]
	v_mfma_f32_16x16x32_bf16 v[100:103], v[146:149], v[186:189], v[100:103]
	v_mfma_f32_16x16x32_bf16 v[92:95], v[138:141], v[194:197], v[92:95]
	v_mfma_f32_16x16x32_bf16 v[84:87], v[146:149], v[194:197], v[84:87]
	v_mfma_f32_16x16x32_bf16 v[76:79], v[138:141], v[202:205], v[76:79]
	v_mfma_f32_16x16x32_bf16 v[68:71], v[146:149], v[202:205], v[68:71]
	v_mfma_f32_16x16x32_bf16 v[124:127], v[142:145], v[182:185], v[124:127]
	v_mfma_f32_16x16x32_bf16 v[120:123], v[150:153], v[182:185], v[120:123]
	v_mfma_f32_16x16x32_bf16 v[108:111], v[142:145], v[190:193], v[108:111]
	v_mfma_f32_16x16x32_bf16 v[100:103], v[150:153], v[190:193], v[100:103]
	v_mfma_f32_16x16x32_bf16 v[92:95], v[142:145], v[198:201], v[92:95]
	v_mfma_f32_16x16x32_bf16 v[84:87], v[150:153], v[198:201], v[84:87]
	v_mfma_f32_16x16x32_bf16 v[76:79], v[142:145], v[206:209], v[76:79]
	v_mfma_f32_16x16x32_bf16 v[68:71], v[150:153], v[206:209], v[68:71]
	s_setprio 0
	s_setprio 1
	v_mfma_f32_16x16x32_bf16 v[116:119], v[162:165], v[178:181], v[116:119]
	v_mfma_f32_16x16x32_bf16 v[112:115], v[170:173], v[178:181], v[112:115]
	v_mfma_f32_16x16x32_bf16 v[104:107], v[162:165], v[186:189], v[104:107]
	v_mfma_f32_16x16x32_bf16 v[96:99], v[170:173], v[186:189], v[96:99]
	v_mfma_f32_16x16x32_bf16 v[88:91], v[162:165], v[194:197], v[88:91]
	v_mfma_f32_16x16x32_bf16 v[80:83], v[170:173], v[194:197], v[80:83]
	v_mfma_f32_16x16x32_bf16 v[72:75], v[162:165], v[202:205], v[72:75]
	v_mfma_f32_16x16x32_bf16 v[64:67], v[170:173], v[202:205], v[64:67]
	v_mfma_f32_16x16x32_bf16 v[116:119], v[166:169], v[182:185], v[116:119]
	v_mfma_f32_16x16x32_bf16 v[112:115], v[174:177], v[182:185], v[112:115]
	v_mfma_f32_16x16x32_bf16 v[104:107], v[166:169], v[190:193], v[104:107]
	v_mfma_f32_16x16x32_bf16 v[96:99], v[174:177], v[190:193], v[96:99]
	v_mfma_f32_16x16x32_bf16 v[88:91], v[166:169], v[198:201], v[88:91]
	v_mfma_f32_16x16x32_bf16 v[80:83], v[174:177], v[198:201], v[80:83]
	v_mfma_f32_16x16x32_bf16 v[72:75], v[166:169], v[206:209], v[72:75]
	v_mfma_f32_16x16x32_bf16 v[64:67], v[174:177], v[206:209], v[64:67]
	s_setprio 0
	s_barrier
	s_add_i32 s65, s65, s29
	v_lshl_add_u64 v[154:155], s[16:17], 0, v[160:161]
	s_mov_b32 m0, s65
	ds_read_b128 v[178:181], v159 offset:16384
	ds_read_b128 v[182:185], v159 offset:17408
	ds_read_b128 v[186:189], v159 offset:18432
	ds_read_b128 v[190:193], v159 offset:19456
	ds_read_b128 v[194:197], v159 offset:20480
	ds_read_b128 v[198:201], v159 offset:21504
	ds_read_b128 v[202:205], v159 offset:22528
	ds_read_b128 v[206:209], v159 offset:23552
	global_load_lds_dwordx4 v[154:155], off
	s_add_i32 m0, s65, 0x2000
	s_add_u32 s66, s16, 0x40000
	v_lshl_add_u64 v[210:211], s[16:17], 0, v[128:129]
	s_addc_u32 s67, s17, 0
	s_add_i32 s65, s68, s29
	global_load_lds_dwordx4 v[210:211], off
	s_mov_b32 m0, s65
	v_lshl_add_u64 v[218:219], s[18:19], 0, v[130:131]
	global_load_lds_dwordx4 v160, s[66:67]
	s_add_i32 m0, s65, 0x2000
	s_nop 0
	global_load_lds_dwordx4 v128, s[66:67]
	v_lshl_add_u64 v[212:213], s[18:19], 0, v[132:133]
	s_mov_b32 m0, s55
	s_nop 0
	global_load_lds_dwordx4 v[212:213], off
	s_mov_b32 m0, s56
	s_nop 0
	global_load_lds_dwordx4 v[218:219], off
	s_waitcnt vmcnt(8)
	s_waitcnt lgkmcnt(0)
	s_barrier
; #define PG8_STAGE(bufoff, gbase, voff) do { _Pragma("unroll") for (int _i = 0; _i < 2; ++_i) \
;         __builtin_amdgcn_global_load_lds((const unsigned*)((const char*)(gbase) + (voff)[_i]), (LAS unsigned*)(lds + (bufoff) + ldsw + _i * 8192), 16, 0, 0); } while (0)
; #define PG8_LDA(dst, b, h) do { _Pragma("unroll") for (int m = 0; m < 4; ++m) _Pragma("unroll") for (int k = 0; k < 2; ++k) dst[m][k] = *(const LAS bf16x8*)(lds + PG8_SA(b, h) + aoff + m * 2048 + k * 1024); } while (0)
; #define PG8_LDB(dst, b, h) do { _Pragma("unroll") for (int n = 0; n < 2; ++n) _Pragma("unroll") for (int k = 0; k < 2; ++k) dst[n][k] = *(const LAS bf16x8*)(lds + PG8_SB(b, h) + boff + n * 2048 + k * 1024); } while (0)
; #define PG8_MMA(ai, bj, At, Bt) do { __builtin_amdgcn_s_setprio(1); _Pragma("unroll") for (int m = 0; m < 4; ++m) _Pragma("unroll") for (int n = 0; n < 2; ++n) _Pragma("unroll") for (int k = 0; k < 2; ++k) \
;         acc[ai][bj][m][n] = __builtin_amdgcn_mfma_f32_16x16x32_bf16(Bt[n][k], At[m][k], acc[ai][bj][m][n], 0, 0, 0); __builtin_amdgcn_s_setprio(0); } while (0)
; #define PG8_WAIT_V(n) asm volatile("s_waitcnt vmcnt(" #n ")" ::: "memory")
; #define PG8_WAIT_L(n) asm volatile("s_waitcnt lgkmcnt(" #n ")" ::: "memory")
; #define PG8_BAR __builtin_amdgcn_s_barrier()
; #define PG8_SCHED __builtin_amdgcn_sched_barrier(0)
; template <class Epi, bool ALIGN_EPI = true>
; __device__ __forceinline__ void gemm_phase(LAS unsigned char* lds, const Gemm g, const StaticOrder& S, const Epi& E, int wave_k) {
;     ...
;             PG8_WAIT_V(8); PG8_WAIT_L(0); PG8_BAR; PG8_MMA(1, 0, At, B0); PG8_MMA(1, 1, At, B1); PG8_BAR; PG8_SCHED;
;             PG8_LDB(B0, 1, 0); PG8_LDB(B1, 1, 1); PG8_SCHED; PG8_LDA(At, 1, 0); PG8_STAGE(PG8_SA(0, 1), a2 + hstepA, voffA);
;             PG8_WAIT_V(8); PG8_WAIT_L(0); PG8_BAR; PG8_MMA(0, 0, At, B0); PG8_MMA(0, 1, At, B1); PG8_BAR; PG8_SCHED;
	s_setprio 1
	s_waitcnt lgkmcnt(0)
	v_mfma_f32_16x16x32_bf16 v[60:63], v[138:141], v[178:181], v[60:63]
	v_mfma_f32_16x16x32_bf16 v[52:55], v[146:149], v[178:181], v[52:55]
	v_mfma_f32_16x16x32_bf16 v[44:47], v[138:141], v[186:189], v[44:47]
	v_mfma_f32_16x16x32_bf16 v[36:39], v[146:149], v[186:189], v[36:39]
	v_mfma_f32_16x16x32_bf16 v[28:31], v[138:141], v[194:197], v[28:31]
	v_mfma_f32_16x16x32_bf16 v[20:23], v[146:149], v[194:197], v[20:23]
	v_mfma_f32_16x16x32_bf16 v[12:15], v[138:141], v[202:205], v[12:15]
	v_mfma_f32_16x16x32_bf16 v[4:7], v[146:149], v[202:205], v[4:7]
	v_mfma_f32_16x16x32_bf16 v[60:63], v[142:145], v[182:185], v[60:63]
	v_mfma_f32_16x16x32_bf16 v[52:55], v[150:153], v[182:185], v[52:55]
	v_mfma_f32_16x16x32_bf16 v[44:47], v[142:145], v[190:193], v[44:47]
	v_mfma_f32_16x16x32_bf16 v[36:39], v[150:153], v[190:193], v[36:39]
	v_mfma_f32_16x16x32_bf16 v[28:31], v[142:145], v[198:201], v[28:31]
	v_mfma_f32_16x16x32_bf16 v[20:23], v[150:153], v[198:201], v[20:23]
	v_mfma_f32_16x16x32_bf16 v[12:15], v[142:145], v[206:209], v[12:15]
	v_mfma_f32_16x16x32_bf16 v[4:7], v[150:153], v[206:209], v[4:7]
	s_setprio 0
	s_setprio 1
	v_mfma_f32_16x16x32_bf16 v[56:59], v[162:165], v[178:181], v[56:59]
	v_mfma_f32_16x16x32_bf16 v[48:51], v[170:173], v[178:181], v[48:51]
	v_mfma_f32_16x16x32_bf16 v[40:43], v[162:165], v[186:189], v[40:43]
	v_mfma_f32_16x16x32_bf16 v[32:35], v[170:173], v[186:189], v[32:35]
	v_mfma_f32_16x16x32_bf16 v[24:27], v[162:165], v[194:197], v[24:27]
	v_mfma_f32_16x16x32_bf16 v[16:19], v[170:173], v[194:197], v[16:19]
	v_mfma_f32_16x16x32_bf16 v[8:11], v[162:165], v[202:205], v[8:11]
	v_mfma_f32_16x16x32_bf16 v[0:3], v[170:173], v[202:205], v[0:3]
	v_mfma_f32_16x16x32_bf16 v[56:59], v[166:169], v[182:185], v[56:59]
	v_mfma_f32_16x16x32_bf16 v[48:51], v[174:177], v[182:185], v[48:51]
	v_mfma_f32_16x16x32_bf16 v[40:43], v[166:169], v[190:193], v[40:43]
	v_mfma_f32_16x16x32_bf16 v[32:35], v[174:177], v[190:193], v[32:35]
	v_mfma_f32_16x16x32_bf16 v[24:27], v[166:169], v[198:201], v[24:27]
	v_mfma_f32_16x16x32_bf16 v[16:19], v[174:177], v[198:201], v[16:19]
	v_mfma_f32_16x16x32_bf16 v[8:11], v[166:169], v[206:209], v[8:11]
	v_mfma_f32_16x16x32_bf16 v[0:3], v[174:177], v[206:209], v[0:3]
	s_setprio 0
	s_barrier
	s_add_i32 s65, 0, 0x18000
	s_add_i32 s66, 0, 0x1c000
	v_add_u32_e32 v150, s65, v157
	v_add_u32_e32 v174, s66, v157
	ds_read_b128 v[138:141], v150
	ds_read_b128 v[142:145], v150 offset:1024
	ds_read_b128 v[146:149], v150 offset:2048
	ds_read_b128 v[150:153], v150 offset:3072
	ds_read_b128 v[162:165], v174
	ds_read_b128 v[166:169], v174 offset:1024
	ds_read_b128 v[170:173], v174 offset:2048
	ds_read_b128 v[174:177], v174 offset:3072
	s_add_u32 s18, s18, 0x40000
	s_addc_u32 s19, s19, 0
	s_mov_b32 m0, s57
	ds_read_b128 v[178:181], v159 offset:32768
	ds_read_b128 v[182:185], v159 offset:33792
	ds_read_b128 v[186:189], v159 offset:34816
	ds_read_b128 v[190:193], v159 offset:35840
	ds_read_b128 v[194:197], v159 offset:36864
	ds_read_b128 v[198:201], v159 offset:37888
	ds_read_b128 v[202:205], v159 offset:38912
	ds_read_b128 v[206:209], v159 offset:39936
	global_load_lds_dwordx4 v132, s[18:19]
	s_mov_b32 m0, s58
	s_nop 0
	global_load_lds_dwordx4 v130, s[18:19]
	s_waitcnt vmcnt(8)
	s_waitcnt lgkmcnt(0)
	s_barrier
	s_setprio 1
	s_waitcnt lgkmcnt(0)
	v_mfma_f32_16x16x32_bf16 v[124:127], v[138:141], v[178:181], v[124:127]
	v_mfma_f32_16x16x32_bf16 v[120:123], v[146:149], v[178:181], v[120:123]
	v_mfma_f32_16x16x32_bf16 v[108:111], v[138:141], v[186:189], v[108:111]
	v_mfma_f32_16x16x32_bf16 v[100:103], v[146:149], v[186:189], v[100:103]
	v_mfma_f32_16x16x32_bf16 v[92:95], v[138:141], v[194:197], v[92:95]
	v_mfma_f32_16x16x32_bf16 v[84:87], v[146:149], v[194:197], v[84:87]
	v_mfma_f32_16x16x32_bf16 v[76:79], v[138:141], v[202:205], v[76:79]
	v_mfma_f32_16x16x32_bf16 v[68:71], v[146:149], v[202:205], v[68:71]
	v_mfma_f32_16x16x32_bf16 v[124:127], v[142:145], v[182:185], v[124:127]
	v_mfma_f32_16x16x32_bf16 v[120:123], v[150:153], v[182:185], v[120:123]
	v_mfma_f32_16x16x32_bf16 v[108:111], v[142:145], v[190:193], v[108:111]
	v_mfma_f32_16x16x32_bf16 v[100:103], v[150:153], v[190:193], v[100:103]
	v_mfma_f32_16x16x32_bf16 v[92:95], v[142:145], v[198:201], v[92:95]
	v_mfma_f32_16x16x32_bf16 v[84:87], v[150:153], v[198:201], v[84:87]
	v_mfma_f32_16x16x32_bf16 v[76:79], v[142:145], v[206:209], v[76:79]
	v_mfma_f32_16x16x32_bf16 v[68:71], v[150:153], v[206:209], v[68:71]
	s_setprio 0
	s_setprio 1
	v_mfma_f32_16x16x32_bf16 v[116:119], v[162:165], v[178:181], v[116:119]
	v_mfma_f32_16x16x32_bf16 v[112:115], v[170:173], v[178:181], v[112:115]
	v_mfma_f32_16x16x32_bf16 v[104:107], v[162:165], v[186:189], v[104:107]
	v_mfma_f32_16x16x32_bf16 v[96:99], v[170:173], v[186:189], v[96:99]
	v_mfma_f32_16x16x32_bf16 v[88:91], v[162:165], v[194:197], v[88:91]
	v_mfma_f32_16x16x32_bf16 v[80:83], v[170:173], v[194:197], v[80:83]
	v_mfma_f32_16x16x32_bf16 v[72:75], v[162:165], v[202:205], v[72:75]
	v_mfma_f32_16x16x32_bf16 v[64:67], v[170:173], v[202:205], v[64:67]
	v_mfma_f32_16x16x32_bf16 v[116:119], v[166:169], v[182:185], v[116:119]
	v_mfma_f32_16x16x32_bf16 v[112:115], v[174:177], v[182:185], v[112:115]
	v_mfma_f32_16x16x32_bf16 v[104:107], v[166:169], v[190:193], v[104:107]
	v_mfma_f32_16x16x32_bf16 v[96:99], v[174:177], v[190:193], v[96:99]
	v_mfma_f32_16x16x32_bf16 v[88:91], v[166:169], v[198:201], v[88:91]
	v_mfma_f32_16x16x32_bf16 v[80:83], v[174:177], v[198:201], v[80:83]
	v_mfma_f32_16x16x32_bf16 v[72:75], v[166:169], v[206:209], v[72:75]
	v_mfma_f32_16x16x32_bf16 v[64:67], v[174:177], v[206:209], v[64:67]
	s_setprio 0
	s_barrier
; #define PG8_STAGE(bufoff, gbase, voff) do { _Pragma("unroll") for (int _i = 0; _i < 2; ++_i) \
;         __builtin_amdgcn_global_load_lds((const unsigned*)((const char*)(gbase) + (voff)[_i]), (LAS unsigned*)(lds + (bufoff) + ldsw + _i * 8192), 16, 0, 0); } while (0)
; #define PG8_LDA(dst, b, h) do { _Pragma("unroll") for (int m = 0; m < 4; ++m) _Pragma("unroll") for (int k = 0; k < 2; ++k) dst[m][k] = *(const LAS bf16x8*)(lds + PG8_SA(b, h) + aoff + m * 2048 + k * 1024); } while (0)
; #define PG8_MMA(ai, bj, At, Bt) do { __builtin_amdgcn_s_setprio(1); _Pragma("unroll") for (int m = 0; m < 4; ++m) _Pragma("unroll") for (int n = 0; n < 2; ++n) _Pragma("unroll") for (int k = 0; k < 2; ++k) \
;         acc[ai][bj][m][n] = __builtin_amdgcn_mfma_f32_16x16x32_bf16(Bt[n][k], At[m][k], acc[ai][bj][m][n], 0, 0, 0); __builtin_amdgcn_s_setprio(0); } while (0)
; #define PG8_WAIT_V(n) asm volatile("s_waitcnt vmcnt(" #n ")" ::: "memory")
; #define PG8_WAIT_L(n) asm volatile("s_waitcnt lgkmcnt(" #n ")" ::: "memory")
; #define PG8_BAR __builtin_amdgcn_s_barrier()
; #define PG8_SCHED __builtin_amdgcn_sched_barrier(0)
; template <class Epi, bool ALIGN_EPI = true>
; __device__ __forceinline__ void gemm_phase(LAS unsigned char* lds, const Gemm g, const StaticOrder& S, const Epi& E, int wave_k) {
;     ...
;             PG8_LDA(At, 1, 1); PG8_STAGE(PG8_SB(1, 0), b3, voffB); PG8_STAGE(PG8_SB(1, 1), b3 + hstepB, voffB); PG8_STAGE(PG8_SA(1, 0), a3, voffA);
;             PG8_WAIT_V(8); PG8_WAIT_L(0); PG8_BAR; PG8_MMA(1, 0, At, B0); PG8_MMA(1, 1, At, B1); PG8_BAR; PG8_SCHED;
;         }
;         if constexpr (ALIGN_EPI) { if (wr == 0) PG8_BAR; }
	s_add_i32 s18, s65, s29
	v_lshl_add_u64 v[154:155], v[154:155], 0, s[22:23]
	s_mov_b32 m0, s18
	ds_read_b128 v[178:181], v159 offset:49152
	ds_read_b128 v[182:185], v159 offset:50176
	ds_read_b128 v[186:189], v159 offset:51200
	ds_read_b128 v[190:193], v159 offset:52224
	ds_read_b128 v[194:197], v159 offset:53248
	ds_read_b128 v[198:201], v159 offset:54272
	ds_read_b128 v[202:205], v159 offset:55296
	ds_read_b128 v[206:209], v159 offset:56320
	global_load_lds_dwordx4 v[154:155], off
	s_add_i32 m0, s18, 0x2000
	s_add_u32 s16, s16, 0x40080
	v_lshl_add_u64 v[154:155], v[210:211], 0, s[22:23]
	s_addc_u32 s17, s17, 0
	s_add_i32 s18, s66, s29
	global_load_lds_dwordx4 v[154:155], off
	s_mov_b32 m0, s18
	s_nop 0
	global_load_lds_dwordx4 v160, s[16:17]
	s_add_i32 m0, s18, 0x2000
	s_nop 0
	global_load_lds_dwordx4 v128, s[16:17]
	v_lshl_add_u64 v[154:155], v[212:213], 0, s[22:23]
	s_mov_b32 m0, s20
	s_nop 0
	global_load_lds_dwordx4 v[154:155], off
	v_lshl_add_u64 v[154:155], v[218:219], 0, s[22:23]
	s_mov_b32 m0, s59
	s_nop 0
	global_load_lds_dwordx4 v[154:155], off
	s_waitcnt vmcnt(8)
	s_waitcnt lgkmcnt(0)
	s_barrier
	s_setprio 1
	s_waitcnt lgkmcnt(0)
	v_mfma_f32_16x16x32_bf16 v[60:63], v[138:141], v[178:181], v[60:63]
	v_mfma_f32_16x16x32_bf16 v[52:55], v[146:149], v[178:181], v[52:55]
	v_mfma_f32_16x16x32_bf16 v[44:47], v[138:141], v[186:189], v[44:47]
	v_mfma_f32_16x16x32_bf16 v[36:39], v[146:149], v[186:189], v[36:39]
	v_mfma_f32_16x16x32_bf16 v[28:31], v[138:141], v[194:197], v[28:31]
	v_mfma_f32_16x16x32_bf16 v[20:23], v[146:149], v[194:197], v[20:23]
	v_mfma_f32_16x16x32_bf16 v[12:15], v[138:141], v[202:205], v[12:15]
	v_mfma_f32_16x16x32_bf16 v[4:7], v[146:149], v[202:205], v[4:7]
	v_mfma_f32_16x16x32_bf16 v[60:63], v[142:145], v[182:185], v[60:63]
	v_mfma_f32_16x16x32_bf16 v[52:55], v[150:153], v[182:185], v[52:55]
	v_mfma_f32_16x16x32_bf16 v[44:47], v[142:145], v[190:193], v[44:47]
	v_mfma_f32_16x16x32_bf16 v[36:39], v[150:153], v[190:193], v[36:39]
	v_mfma_f32_16x16x32_bf16 v[28:31], v[142:145], v[198:201], v[28:31]
	v_mfma_f32_16x16x32_bf16 v[20:23], v[150:153], v[198:201], v[20:23]
	v_mfma_f32_16x16x32_bf16 v[12:15], v[142:145], v[206:209], v[12:15]
	v_mfma_f32_16x16x32_bf16 v[4:7], v[150:153], v[206:209], v[4:7]
	s_setprio 0
	s_setprio 1
	v_mfma_f32_16x16x32_bf16 v[56:59], v[162:165], v[178:181], v[56:59]
	v_mfma_f32_16x16x32_bf16 v[48:51], v[170:173], v[178:181], v[48:51]
	v_mfma_f32_16x16x32_bf16 v[40:43], v[162:165], v[186:189], v[40:43]
	v_mfma_f32_16x16x32_bf16 v[32:35], v[170:173], v[186:189], v[32:35]
	v_mfma_f32_16x16x32_bf16 v[24:27], v[162:165], v[194:197], v[24:27]
	v_mfma_f32_16x16x32_bf16 v[16:19], v[170:173], v[194:197], v[16:19]
	v_mfma_f32_16x16x32_bf16 v[8:11], v[162:165], v[202:205], v[8:11]
	v_mfma_f32_16x16x32_bf16 v[0:3], v[170:173], v[202:205], v[0:3]
	v_mfma_f32_16x16x32_bf16 v[56:59], v[166:169], v[182:185], v[56:59]
	v_mfma_f32_16x16x32_bf16 v[48:51], v[174:177], v[182:185], v[48:51]
	v_mfma_f32_16x16x32_bf16 v[40:43], v[166:169], v[190:193], v[40:43]
	v_mfma_f32_16x16x32_bf16 v[32:35], v[174:177], v[190:193], v[32:35]
	v_mfma_f32_16x16x32_bf16 v[24:27], v[166:169], v[198:201], v[24:27]
	v_mfma_f32_16x16x32_bf16 v[16:19], v[174:177], v[198:201], v[16:19]
	v_mfma_f32_16x16x32_bf16 v[8:11], v[166:169], v[206:209], v[8:11]
	v_mfma_f32_16x16x32_bf16 v[0:3], v[174:177], v[206:209], v[0:3]
	s_setprio 0
	s_barrier
	s_add_i32 s64, s64, 2
	s_add_u32 s2, s2, 0x100
	s_addc_u32 s3, s3, 0
	s_add_u32 s62, s62, 0x100
	s_addc_u32 s63, s63, 0
	s_cmp_gt_u32 s64, 13
	s_cbranch_scc0 .LBB0_1141
	s_and_b64 vcc, exec, s[40:41]
	s_cbranch_vccz .LBB0_1144
	s_barrier

; #define PG8_STAGE(bufoff, gbase, voff) do { _Pragma("unroll") for (int _i = 0; _i < 2; ++_i) \
;         __builtin_amdgcn_global_load_lds((const unsigned*)((const char*)(gbase) + (voff)[_i]), (LAS unsigned*)(lds + (bufoff) + ldsw + _i * 8192), 16, 0, 0); } while (0)
; #define PG8_LDA(dst, b, h) do { _Pragma("unroll") for (int m = 0; m < 4; ++m) _Pragma("unroll") for (int k = 0; k < 2; ++k) dst[m][k] = *(const LAS bf16x8*)(lds + PG8_SA(b, h) + aoff + m * 2048 + k * 1024); } while (0)
; #define PG8_LDB(dst, b, h) do { _Pragma("unroll") for (int n = 0; n < 2; ++n) _Pragma("unroll") for (int k = 0; k < 2; ++k) dst[n][k] = *(const LAS bf16x8*)(lds + PG8_SB(b, h) + boff + n * 2048 + k * 1024); } while (0)
; #define PG8_MMA(ai, bj, At, Bt) do { __builtin_amdgcn_s_setprio(1); _Pragma("unroll") for (int m = 0; m < 4; ++m) _Pragma("unroll") for (int n = 0; n < 2; ++n) _Pragma("unroll") for (int k = 0; k < 2; ++k) \
;         acc[ai][bj][m][n] = __builtin_amdgcn_mfma_f32_16x16x32_bf16(Bt[n][k], At[m][k], acc[ai][bj][m][n], 0, 0, 0); __builtin_amdgcn_s_setprio(0); } while (0)
; #define PG8_WAIT_V(n) asm volatile("s_waitcnt vmcnt(" #n ")" ::: "memory")
; #define PG8_WAIT_L(n) asm volatile("s_waitcnt lgkmcnt(" #n ")" ::: "memory")
; #define PG8_BAR __builtin_amdgcn_s_barrier()
; #define PG8_SCHED __builtin_amdgcn_sched_barrier(0)
; template <class Epi, bool ALIGN_EPI = true>
; __device__ __forceinline__ void gemm_phase(LAS unsigned char* lds, const Gemm g, const StaticOrder& S, const Epi& E, int wave_k) {
;     ...
;         for (int t = 0; t < nt; t += 2) {
;             const bool last = (t == nt - 2);
;             const char* a1 = cA + (size_t)(t + 1) * kstep;
;             const char* a2 = last ? nA : cA + (size_t)(t + 2) * kstep; const char* b2 = last ? nB : cB + (size_t)(t + 2) * kstep;
;             const char* a3 = a2 + kstep; const char* b3 = b2 + kstep;
;             PG8_LDB(B0, 0, 0); PG8_LDB(B1, 0, 1); PG8_SCHED; PG8_LDA(At, 0, 0); PG8_STAGE(PG8_SA(1, 1), a1 + hstepA, voffA);
;             PG8_WAIT_V(8); PG8_WAIT_L(0); PG8_BAR; PG8_MMA(0, 0, At, B0); PG8_MMA(0, 1, At, B1); PG8_BAR; PG8_SCHED;
;             PG8_LDA(At, 0, 1); PG8_STAGE(PG8_SB(0, 0), b2, voffB); PG8_STAGE(PG8_SB(0, 1), b2 + hstepB, voffB); PG8_STAGE(PG8_SA(0, 0), a2, voffA);
;             PG8_WAIT_V(8); PG8_WAIT_L(0); PG8_BAR; PG8_MMA(1, 0, At, B0); PG8_MMA(1, 1, At, B1); PG8_BAR; PG8_SCHED;
.LBB0_1257:
	s_add_u32 s16, s24, 0x100
	s_addc_u32 s17, s25, 0
	s_add_i32 s67, 0, 0x10000
	s_cmp_eq_u32 s66, 40
	s_cselect_b32 s29, s1, s17
	s_cselect_b32 s28, s0, s16
	s_cselect_b32 s27, s35, s45
	s_cselect_b32 s26, s34, s44
	s_add_i32 s68, 0, 0x14000
	v_add_u32_e32 v154, s67, v143
	v_add_u32_e32 v158, s68, v143
	ds_read_b128 v[138:141], v154
	ds_read_b128 v[146:149], v154 offset:1024
	ds_read_b128 v[150:153], v154 offset:2048
	ds_read_b128 v[154:157], v154 offset:3072
	ds_read_b128 v[162:165], v158
	ds_read_b128 v[166:169], v158 offset:1024
	ds_read_b128 v[170:173], v158 offset:2048
	ds_read_b128 v[174:177], v158 offset:3072
	v_lshl_add_u64 v[158:159], s[24:25], 0, v[134:135]
	s_add_i32 m0, s55, 0xc000
	ds_read_b128 v[178:181], v145
	ds_read_b128 v[182:185], v145 offset:1024
	ds_read_b128 v[186:189], v145 offset:2048
	ds_read_b128 v[190:193], v145 offset:3072
	ds_read_b128 v[194:197], v145 offset:4096
	ds_read_b128 v[198:201], v145 offset:5120
	ds_read_b128 v[202:205], v145 offset:6144
	ds_read_b128 v[206:209], v145 offset:7168
	global_load_lds_dwordx4 v[158:159], off
	v_lshl_add_u64 v[158:159], s[24:25], 0, v[136:137]
	s_add_i32 m0, s55, 0xe000
	s_nop 0
	global_load_lds_dwordx4 v[158:159], off
	s_waitcnt vmcnt(8)
	s_waitcnt lgkmcnt(0)
	s_barrier
	s_setprio 1
	s_waitcnt lgkmcnt(0)
	v_mfma_f32_16x16x32_bf16 v[124:127], v[138:141], v[178:181], v[124:127]
	v_mfma_f32_16x16x32_bf16 v[120:123], v[150:153], v[178:181], v[120:123]
	v_mfma_f32_16x16x32_bf16 v[108:111], v[138:141], v[186:189], v[108:111]
	v_mfma_f32_16x16x32_bf16 v[104:107], v[150:153], v[186:189], v[104:107]
	v_mfma_f32_16x16x32_bf16 v[92:95], v[138:141], v[194:197], v[92:95]
	v_mfma_f32_16x16x32_bf16 v[88:91], v[150:153], v[194:197], v[88:91]
	v_mfma_f32_16x16x32_bf16 v[76:79], v[138:141], v[202:205], v[76:79]
	v_mfma_f32_16x16x32_bf16 v[72:75], v[150:153], v[202:205], v[72:75]
	v_mfma_f32_16x16x32_bf16 v[124:127], v[146:149], v[182:185], v[124:127]
	v_mfma_f32_16x16x32_bf16 v[120:123], v[154:157], v[182:185], v[120:123]
	v_mfma_f32_16x16x32_bf16 v[108:111], v[146:149], v[190:193], v[108:111]
	v_mfma_f32_16x16x32_bf16 v[104:107], v[154:157], v[190:193], v[104:107]
	v_mfma_f32_16x16x32_bf16 v[92:95], v[146:149], v[198:201], v[92:95]
	v_mfma_f32_16x16x32_bf16 v[88:91], v[154:157], v[198:201], v[88:91]
	v_mfma_f32_16x16x32_bf16 v[76:79], v[146:149], v[206:209], v[76:79]
	v_mfma_f32_16x16x32_bf16 v[72:75], v[154:157], v[206:209], v[72:75]
	s_setprio 0
	s_setprio 1
	v_mfma_f32_16x16x32_bf16 v[116:119], v[162:165], v[178:181], v[116:119]
	v_mfma_f32_16x16x32_bf16 v[112:115], v[170:173], v[178:181], v[112:115]
	v_mfma_f32_16x16x32_bf16 v[100:103], v[162:165], v[186:189], v[100:103]
	v_mfma_f32_16x16x32_bf16 v[96:99], v[170:173], v[186:189], v[96:99]
	v_mfma_f32_16x16x32_bf16 v[84:87], v[162:165], v[194:197], v[84:87]
	v_mfma_f32_16x16x32_bf16 v[80:83], v[170:173], v[194:197], v[80:83]
	v_mfma_f32_16x16x32_bf16 v[68:71], v[162:165], v[202:205], v[68:71]
	v_mfma_f32_16x16x32_bf16 v[64:67], v[170:173], v[202:205], v[64:67]
	v_mfma_f32_16x16x32_bf16 v[116:119], v[166:169], v[182:185], v[116:119]
	v_mfma_f32_16x16x32_bf16 v[112:115], v[174:177], v[182:185], v[112:115]
	v_mfma_f32_16x16x32_bf16 v[100:103], v[166:169], v[190:193], v[100:103]
	v_mfma_f32_16x16x32_bf16 v[96:99], v[174:177], v[190:193], v[96:99]
	v_mfma_f32_16x16x32_bf16 v[84:87], v[166:169], v[198:201], v[84:87]
	v_mfma_f32_16x16x32_bf16 v[80:83], v[174:177], v[198:201], v[80:83]
	v_mfma_f32_16x16x32_bf16 v[68:71], v[166:169], v[206:209], v[68:71]
	v_mfma_f32_16x16x32_bf16 v[64:67], v[174:177], v[206:209], v[64:67]
	s_setprio 0
	s_barrier
	s_add_i32 s24, s67, s54
	v_lshl_add_u64 v[158:159], s[26:27], 0, v[160:161]
	s_mov_b32 m0, s24
	ds_read_b128 v[178:181], v145 offset:16384
	ds_read_b128 v[182:185], v145 offset:17408
	ds_read_b128 v[186:189], v145 offset:18432
	ds_read_b128 v[190:193], v145 offset:19456
	ds_read_b128 v[194:197], v145 offset:20480
	ds_read_b128 v[198:201], v145 offset:21504
	ds_read_b128 v[202:205], v145 offset:22528
	ds_read_b128 v[206:209], v145 offset:23552
	global_load_lds_dwordx4 v[158:159], off
	s_add_i32 m0, s24, 0x2000
	s_add_u32 s24, s26, 0xb0000
	v_lshl_add_u64 v[210:211], s[26:27], 0, v[132:133]
	s_addc_u32 s25, s27, 0
	s_add_i32 s67, s68, s54
	global_load_lds_dwordx4 v[210:211], off
	s_mov_b32 m0, s67
	v_lshl_add_u64 v[218:219], s[28:29], 0, v[130:131]
	global_load_lds_dwordx4 v160, s[24:25]
	s_add_i32 m0, s67, 0x2000
	s_nop 0
	global_load_lds_dwordx4 v132, s[24:25]
	v_lshl_add_u64 v[212:213], s[28:29], 0, v[128:129]
	s_mov_b32 m0, s55
	s_nop 0
	global_load_lds_dwordx4 v[212:213], off
	s_mov_b32 m0, s56
	s_nop 0
	global_load_lds_dwordx4 v[218:219], off
	s_waitcnt vmcnt(8)
	s_waitcnt lgkmcnt(0)
	s_barrier
; #define PG8_STAGE(bufoff, gbase, voff) do { _Pragma("unroll") for (int _i = 0; _i < 2; ++_i) \
;         __builtin_amdgcn_global_load_lds((const unsigned*)((const char*)(gbase) + (voff)[_i]), (LAS unsigned*)(lds + (bufoff) + ldsw + _i * 8192), 16, 0, 0); } while (0)
; #define PG8_LDA(dst, b, h) do { _Pragma("unroll") for (int m = 0; m < 4; ++m) _Pragma("unroll") for (int k = 0; k < 2; ++k) dst[m][k] = *(const LAS bf16x8*)(lds + PG8_SA(b, h) + aoff + m * 2048 + k * 1024); } while (0)
; #define PG8_LDB(dst, b, h) do { _Pragma("unroll") for (int n = 0; n < 2; ++n) _Pragma("unroll") for (int k = 0; k < 2; ++k) dst[n][k] = *(const LAS bf16x8*)(lds + PG8_SB(b, h) + boff + n * 2048 + k * 1024); } while (0)
; #define PG8_MMA(ai, bj, At, Bt) do { __builtin_amdgcn_s_setprio(1); _Pragma("unroll") for (int m = 0; m < 4; ++m) _Pragma("unroll") for (int n = 0; n < 2; ++n) _Pragma("unroll") for (int k = 0; k < 2; ++k) \
;         acc[ai][bj][m][n] = __builtin_amdgcn_mfma_f32_16x16x32_bf16(Bt[n][k], At[m][k], acc[ai][bj][m][n], 0, 0, 0); __builtin_amdgcn_s_setprio(0); } while (0)
; #define PG8_WAIT_V(n) asm volatile("s_waitcnt vmcnt(" #n ")" ::: "memory")
; #define PG8_WAIT_L(n) asm volatile("s_waitcnt lgkmcnt(" #n ")" ::: "memory")
; #define PG8_BAR __builtin_amdgcn_s_barrier()
; #define PG8_SCHED __builtin_amdgcn_sched_barrier(0)
; template <class Epi, bool ALIGN_EPI = true>
; __device__ __forceinline__ void gemm_phase(LAS unsigned char* lds, const Gemm g, const StaticOrder& S, const Epi& E, int wave_k) {
;     ...
;             PG8_WAIT_V(8); PG8_WAIT_L(0); PG8_BAR; PG8_MMA(1, 0, At, B0); PG8_MMA(1, 1, At, B1); PG8_BAR; PG8_SCHED;
;             PG8_LDB(B0, 1, 0); PG8_LDB(B1, 1, 1); PG8_SCHED; PG8_LDA(At, 1, 0); PG8_STAGE(PG8_SA(0, 1), a2 + hstepA, voffA);
;             PG8_WAIT_V(8); PG8_WAIT_L(0); PG8_BAR; PG8_MMA(0, 0, At, B0); PG8_MMA(0, 1, At, B1); PG8_BAR; PG8_SCHED;
	s_setprio 1
	s_waitcnt lgkmcnt(0)
	v_mfma_f32_16x16x32_bf16 v[60:63], v[138:141], v[178:181], v[60:63]
	v_mfma_f32_16x16x32_bf16 v[56:59], v[150:153], v[178:181], v[56:59]
	v_mfma_f32_16x16x32_bf16 v[44:47], v[138:141], v[186:189], v[44:47]
	v_mfma_f32_16x16x32_bf16 v[40:43], v[150:153], v[186:189], v[40:43]
	v_mfma_f32_16x16x32_bf16 v[28:31], v[138:141], v[194:197], v[28:31]
	v_mfma_f32_16x16x32_bf16 v[24:27], v[150:153], v[194:197], v[24:27]
	v_mfma_f32_16x16x32_bf16 v[12:15], v[138:141], v[202:205], v[12:15]
	v_mfma_f32_16x16x32_bf16 v[8:11], v[150:153], v[202:205], v[8:11]
	v_mfma_f32_16x16x32_bf16 v[60:63], v[146:149], v[182:185], v[60:63]
	v_mfma_f32_16x16x32_bf16 v[56:59], v[154:157], v[182:185], v[56:59]
	v_mfma_f32_16x16x32_bf16 v[44:47], v[146:149], v[190:193], v[44:47]
	v_mfma_f32_16x16x32_bf16 v[40:43], v[154:157], v[190:193], v[40:43]
	v_mfma_f32_16x16x32_bf16 v[28:31], v[146:149], v[198:201], v[28:31]
	v_mfma_f32_16x16x32_bf16 v[24:27], v[154:157], v[198:201], v[24:27]
	v_mfma_f32_16x16x32_bf16 v[12:15], v[146:149], v[206:209], v[12:15]
	v_mfma_f32_16x16x32_bf16 v[8:11], v[154:157], v[206:209], v[8:11]
	s_setprio 0
	s_setprio 1
	v_mfma_f32_16x16x32_bf16 v[52:55], v[162:165], v[178:181], v[52:55]
	v_mfma_f32_16x16x32_bf16 v[48:51], v[170:173], v[178:181], v[48:51]
	v_mfma_f32_16x16x32_bf16 v[36:39], v[162:165], v[186:189], v[36:39]
	v_mfma_f32_16x16x32_bf16 v[32:35], v[170:173], v[186:189], v[32:35]
	v_mfma_f32_16x16x32_bf16 v[20:23], v[162:165], v[194:197], v[20:23]
	v_mfma_f32_16x16x32_bf16 v[16:19], v[170:173], v[194:197], v[16:19]
	v_mfma_f32_16x16x32_bf16 v[4:7], v[162:165], v[202:205], v[4:7]
	v_mfma_f32_16x16x32_bf16 v[0:3], v[170:173], v[202:205], v[0:3]
	v_mfma_f32_16x16x32_bf16 v[52:55], v[166:169], v[182:185], v[52:55]
	v_mfma_f32_16x16x32_bf16 v[48:51], v[174:177], v[182:185], v[48:51]
	v_mfma_f32_16x16x32_bf16 v[36:39], v[166:169], v[190:193], v[36:39]
	v_mfma_f32_16x16x32_bf16 v[32:35], v[174:177], v[190:193], v[32:35]
	v_mfma_f32_16x16x32_bf16 v[20:23], v[166:169], v[198:201], v[20:23]
	v_mfma_f32_16x16x32_bf16 v[16:19], v[174:177], v[198:201], v[16:19]
	v_mfma_f32_16x16x32_bf16 v[4:7], v[166:169], v[206:209], v[4:7]
	v_mfma_f32_16x16x32_bf16 v[0:3], v[174:177], v[206:209], v[0:3]
	s_setprio 0
	s_barrier
	s_add_i32 s67, 0, 0x18000
	s_add_i32 s68, 0, 0x1c000
	v_add_u32_e32 v154, s67, v143
	v_add_u32_e32 v174, s68, v143
	ds_read_b128 v[138:141], v154
	ds_read_b128 v[146:149], v154 offset:1024
	ds_read_b128 v[150:153], v154 offset:2048
	ds_read_b128 v[154:157], v154 offset:3072
	ds_read_b128 v[162:165], v174
	ds_read_b128 v[166:169], v174 offset:1024
	ds_read_b128 v[170:173], v174 offset:2048
	ds_read_b128 v[174:177], v174 offset:3072
	s_add_u32 s24, s28, 0xb0000
	s_addc_u32 s25, s29, 0
	s_mov_b32 m0, s57
	ds_read_b128 v[178:181], v145 offset:32768
	ds_read_b128 v[182:185], v145 offset:33792
	ds_read_b128 v[186:189], v145 offset:34816
	ds_read_b128 v[190:193], v145 offset:35840
	ds_read_b128 v[194:197], v145 offset:36864
	ds_read_b128 v[198:201], v145 offset:37888
	ds_read_b128 v[202:205], v145 offset:38912
	ds_read_b128 v[206:209], v145 offset:39936
	global_load_lds_dwordx4 v128, s[24:25]
	s_mov_b32 m0, s58
	s_nop 0
	global_load_lds_dwordx4 v130, s[24:25]
	s_waitcnt vmcnt(8)
	s_waitcnt lgkmcnt(0)
	s_barrier
	s_setprio 1
	s_waitcnt lgkmcnt(0)
	v_mfma_f32_16x16x32_bf16 v[124:127], v[138:141], v[178:181], v[124:127]
	v_mfma_f32_16x16x32_bf16 v[120:123], v[150:153], v[178:181], v[120:123]
	v_mfma_f32_16x16x32_bf16 v[108:111], v[138:141], v[186:189], v[108:111]
	v_mfma_f32_16x16x32_bf16 v[104:107], v[150:153], v[186:189], v[104:107]
	v_mfma_f32_16x16x32_bf16 v[92:95], v[138:141], v[194:197], v[92:95]
	v_mfma_f32_16x16x32_bf16 v[88:91], v[150:153], v[194:197], v[88:91]
	v_mfma_f32_16x16x32_bf16 v[76:79], v[138:141], v[202:205], v[76:79]
	v_mfma_f32_16x16x32_bf16 v[72:75], v[150:153], v[202:205], v[72:75]
	v_mfma_f32_16x16x32_bf16 v[124:127], v[146:149], v[182:185], v[124:127]
	v_mfma_f32_16x16x32_bf16 v[120:123], v[154:157], v[182:185], v[120:123]
	v_mfma_f32_16x16x32_bf16 v[108:111], v[146:149], v[190:193], v[108:111]
	v_mfma_f32_16x16x32_bf16 v[104:107], v[154:157], v[190:193], v[104:107]
	v_mfma_f32_16x16x32_bf16 v[92:95], v[146:149], v[198:201], v[92:95]
	v_mfma_f32_16x16x32_bf16 v[88:91], v[154:157], v[198:201], v[88:91]
	v_mfma_f32_16x16x32_bf16 v[76:79], v[146:149], v[206:209], v[76:79]
	v_mfma_f32_16x16x32_bf16 v[72:75], v[154:157], v[206:209], v[72:75]
	s_setprio 0
	s_setprio 1
	v_mfma_f32_16x16x32_bf16 v[116:119], v[162:165], v[178:181], v[116:119]
	v_mfma_f32_16x16x32_bf16 v[112:115], v[170:173], v[178:181], v[112:115]
	v_mfma_f32_16x16x32_bf16 v[100:103], v[162:165], v[186:189], v[100:103]
	v_mfma_f32_16x16x32_bf16 v[96:99], v[170:173], v[186:189], v[96:99]
	v_mfma_f32_16x16x32_bf16 v[84:87], v[162:165], v[194:197], v[84:87]
	v_mfma_f32_16x16x32_bf16 v[80:83], v[170:173], v[194:197], v[80:83]
	v_mfma_f32_16x16x32_bf16 v[68:71], v[162:165], v[202:205], v[68:71]
	v_mfma_f32_16x16x32_bf16 v[64:67], v[170:173], v[202:205], v[64:67]
	v_mfma_f32_16x16x32_bf16 v[116:119], v[166:169], v[182:185], v[116:119]
	v_mfma_f32_16x16x32_bf16 v[112:115], v[174:177], v[182:185], v[112:115]
	v_mfma_f32_16x16x32_bf16 v[100:103], v[166:169], v[190:193], v[100:103]
	v_mfma_f32_16x16x32_bf16 v[96:99], v[174:177], v[190:193], v[96:99]
	v_mfma_f32_16x16x32_bf16 v[84:87], v[166:169], v[198:201], v[84:87]
	v_mfma_f32_16x16x32_bf16 v[80:83], v[174:177], v[198:201], v[80:83]
	v_mfma_f32_16x16x32_bf16 v[68:71], v[166:169], v[206:209], v[68:71]
	v_mfma_f32_16x16x32_bf16 v[64:67], v[174:177], v[206:209], v[64:67]
	s_setprio 0
	s_barrier
; #define PG8_STAGE(bufoff, gbase, voff) do { _Pragma("unroll") for (int _i = 0; _i < 2; ++_i) \
;         __builtin_amdgcn_global_load_lds((const unsigned*)((const char*)(gbase) + (voff)[_i]), (LAS unsigned*)(lds + (bufoff) + ldsw + _i * 8192), 16, 0, 0); } while (0)
; #define PG8_LDA(dst, b, h) do { _Pragma("unroll") for (int m = 0; m < 4; ++m) _Pragma("unroll") for (int k = 0; k < 2; ++k) dst[m][k] = *(const LAS bf16x8*)(lds + PG8_SA(b, h) + aoff + m * 2048 + k * 1024); } while (0)
; #define PG8_LDB(dst, b, h) do { _Pragma("unroll") for (int n = 0; n < 2; ++n) _Pragma("unroll") for (int k = 0; k < 2; ++k) dst[n][k] = *(const LAS bf16x8*)(lds + PG8_SB(b, h) + boff + n * 2048 + k * 1024); } while (0)
; #define PG8_WAIT_V(n) asm volatile("s_waitcnt vmcnt(" #n ")" ::: "memory")
; #define PG8_WAIT_L(n) asm volatile("s_waitcnt lgkmcnt(" #n ")" ::: "memory")
; #define PG8_BAR __builtin_amdgcn_s_barrier()
; template <class Epi, bool ALIGN_EPI = true>
; __device__ __forceinline__ void gemm_phase(LAS unsigned char* lds, const Gemm g, const StaticOrder& S, const Epi& E, int wave_k) {
;     ...
;             const char* a1 = cA + (size_t)(t + 1) * kstep;
;             const char* a2 = last ? nA : cA + (size_t)(t + 2) * kstep; const char* b2 = last ? nB : cB + (size_t)(t + 2) * kstep;
;             const char* a3 = a2 + kstep; const char* b3 = b2 + kstep;
;             PG8_LDB(B0, 0, 0); PG8_LDB(B1, 0, 1); PG8_SCHED; PG8_LDA(At, 0, 0); PG8_STAGE(PG8_SA(1, 1), a1 + hstepA, voffA);
;             PG8_WAIT_V(8); PG8_WAIT_L(0); PG8_BAR; PG8_MMA(0, 0, At, B0); PG8_MMA(0, 1, At, B1); PG8_BAR; PG8_SCHED;
;             PG8_LDA(At, 0, 1); PG8_STAGE(PG8_SB(0, 0), b2, voffB); PG8_STAGE(PG8_SB(0, 1), b2 + hstepB, voffB); PG8_STAGE(PG8_SA(0, 0), a2, voffA);
;             PG8_WAIT_V(8); PG8_WAIT_L(0); PG8_BAR; PG8_MMA(1, 0, At, B0); PG8_MMA(1, 1, At, B1); PG8_BAR; PG8_SCHED;
;             PG8_LDB(B0, 1, 0); PG8_LDB(B1, 1, 1); PG8_SCHED; PG8_LDA(At, 1, 0); PG8_STAGE(PG8_SA(0, 1), a2 + hstepA, voffA);
;             PG8_WAIT_V(8); PG8_WAIT_L(0); PG8_BAR; PG8_MMA(0, 0, At, B0); PG8_MMA(0, 1, At, B1); PG8_BAR; PG8_SCHED;
;             PG8_LDA(At, 1, 1); PG8_STAGE(PG8_SB(1, 0), b3, voffB); PG8_STAGE(PG8_SB(1, 1), b3 + hstepB, voffB); PG8_STAGE(PG8_SA(1, 0), a3, voffA);
;             PG8_WAIT_V(8); PG8_WAIT_L(0); PG8_BAR; PG8_MMA(1, 0, At, B0); PG8_MMA(1, 1, At, B1); PG8_BAR; PG8_SCHED;
;         }
	s_add_i32 s24, s67, s54
	v_lshl_add_u64 v[158:159], v[158:159], 0, s[22:23]
	s_mov_b32 m0, s24
	ds_read_b128 v[178:181], v145 offset:49152
	ds_read_b128 v[182:185], v145 offset:50176
	ds_read_b128 v[186:189], v145 offset:51200
	ds_read_b128 v[190:193], v145 offset:52224
	ds_read_b128 v[194:197], v145 offset:53248
	ds_read_b128 v[198:201], v145 offset:54272
	ds_read_b128 v[202:205], v145 offset:55296
	ds_read_b128 v[206:209], v145 offset:56320
	global_load_lds_dwordx4 v[158:159], off
	s_add_i32 m0, s24, 0x2000
	s_add_u32 s24, s26, 0xb0080
	v_lshl_add_u64 v[158:159], v[210:211], 0, s[22:23]
	s_addc_u32 s25, s27, 0
	s_add_i32 s26, s68, s54
	global_load_lds_dwordx4 v[158:159], off
	s_mov_b32 m0, s26
	s_nop 0
	global_load_lds_dwordx4 v160, s[24:25]
	s_add_i32 m0, s26, 0x2000
	s_nop 0
	global_load_lds_dwordx4 v132, s[24:25]
	v_lshl_add_u64 v[158:159], v[212:213], 0, s[22:23]
	s_mov_b32 m0, s50
	s_nop 0
	global_load_lds_dwordx4 v[158:159], off
	v_lshl_add_u64 v[158:159], v[218:219], 0, s[22:23]
	s_mov_b32 m0, s51
	s_nop 0
	global_load_lds_dwordx4 v[158:159], off
	s_waitcnt vmcnt(8)
	s_waitcnt lgkmcnt(0)
	s_barrier
	s_setprio 1
	s_waitcnt lgkmcnt(0)
	v_mfma_f32_16x16x32_bf16 v[60:63], v[138:141], v[178:181], v[60:63]
	v_mfma_f32_16x16x32_bf16 v[56:59], v[150:153], v[178:181], v[56:59]
	v_mfma_f32_16x16x32_bf16 v[44:47], v[138:141], v[186:189], v[44:47]
	v_mfma_f32_16x16x32_bf16 v[40:43], v[150:153], v[186:189], v[40:43]
	v_mfma_f32_16x16x32_bf16 v[28:31], v[138:141], v[194:197], v[28:31]
	v_mfma_f32_16x16x32_bf16 v[24:27], v[150:153], v[194:197], v[24:27]
	v_mfma_f32_16x16x32_bf16 v[12:15], v[138:141], v[202:205], v[12:15]
	v_mfma_f32_16x16x32_bf16 v[8:11], v[150:153], v[202:205], v[8:11]
	v_mfma_f32_16x16x32_bf16 v[60:63], v[146:149], v[182:185], v[60:63]
	v_mfma_f32_16x16x32_bf16 v[56:59], v[154:157], v[182:185], v[56:59]
	v_mfma_f32_16x16x32_bf16 v[44:47], v[146:149], v[190:193], v[44:47]
	v_mfma_f32_16x16x32_bf16 v[40:43], v[154:157], v[190:193], v[40:43]
	v_mfma_f32_16x16x32_bf16 v[28:31], v[146:149], v[198:201], v[28:31]
	v_mfma_f32_16x16x32_bf16 v[24:27], v[154:157], v[198:201], v[24:27]
	v_mfma_f32_16x16x32_bf16 v[12:15], v[146:149], v[206:209], v[12:15]
	v_mfma_f32_16x16x32_bf16 v[8:11], v[154:157], v[206:209], v[8:11]
	s_setprio 0
	s_setprio 1
	v_mfma_f32_16x16x32_bf16 v[52:55], v[162:165], v[178:181], v[52:55]
	v_mfma_f32_16x16x32_bf16 v[48:51], v[170:173], v[178:181], v[48:51]
	v_mfma_f32_16x16x32_bf16 v[36:39], v[162:165], v[186:189], v[36:39]
	v_mfma_f32_16x16x32_bf16 v[32:35], v[170:173], v[186:189], v[32:35]
	v_mfma_f32_16x16x32_bf16 v[20:23], v[162:165], v[194:197], v[20:23]
	v_mfma_f32_16x16x32_bf16 v[16:19], v[170:173], v[194:197], v[16:19]
	v_mfma_f32_16x16x32_bf16 v[4:7], v[162:165], v[202:205], v[4:7]
	v_mfma_f32_16x16x32_bf16 v[0:3], v[170:173], v[202:205], v[0:3]
	v_mfma_f32_16x16x32_bf16 v[52:55], v[166:169], v[182:185], v[52:55]
	v_mfma_f32_16x16x32_bf16 v[48:51], v[174:177], v[182:185], v[48:51]
	v_mfma_f32_16x16x32_bf16 v[36:39], v[166:169], v[190:193], v[36:39]
	v_mfma_f32_16x16x32_bf16 v[32:35], v[174:177], v[190:193], v[32:35]
	v_mfma_f32_16x16x32_bf16 v[20:23], v[166:169], v[198:201], v[20:23]
	v_mfma_f32_16x16x32_bf16 v[16:19], v[174:177], v[198:201], v[16:19]
	v_mfma_f32_16x16x32_bf16 v[4:7], v[166:169], v[206:209], v[4:7]
	v_mfma_f32_16x16x32_bf16 v[0:3], v[174:177], v[206:209], v[0:3]
	s_setprio 0
	s_barrier
	s_add_i32 s66, s66, 2
	s_add_u32 s44, s44, 0x100
	s_addc_u32 s45, s45, 0
	s_cmp_gt_u32 s66, 41
	s_mov_b64 s[24:25], s[16:17]
	s_cbranch_scc0 .LBB0_1257
	s_and_b64 vcc, exec, s[20:21]
	s_cbranch_vccz .LBB0_1260
	s_barrier
